# row-statistics cross-lane sums: ds_bpermute replaced by v_permlane16/32_swap (bitwise same sums)
# speedup vs baseline: 1.0121x; 1.0016x over previous
.LBB0_570:
	v_mov_b32_e32 v130, v127
	v_mov_b32_e32 v131, v128
	v_mov_b32_e32 v132, v126
	v_mov_b32_e32 v133, v129
	v_pk_add_f32 v[130:131], v[130:131], v[132:133]
	v_mov_b32_e32 v132, v123
	v_mov_b32_e32 v133, v124
	v_mov_b32_e32 v134, v122
	v_mov_b32_e32 v135, v125
	v_pk_add_f32 v[132:133], v[132:133], v[134:135]
	v_add_f32_e32 v130, v130, v131
	v_pk_add_f32 v[132:133], v[132:133], v[132:133] op_sel_hi:[0,1]
	v_add_f32_e32 v131, 0, v130
	v_add_f32_e32 v135, v118, v119
	v_add_f32_e32 v137, v120, v121
	v_mov_b32_e32 v134, v114
	v_mov_b32_e32 v136, v115
	v_mov_b32_e32 v132, v116
	v_mov_b32_e32 v130, v117
	v_pk_add_f32 v[134:135], v[134:135], v[136:137]
	v_pk_add_f32 v[130:131], v[132:133], v[130:131]
	v_mov_b32_e32 v133, v126
	v_pk_add_f32 v[130:131], v[134:135], v[130:131]
	v_mov_b32_e32 v134, v127
	v_add_f32_e32 v130, v130, v131
	v_mov_b32_e32 v131, v130
	s_nop 1
	v_permlane16_swap_b32_e32 v130, v131
	v_mov_b32_e32 v135, v123
	s_lshl_b32 s0, s17, 3
	s_add_i32 s27, s0, 0
	s_barrier
	s_waitcnt lgkmcnt(0)
	v_add_f32_e32 v130, v130, v131
	v_mov_b32_e32 v131, v130
	s_nop 1
	v_permlane32_swap_b32_e32 v130, v131
	s_waitcnt lgkmcnt(0)
	v_add_f32_e32 v131, v130, v131
	v_fmamk_f32 v132, v131, 0xbc800000, v129
	v_fmac_f32_e32 v134, 0xbc800000, v131
	v_fmamk_f32 v130, v131, 0xbc800000, v128
	v_fmac_f32_e32 v133, 0xbc800000, v131
	v_mul_f32_e32 v134, v134, v134
	v_mul_f32_e32 v132, v132, v132
	v_fmac_f32_e32 v134, v133, v133
	v_fmac_f32_e32 v132, v130, v130
	v_add_f32_e32 v130, v134, v132
	v_fmamk_f32 v133, v131, 0xbc800000, v125
	v_mov_b32_e32 v134, v122
	v_fmac_f32_e32 v135, 0xbc800000, v131
	v_fmamk_f32 v132, v131, 0xbc800000, v124
	v_fmac_f32_e32 v134, 0xbc800000, v131
	v_mul_f32_e32 v135, v135, v135
	v_mul_f32_e32 v133, v133, v133
	v_fmac_f32_e32 v135, v134, v134
	v_fmac_f32_e32 v133, v132, v132
	v_add_f32_e32 v132, v135, v133
	v_mov_b32_e32 v135, v119
	v_fmamk_f32 v133, v131, 0xbc800000, v121
	v_mov_b32_e32 v134, v118
	v_fmac_f32_e32 v135, 0xbc800000, v131
	v_add_f32_e32 v130, v130, v132
	v_fmamk_f32 v132, v131, 0xbc800000, v120
	v_fmac_f32_e32 v134, 0xbc800000, v131
	v_mul_f32_e32 v135, v135, v135
	v_mul_f32_e32 v133, v133, v133
	v_fmac_f32_e32 v135, v134, v134
	v_fmac_f32_e32 v133, v132, v132
	v_add_f32_e32 v132, v135, v133
	v_mov_b32_e32 v135, v115
	v_fmamk_f32 v133, v131, 0xbc800000, v117
	v_mov_b32_e32 v134, v114
	v_fmac_f32_e32 v135, 0xbc800000, v131
	v_add_f32_e32 v130, v132, v130
	v_fmamk_f32 v132, v131, 0xbc800000, v116
	v_fmac_f32_e32 v134, 0xbc800000, v131
	v_mul_f32_e32 v135, v135, v135
	v_mul_f32_e32 v133, v133, v133
	v_fmac_f32_e32 v135, v134, v134
	v_fmac_f32_e32 v133, v132, v132
	v_add_f32_e32 v132, v135, v133
	v_add_f32_e32 v132, v132, v130
	v_mov_b32_e32 v133, v132
	s_nop 1
	v_permlane16_swap_b32_e32 v132, v133
	v_and_b32_e32 v130, 63, v148
	v_cmp_gt_u32_e64 s[4:5], 16, v130
	s_waitcnt lgkmcnt(0)
	v_add_f32_e32 v132, v132, v133
	v_mov_b32_e32 v133, v132
	s_nop 1
	v_permlane32_swap_b32_e32 v132, v133
	s_and_saveexec_b64 s[0:1], s[4:5]
	s_cbranch_execz .LBB0_572
	s_lshl_b32 s6, s26, 11
	s_add_i32 s6, s27, s6
	v_mul_f32_e32 v134, 0x3c800000, v131
	s_waitcnt lgkmcnt(0)
	v_add_f32_e32 v135, v132, v133
	v_lshl_add_u32 v131, v170, 5, s6
	ds_write_b64 v131, v[134:135]
.LBB0_572:
	s_or_b64 exec, exec, s[0:1]
	v_mov_b32_e32 v132, v111
	s_waitcnt lgkmcnt(0)
	v_mov_b32_e32 v133, v112
	v_mov_b32_e32 v134, v110
	v_mov_b32_e32 v135, v113
	v_pk_add_f32 v[132:133], v[132:133], v[134:135]
	v_mov_b32_e32 v134, v107
	v_mov_b32_e32 v135, v108
	v_mov_b32_e32 v136, v106
	v_mov_b32_e32 v137, v109
	v_pk_add_f32 v[134:135], v[134:135], v[136:137]
	v_add_f32_e32 v131, v132, v133
	v_pk_add_f32 v[134:135], v[134:135], v[134:135] op_sel_hi:[0,1]
	v_add_f32_e32 v133, 0, v131
	v_add_f32_e32 v137, v102, v103
	v_add_f32_e32 v139, v104, v105
	v_mov_b32_e32 v136, v98
	v_mov_b32_e32 v138, v99
	v_mov_b32_e32 v134, v100
	v_mov_b32_e32 v132, v101
	v_pk_add_f32 v[136:137], v[136:137], v[138:139]
	v_pk_add_f32 v[132:133], v[134:135], v[132:133]
	v_mov_b32_e32 v135, v111
	v_pk_add_f32 v[132:133], v[136:137], v[132:133]
	v_mov_b32_e32 v134, v110
	v_add_f32_e32 v131, v132, v133
	v_mov_b32_e32 v132, v131
	s_nop 1
	v_permlane16_swap_b32_e32 v131, v132
	v_mov_b32_e32 v136, v107
	s_waitcnt lgkmcnt(0)
	v_add_f32_e32 v131, v131, v132
	v_mov_b32_e32 v132, v131
	s_nop 1
	v_permlane32_swap_b32_e32 v131, v132
	s_waitcnt lgkmcnt(0)
	v_add_f32_e32 v131, v131, v132
	v_fmamk_f32 v133, v131, 0xbc800000, v113
	v_fmac_f32_e32 v135, 0xbc800000, v131
	v_fmamk_f32 v132, v131, 0xbc800000, v112
	v_fmac_f32_e32 v134, 0xbc800000, v131
	v_mul_f32_e32 v135, v135, v135
	v_mul_f32_e32 v133, v133, v133
	v_fmac_f32_e32 v135, v134, v134
	v_fmac_f32_e32 v133, v132, v132
	v_add_f32_e32 v132, v135, v133
	v_fmamk_f32 v134, v131, 0xbc800000, v109
	v_mov_b32_e32 v135, v106
	v_fmac_f32_e32 v136, 0xbc800000, v131
	v_fmamk_f32 v133, v131, 0xbc800000, v108
	v_fmac_f32_e32 v135, 0xbc800000, v131
	v_mul_f32_e32 v136, v136, v136
	v_mul_f32_e32 v134, v134, v134
	v_fmac_f32_e32 v136, v135, v135
	v_fmac_f32_e32 v134, v133, v133
	v_add_f32_e32 v133, v136, v134
	v_mov_b32_e32 v136, v103
	v_fmamk_f32 v134, v131, 0xbc800000, v105
	v_mov_b32_e32 v135, v102
	v_fmac_f32_e32 v136, 0xbc800000, v131
	v_add_f32_e32 v132, v132, v133
	v_fmamk_f32 v133, v131, 0xbc800000, v104
	v_fmac_f32_e32 v135, 0xbc800000, v131
	v_mul_f32_e32 v136, v136, v136
	v_mul_f32_e32 v134, v134, v134
	v_fmac_f32_e32 v136, v135, v135
	v_fmac_f32_e32 v134, v133, v133
	v_add_f32_e32 v133, v136, v134
	v_mov_b32_e32 v136, v99
	v_fmamk_f32 v134, v131, 0xbc800000, v101
	v_mov_b32_e32 v135, v98
	v_fmac_f32_e32 v136, 0xbc800000, v131
	v_add_f32_e32 v132, v133, v132
	v_fmamk_f32 v133, v131, 0xbc800000, v100
	v_fmac_f32_e32 v135, 0xbc800000, v131
	v_mul_f32_e32 v136, v136, v136
	v_mul_f32_e32 v134, v134, v134
	v_fmac_f32_e32 v136, v135, v135
	v_fmac_f32_e32 v134, v133, v133
	v_add_f32_e32 v133, v136, v134
	v_add_f32_e32 v132, v133, v132
	v_mov_b32_e32 v133, v132
	s_nop 1
	v_permlane16_swap_b32_e32 v132, v133
	s_waitcnt lgkmcnt(0)
	v_add_f32_e32 v132, v132, v133
	v_mov_b32_e32 v133, v132
	s_nop 1
	v_permlane32_swap_b32_e32 v132, v133
	s_and_saveexec_b64 s[0:1], s[4:5]
	s_cbranch_execz .LBB0_574
	s_lshl_b32 s6, s26, 11
	s_add_i32 s6, s27, s6
	v_mul_f32_e32 v134, 0x3c800000, v131
	s_waitcnt lgkmcnt(0)
	v_add_f32_e32 v135, v132, v133
	v_lshl_add_u32 v131, v170, 5, s6
	ds_write_b64 v131, v[134:135] offset:512
.LBB0_574:
	s_or_b64 exec, exec, s[0:1]
	v_mov_b32_e32 v132, v95
	s_waitcnt lgkmcnt(0)
	v_mov_b32_e32 v133, v96
	v_mov_b32_e32 v134, v94
	v_mov_b32_e32 v135, v97
	v_pk_add_f32 v[132:133], v[132:133], v[134:135]
	v_mov_b32_e32 v134, v91
	v_mov_b32_e32 v135, v92
	v_mov_b32_e32 v136, v90
	v_mov_b32_e32 v137, v93
	v_pk_add_f32 v[134:135], v[134:135], v[136:137]
	v_add_f32_e32 v131, v132, v133
	v_pk_add_f32 v[134:135], v[134:135], v[134:135] op_sel_hi:[0,1]
	v_add_f32_e32 v133, 0, v131
	v_add_f32_e32 v137, v86, v87
	v_add_f32_e32 v139, v88, v89
	v_mov_b32_e32 v136, v82
	v_mov_b32_e32 v138, v83
	v_mov_b32_e32 v134, v84
	v_mov_b32_e32 v132, v85
	v_pk_add_f32 v[136:137], v[136:137], v[138:139]
	v_pk_add_f32 v[132:133], v[134:135], v[132:133]
	v_mov_b32_e32 v135, v95
	v_pk_add_f32 v[132:133], v[136:137], v[132:133]
	v_mov_b32_e32 v134, v94
	v_add_f32_e32 v131, v132, v133
	v_mov_b32_e32 v132, v131
	s_nop 1
	v_permlane16_swap_b32_e32 v131, v132
	v_mov_b32_e32 v136, v91
	s_waitcnt lgkmcnt(0)
	v_add_f32_e32 v131, v131, v132
	v_mov_b32_e32 v132, v131
	s_nop 1
	v_permlane32_swap_b32_e32 v131, v132
	s_waitcnt lgkmcnt(0)
	v_add_f32_e32 v131, v131, v132
	v_fmamk_f32 v133, v131, 0xbc800000, v97
	v_fmac_f32_e32 v135, 0xbc800000, v131
	v_fmamk_f32 v132, v131, 0xbc800000, v96
	v_fmac_f32_e32 v134, 0xbc800000, v131
	v_mul_f32_e32 v135, v135, v135
	v_mul_f32_e32 v133, v133, v133
	v_fmac_f32_e32 v135, v134, v134
	v_fmac_f32_e32 v133, v132, v132
	v_add_f32_e32 v132, v135, v133
	v_fmamk_f32 v134, v131, 0xbc800000, v93
	v_mov_b32_e32 v135, v90
	v_fmac_f32_e32 v136, 0xbc800000, v131
	v_fmamk_f32 v133, v131, 0xbc800000, v92
	v_fmac_f32_e32 v135, 0xbc800000, v131
	v_mul_f32_e32 v136, v136, v136
	v_mul_f32_e32 v134, v134, v134
	v_fmac_f32_e32 v136, v135, v135
	v_fmac_f32_e32 v134, v133, v133
	v_add_f32_e32 v133, v136, v134
	v_mov_b32_e32 v136, v87
	v_fmamk_f32 v134, v131, 0xbc800000, v89
	v_mov_b32_e32 v135, v86
	v_fmac_f32_e32 v136, 0xbc800000, v131
	v_add_f32_e32 v132, v132, v133
	v_fmamk_f32 v133, v131, 0xbc800000, v88
	v_fmac_f32_e32 v135, 0xbc800000, v131
	v_mul_f32_e32 v136, v136, v136
	v_mul_f32_e32 v134, v134, v134
	v_fmac_f32_e32 v136, v135, v135
	v_fmac_f32_e32 v134, v133, v133
	v_add_f32_e32 v133, v136, v134
	v_mov_b32_e32 v136, v83
	v_fmamk_f32 v134, v131, 0xbc800000, v85
	v_mov_b32_e32 v135, v82
	v_fmac_f32_e32 v136, 0xbc800000, v131
	v_add_f32_e32 v132, v133, v132
	v_fmamk_f32 v133, v131, 0xbc800000, v84
	v_fmac_f32_e32 v135, 0xbc800000, v131
	v_mul_f32_e32 v136, v136, v136
	v_mul_f32_e32 v134, v134, v134
	v_fmac_f32_e32 v136, v135, v135
	v_fmac_f32_e32 v134, v133, v133
	v_add_f32_e32 v133, v136, v134
	v_add_f32_e32 v132, v133, v132
	v_mov_b32_e32 v133, v132
	s_nop 1
	v_permlane16_swap_b32_e32 v132, v133
	s_waitcnt lgkmcnt(0)
	v_add_f32_e32 v132, v132, v133
	v_mov_b32_e32 v133, v132
	s_nop 1
	v_permlane32_swap_b32_e32 v132, v133
	s_and_saveexec_b64 s[0:1], s[4:5]
	s_cbranch_execz .LBB0_576
	s_lshl_b32 s6, s26, 11
	s_add_i32 s6, s27, s6
	v_mul_f32_e32 v134, 0x3c800000, v131
	s_waitcnt lgkmcnt(0)
	v_add_f32_e32 v135, v132, v133
	v_lshl_add_u32 v131, v170, 5, s6
	ds_write_b64 v131, v[134:135] offset:1024
.LBB0_576:
	s_or_b64 exec, exec, s[0:1]
	v_mov_b32_e32 v132, v79
	s_waitcnt lgkmcnt(0)
	v_mov_b32_e32 v133, v80
	v_mov_b32_e32 v134, v78
	v_mov_b32_e32 v135, v81
	v_pk_add_f32 v[132:133], v[132:133], v[134:135]
	v_mov_b32_e32 v134, v75
	v_mov_b32_e32 v135, v76
	v_mov_b32_e32 v136, v74
	v_mov_b32_e32 v137, v77
	v_pk_add_f32 v[134:135], v[134:135], v[136:137]
	v_add_f32_e32 v131, v132, v133
	v_pk_add_f32 v[134:135], v[134:135], v[134:135] op_sel_hi:[0,1]
	v_add_f32_e32 v133, 0, v131
	v_add_f32_e32 v137, v70, v71
	v_add_f32_e32 v139, v72, v73
	v_mov_b32_e32 v136, v66
	v_mov_b32_e32 v138, v67
	v_mov_b32_e32 v134, v68
	v_mov_b32_e32 v132, v69
	v_pk_add_f32 v[136:137], v[136:137], v[138:139]
	v_pk_add_f32 v[132:133], v[134:135], v[132:133]
	v_mov_b32_e32 v135, v79
	v_pk_add_f32 v[132:133], v[136:137], v[132:133]
	v_mov_b32_e32 v134, v78
	v_add_f32_e32 v131, v132, v133
	v_mov_b32_e32 v132, v131
	s_nop 1
	v_permlane16_swap_b32_e32 v131, v132
	v_mov_b32_e32 v136, v75
	s_waitcnt lgkmcnt(0)
	v_add_f32_e32 v131, v131, v132
	v_mov_b32_e32 v132, v131
	s_nop 1
	v_permlane32_swap_b32_e32 v131, v132
	s_waitcnt lgkmcnt(0)
	v_add_f32_e32 v131, v131, v132
	v_fmamk_f32 v133, v131, 0xbc800000, v81
	v_fmac_f32_e32 v135, 0xbc800000, v131
	v_fmamk_f32 v132, v131, 0xbc800000, v80
	v_fmac_f32_e32 v134, 0xbc800000, v131
	v_mul_f32_e32 v135, v135, v135
	v_mul_f32_e32 v133, v133, v133
	v_fmac_f32_e32 v135, v134, v134
	v_fmac_f32_e32 v133, v132, v132
	v_add_f32_e32 v132, v135, v133
	v_fmamk_f32 v134, v131, 0xbc800000, v77
	v_mov_b32_e32 v135, v74
	v_fmac_f32_e32 v136, 0xbc800000, v131
	v_fmamk_f32 v133, v131, 0xbc800000, v76
	v_fmac_f32_e32 v135, 0xbc800000, v131
	v_mul_f32_e32 v136, v136, v136
	v_mul_f32_e32 v134, v134, v134
	v_fmac_f32_e32 v136, v135, v135
	v_fmac_f32_e32 v134, v133, v133
	v_add_f32_e32 v133, v136, v134
	v_mov_b32_e32 v136, v71
	v_fmamk_f32 v134, v131, 0xbc800000, v73
	v_mov_b32_e32 v135, v70
	v_fmac_f32_e32 v136, 0xbc800000, v131
	v_add_f32_e32 v132, v132, v133
	v_fmamk_f32 v133, v131, 0xbc800000, v72
	v_fmac_f32_e32 v135, 0xbc800000, v131
	v_mul_f32_e32 v136, v136, v136
	v_mul_f32_e32 v134, v134, v134
	v_fmac_f32_e32 v136, v135, v135
	v_fmac_f32_e32 v134, v133, v133
	v_add_f32_e32 v133, v136, v134
	v_mov_b32_e32 v136, v67
	v_fmamk_f32 v134, v131, 0xbc800000, v69
	v_mov_b32_e32 v135, v66
	v_fmac_f32_e32 v136, 0xbc800000, v131
	v_add_f32_e32 v132, v133, v132
	v_fmamk_f32 v133, v131, 0xbc800000, v68
	v_fmac_f32_e32 v135, 0xbc800000, v131
	v_mul_f32_e32 v136, v136, v136
	v_mul_f32_e32 v134, v134, v134
	v_fmac_f32_e32 v136, v135, v135
	v_fmac_f32_e32 v134, v133, v133
	v_add_f32_e32 v133, v136, v134
	v_add_f32_e32 v132, v133, v132
	v_mov_b32_e32 v133, v132
	s_nop 1
	v_permlane16_swap_b32_e32 v132, v133
	s_waitcnt lgkmcnt(0)
	v_add_f32_e32 v132, v132, v133
	v_mov_b32_e32 v133, v132
	s_nop 1
	v_permlane32_swap_b32_e32 v132, v133
	s_and_saveexec_b64 s[0:1], s[4:5]
	s_cbranch_execz .LBB0_578
	s_lshl_b32 s6, s26, 11
	s_add_i32 s6, s27, s6
	v_mul_f32_e32 v134, 0x3c800000, v131
	s_waitcnt lgkmcnt(0)
	v_add_f32_e32 v135, v132, v133
	v_lshl_add_u32 v131, v170, 5, s6
	ds_write_b64 v131, v[134:135] offset:1536
.LBB0_578:
	s_or_b64 exec, exec, s[0:1]
	v_mov_b32_e32 v132, v63
	s_waitcnt lgkmcnt(0)
	v_mov_b32_e32 v133, v64
	v_mov_b32_e32 v134, v62
	v_mov_b32_e32 v135, v65
	v_pk_add_f32 v[132:133], v[132:133], v[134:135]
	v_mov_b32_e32 v134, v59
	v_mov_b32_e32 v135, v60
	v_mov_b32_e32 v136, v58
	v_mov_b32_e32 v137, v61
	v_pk_add_f32 v[134:135], v[134:135], v[136:137]
	v_add_f32_e32 v131, v132, v133
	v_pk_add_f32 v[134:135], v[134:135], v[134:135] op_sel_hi:[0,1]
	v_add_f32_e32 v133, 0, v131
	v_add_f32_e32 v137, v54, v55
	v_add_f32_e32 v139, v56, v57
	v_mov_b32_e32 v136, v50
	v_mov_b32_e32 v138, v51
	v_mov_b32_e32 v134, v52
	v_mov_b32_e32 v132, v53
	v_pk_add_f32 v[136:137], v[136:137], v[138:139]
	v_pk_add_f32 v[132:133], v[134:135], v[132:133]
	v_mov_b32_e32 v135, v63
	v_pk_add_f32 v[132:133], v[136:137], v[132:133]
	v_mov_b32_e32 v134, v62
	v_add_f32_e32 v131, v132, v133
	v_mov_b32_e32 v132, v131
	s_nop 1
	v_permlane16_swap_b32_e32 v131, v132
	v_mov_b32_e32 v136, v59
	s_waitcnt lgkmcnt(0)
	v_add_f32_e32 v131, v131, v132
	v_mov_b32_e32 v132, v131
	s_nop 1
	v_permlane32_swap_b32_e32 v131, v132
	s_waitcnt lgkmcnt(0)
	v_add_f32_e32 v131, v131, v132
	v_fmamk_f32 v133, v131, 0xbc800000, v65
	v_fmac_f32_e32 v135, 0xbc800000, v131
	v_fmamk_f32 v132, v131, 0xbc800000, v64
	v_fmac_f32_e32 v134, 0xbc800000, v131
	v_mul_f32_e32 v135, v135, v135
	v_mul_f32_e32 v133, v133, v133
	v_fmac_f32_e32 v135, v134, v134
	v_fmac_f32_e32 v133, v132, v132
	v_add_f32_e32 v132, v135, v133
	v_fmamk_f32 v134, v131, 0xbc800000, v61
	v_mov_b32_e32 v135, v58
	v_fmac_f32_e32 v136, 0xbc800000, v131
	v_fmamk_f32 v133, v131, 0xbc800000, v60
	v_fmac_f32_e32 v135, 0xbc800000, v131
	v_mul_f32_e32 v136, v136, v136
	v_mul_f32_e32 v134, v134, v134
	v_fmac_f32_e32 v136, v135, v135
	v_fmac_f32_e32 v134, v133, v133
	v_add_f32_e32 v133, v136, v134
	v_mov_b32_e32 v136, v55
	v_fmamk_f32 v134, v131, 0xbc800000, v57
	v_mov_b32_e32 v135, v54
	v_fmac_f32_e32 v136, 0xbc800000, v131
	v_add_f32_e32 v132, v132, v133
	v_fmamk_f32 v133, v131, 0xbc800000, v56
	v_fmac_f32_e32 v135, 0xbc800000, v131
	v_mul_f32_e32 v136, v136, v136
	v_mul_f32_e32 v134, v134, v134
	v_fmac_f32_e32 v136, v135, v135
	v_fmac_f32_e32 v134, v133, v133
	v_add_f32_e32 v133, v136, v134
	v_mov_b32_e32 v136, v51
	v_fmamk_f32 v134, v131, 0xbc800000, v53
	v_mov_b32_e32 v135, v50
	v_fmac_f32_e32 v136, 0xbc800000, v131
	v_add_f32_e32 v132, v133, v132
	v_fmamk_f32 v133, v131, 0xbc800000, v52
	v_fmac_f32_e32 v135, 0xbc800000, v131
	v_mul_f32_e32 v136, v136, v136
	v_mul_f32_e32 v134, v134, v134
	v_fmac_f32_e32 v136, v135, v135
	v_fmac_f32_e32 v134, v133, v133
	v_add_f32_e32 v133, v136, v134
	v_add_f32_e32 v132, v133, v132
	v_mov_b32_e32 v133, v132
	s_nop 1
	v_permlane16_swap_b32_e32 v132, v133
	s_waitcnt lgkmcnt(0)
	v_add_f32_e32 v132, v132, v133
	v_mov_b32_e32 v133, v132
	s_nop 1
	v_permlane32_swap_b32_e32 v132, v133
	s_and_saveexec_b64 s[0:1], s[4:5]
	s_cbranch_execz .LBB0_580
	s_lshl_b32 s6, s26, 11
	s_add_i32 s6, s27, s6
	v_mul_f32_e32 v134, 0x3c800000, v131
	s_waitcnt lgkmcnt(0)
	v_add_f32_e32 v135, v132, v133
	v_lshl_add_u32 v131, v170, 5, s6
	ds_write_b64 v131, v[134:135] offset:4096
.LBB0_580:
	s_or_b64 exec, exec, s[0:1]
	v_mov_b32_e32 v132, v47
	s_waitcnt lgkmcnt(0)
	v_mov_b32_e32 v133, v48
	v_mov_b32_e32 v134, v46
	v_mov_b32_e32 v135, v49
	v_pk_add_f32 v[132:133], v[132:133], v[134:135]
	v_mov_b32_e32 v134, v43
	v_mov_b32_e32 v135, v44
	v_mov_b32_e32 v136, v42
	v_mov_b32_e32 v137, v45
	v_pk_add_f32 v[134:135], v[134:135], v[136:137]
	v_add_f32_e32 v131, v132, v133
	v_pk_add_f32 v[134:135], v[134:135], v[134:135] op_sel_hi:[0,1]
	v_add_f32_e32 v133, 0, v131
	v_add_f32_e32 v137, v38, v39
	v_add_f32_e32 v139, v40, v41
	v_mov_b32_e32 v136, v34
	v_mov_b32_e32 v138, v35
	v_mov_b32_e32 v134, v36
	v_mov_b32_e32 v132, v37
	v_pk_add_f32 v[136:137], v[136:137], v[138:139]
	v_pk_add_f32 v[132:133], v[134:135], v[132:133]
	v_mov_b32_e32 v135, v47
	v_pk_add_f32 v[132:133], v[136:137], v[132:133]
	v_mov_b32_e32 v134, v46
	v_add_f32_e32 v131, v132, v133
	v_mov_b32_e32 v132, v131
	s_nop 1
	v_permlane16_swap_b32_e32 v131, v132
	v_mov_b32_e32 v136, v43
	s_waitcnt lgkmcnt(0)
	v_add_f32_e32 v131, v131, v132
	v_mov_b32_e32 v132, v131
	s_nop 1
	v_permlane32_swap_b32_e32 v131, v132
	s_waitcnt lgkmcnt(0)
	v_add_f32_e32 v131, v131, v132
	v_fmamk_f32 v133, v131, 0xbc800000, v49
	v_fmac_f32_e32 v135, 0xbc800000, v131
	v_fmamk_f32 v132, v131, 0xbc800000, v48
	v_fmac_f32_e32 v134, 0xbc800000, v131
	v_mul_f32_e32 v135, v135, v135
	v_mul_f32_e32 v133, v133, v133
	v_fmac_f32_e32 v135, v134, v134
	v_fmac_f32_e32 v133, v132, v132
	v_add_f32_e32 v132, v135, v133
	v_fmamk_f32 v134, v131, 0xbc800000, v45
	v_mov_b32_e32 v135, v42
	v_fmac_f32_e32 v136, 0xbc800000, v131
	v_fmamk_f32 v133, v131, 0xbc800000, v44
	v_fmac_f32_e32 v135, 0xbc800000, v131
	v_mul_f32_e32 v136, v136, v136
	v_mul_f32_e32 v134, v134, v134
	v_fmac_f32_e32 v136, v135, v135
	v_fmac_f32_e32 v134, v133, v133
	v_add_f32_e32 v133, v136, v134
	v_mov_b32_e32 v136, v39
	v_fmamk_f32 v134, v131, 0xbc800000, v41
	v_mov_b32_e32 v135, v38
	v_fmac_f32_e32 v136, 0xbc800000, v131
	v_add_f32_e32 v132, v132, v133
	v_fmamk_f32 v133, v131, 0xbc800000, v40
	v_fmac_f32_e32 v135, 0xbc800000, v131
	v_mul_f32_e32 v136, v136, v136
	v_mul_f32_e32 v134, v134, v134
	v_fmac_f32_e32 v136, v135, v135
	v_fmac_f32_e32 v134, v133, v133
	v_add_f32_e32 v133, v136, v134
	v_mov_b32_e32 v136, v35
	v_fmamk_f32 v134, v131, 0xbc800000, v37
	v_mov_b32_e32 v135, v34
	v_fmac_f32_e32 v136, 0xbc800000, v131
	v_add_f32_e32 v132, v133, v132
	v_fmamk_f32 v133, v131, 0xbc800000, v36
	v_fmac_f32_e32 v135, 0xbc800000, v131
	v_mul_f32_e32 v136, v136, v136
	v_mul_f32_e32 v134, v134, v134
	v_fmac_f32_e32 v136, v135, v135
	v_fmac_f32_e32 v134, v133, v133
	v_add_f32_e32 v133, v136, v134
	v_add_f32_e32 v132, v133, v132
	v_mov_b32_e32 v133, v132
	s_nop 1
	v_permlane16_swap_b32_e32 v132, v133
	s_waitcnt lgkmcnt(0)
	v_add_f32_e32 v132, v132, v133
	v_mov_b32_e32 v133, v132
	s_nop 1
	v_permlane32_swap_b32_e32 v132, v133
	s_and_saveexec_b64 s[0:1], s[4:5]
	s_cbranch_execz .LBB0_582
	s_lshl_b32 s6, s26, 11
	s_add_i32 s6, s27, s6
	v_mul_f32_e32 v134, 0x3c800000, v131
	s_waitcnt lgkmcnt(0)
	v_add_f32_e32 v135, v132, v133
	v_lshl_add_u32 v131, v170, 5, s6
	ds_write_b64 v131, v[134:135] offset:4608
.LBB0_582:
	s_or_b64 exec, exec, s[0:1]
	v_mov_b32_e32 v132, v31
	s_waitcnt lgkmcnt(0)
	v_mov_b32_e32 v133, v32
	v_mov_b32_e32 v134, v30
	v_mov_b32_e32 v135, v33
	v_pk_add_f32 v[132:133], v[132:133], v[134:135]
	v_mov_b32_e32 v134, v27
	v_mov_b32_e32 v135, v28
	v_mov_b32_e32 v136, v26
	v_mov_b32_e32 v137, v29
	v_pk_add_f32 v[134:135], v[134:135], v[136:137]
	v_add_f32_e32 v131, v132, v133
	v_pk_add_f32 v[134:135], v[134:135], v[134:135] op_sel_hi:[0,1]
	v_add_f32_e32 v133, 0, v131
	v_add_f32_e32 v137, v22, v23
	v_add_f32_e32 v139, v24, v25
	v_mov_b32_e32 v136, v18
	v_mov_b32_e32 v138, v19
	v_mov_b32_e32 v134, v20
	v_mov_b32_e32 v132, v21
	v_pk_add_f32 v[136:137], v[136:137], v[138:139]
	v_pk_add_f32 v[132:133], v[134:135], v[132:133]
	v_mov_b32_e32 v135, v31
	v_pk_add_f32 v[132:133], v[136:137], v[132:133]
	v_mov_b32_e32 v134, v30
	v_add_f32_e32 v131, v132, v133
	v_mov_b32_e32 v132, v131
	s_nop 1
	v_permlane16_swap_b32_e32 v131, v132
	v_mov_b32_e32 v136, v27
	s_waitcnt lgkmcnt(0)
	v_add_f32_e32 v131, v131, v132
	v_mov_b32_e32 v132, v131
	s_nop 1
	v_permlane32_swap_b32_e32 v131, v132
	s_waitcnt lgkmcnt(0)
	v_add_f32_e32 v131, v131, v132
	v_fmamk_f32 v133, v131, 0xbc800000, v33
	v_fmac_f32_e32 v135, 0xbc800000, v131
	v_fmamk_f32 v132, v131, 0xbc800000, v32
	v_fmac_f32_e32 v134, 0xbc800000, v131
	v_mul_f32_e32 v135, v135, v135
	v_mul_f32_e32 v133, v133, v133
	v_fmac_f32_e32 v135, v134, v134
	v_fmac_f32_e32 v133, v132, v132
	v_add_f32_e32 v132, v135, v133
	v_fmamk_f32 v134, v131, 0xbc800000, v29
	v_mov_b32_e32 v135, v26
	v_fmac_f32_e32 v136, 0xbc800000, v131
	v_fmamk_f32 v133, v131, 0xbc800000, v28
	v_fmac_f32_e32 v135, 0xbc800000, v131
	v_mul_f32_e32 v136, v136, v136
	v_mul_f32_e32 v134, v134, v134
	v_fmac_f32_e32 v136, v135, v135
	v_fmac_f32_e32 v134, v133, v133
	v_add_f32_e32 v133, v136, v134
	v_mov_b32_e32 v136, v23
	v_fmamk_f32 v134, v131, 0xbc800000, v25
	v_mov_b32_e32 v135, v22
	v_fmac_f32_e32 v136, 0xbc800000, v131
	v_add_f32_e32 v132, v132, v133
	v_fmamk_f32 v133, v131, 0xbc800000, v24
	v_fmac_f32_e32 v135, 0xbc800000, v131
	v_mul_f32_e32 v136, v136, v136
	v_mul_f32_e32 v134, v134, v134
	v_fmac_f32_e32 v136, v135, v135
	v_fmac_f32_e32 v134, v133, v133
	v_add_f32_e32 v133, v136, v134
	v_mov_b32_e32 v136, v19
	v_fmamk_f32 v134, v131, 0xbc800000, v21
	v_mov_b32_e32 v135, v18
	v_fmac_f32_e32 v136, 0xbc800000, v131
	v_add_f32_e32 v132, v133, v132
	v_fmamk_f32 v133, v131, 0xbc800000, v20
	v_fmac_f32_e32 v135, 0xbc800000, v131
	v_mul_f32_e32 v136, v136, v136
	v_mul_f32_e32 v134, v134, v134
	v_fmac_f32_e32 v136, v135, v135
	v_fmac_f32_e32 v134, v133, v133
	v_add_f32_e32 v133, v136, v134
	v_add_f32_e32 v132, v133, v132
	v_mov_b32_e32 v133, v132
	s_nop 1
	v_permlane16_swap_b32_e32 v132, v133
	s_waitcnt lgkmcnt(0)
	v_add_f32_e32 v132, v132, v133
	v_mov_b32_e32 v133, v132
	s_nop 1
	v_permlane32_swap_b32_e32 v132, v133
	s_and_saveexec_b64 s[0:1], s[4:5]
	s_cbranch_execz .LBB0_584
	s_lshl_b32 s6, s26, 11
	s_add_i32 s6, s27, s6
	v_mul_f32_e32 v134, 0x3c800000, v131
	s_waitcnt lgkmcnt(0)
	v_add_f32_e32 v135, v132, v133
	v_lshl_add_u32 v131, v170, 5, s6
	ds_write_b64 v131, v[134:135] offset:5120
.LBB0_584:
	s_or_b64 exec, exec, s[0:1]
	v_mov_b32_e32 v132, v15
	s_waitcnt lgkmcnt(0)
	v_mov_b32_e32 v133, v16
	v_mov_b32_e32 v134, v14
	v_mov_b32_e32 v135, v17
	v_pk_add_f32 v[132:133], v[132:133], v[134:135]
	v_mov_b32_e32 v134, v11
	v_mov_b32_e32 v135, v12
	v_mov_b32_e32 v136, v10
	v_mov_b32_e32 v137, v13
	v_pk_add_f32 v[134:135], v[134:135], v[136:137]
	v_add_f32_e32 v131, v132, v133
	v_pk_add_f32 v[134:135], v[134:135], v[134:135] op_sel_hi:[0,1]
	v_add_f32_e32 v133, 0, v131
	v_add_f32_e32 v137, v6, v7
	v_add_f32_e32 v139, v8, v9
	v_mov_b32_e32 v136, v2
	v_mov_b32_e32 v138, v3
	v_mov_b32_e32 v134, v4
	v_mov_b32_e32 v132, v5
	v_pk_add_f32 v[136:137], v[136:137], v[138:139]
	v_pk_add_f32 v[132:133], v[134:135], v[132:133]
	v_mov_b32_e32 v135, v15
	v_pk_add_f32 v[132:133], v[136:137], v[132:133]
	v_mov_b32_e32 v134, v14
	v_add_f32_e32 v131, v132, v133
	v_mov_b32_e32 v132, v131
	s_nop 1
	v_permlane16_swap_b32_e32 v131, v132
	v_mov_b32_e32 v136, v11
	s_waitcnt lgkmcnt(0)
	v_add_f32_e32 v131, v131, v132
	v_mov_b32_e32 v132, v131
	s_nop 1
	v_permlane32_swap_b32_e32 v131, v132
	s_waitcnt lgkmcnt(0)
	v_add_f32_e32 v131, v131, v132
	v_fmamk_f32 v133, v131, 0xbc800000, v17
	v_fmac_f32_e32 v135, 0xbc800000, v131
	v_fmamk_f32 v132, v131, 0xbc800000, v16
	v_fmac_f32_e32 v134, 0xbc800000, v131
	v_mul_f32_e32 v135, v135, v135
	v_mul_f32_e32 v133, v133, v133
	v_fmac_f32_e32 v135, v134, v134
	v_fmac_f32_e32 v133, v132, v132
	v_add_f32_e32 v132, v135, v133
	v_fmamk_f32 v134, v131, 0xbc800000, v13
	v_mov_b32_e32 v135, v10
	v_fmac_f32_e32 v136, 0xbc800000, v131
	v_fmamk_f32 v133, v131, 0xbc800000, v12
	v_fmac_f32_e32 v135, 0xbc800000, v131
	v_mul_f32_e32 v136, v136, v136
	v_mul_f32_e32 v134, v134, v134
	v_fmac_f32_e32 v136, v135, v135
	v_fmac_f32_e32 v134, v133, v133
	v_add_f32_e32 v133, v136, v134
	v_mov_b32_e32 v136, v7
	v_fmamk_f32 v134, v131, 0xbc800000, v9
	v_mov_b32_e32 v135, v6
	v_fmac_f32_e32 v136, 0xbc800000, v131
	v_add_f32_e32 v132, v132, v133
	v_fmamk_f32 v133, v131, 0xbc800000, v8
	v_fmac_f32_e32 v135, 0xbc800000, v131
	v_mul_f32_e32 v136, v136, v136
	v_mul_f32_e32 v134, v134, v134
	v_fmac_f32_e32 v136, v135, v135
	v_fmac_f32_e32 v134, v133, v133
	v_add_f32_e32 v133, v136, v134
	v_mov_b32_e32 v136, v3
	v_fmamk_f32 v134, v131, 0xbc800000, v5
	v_mov_b32_e32 v135, v2
	v_fmac_f32_e32 v136, 0xbc800000, v131
	v_add_f32_e32 v132, v133, v132
	v_fmamk_f32 v133, v131, 0xbc800000, v4
	v_fmac_f32_e32 v135, 0xbc800000, v131
	v_mul_f32_e32 v136, v136, v136
	v_mul_f32_e32 v134, v134, v134
	v_fmac_f32_e32 v136, v135, v135
	v_fmac_f32_e32 v134, v133, v133
	v_add_f32_e32 v133, v136, v134
	v_add_f32_e32 v132, v133, v132
	v_mov_b32_e32 v133, v132
	s_nop 1
	v_permlane16_swap_b32_e32 v132, v133
	s_waitcnt lgkmcnt(0)
	v_add_f32_e32 v132, v132, v133
	v_mov_b32_e32 v133, v132
	s_nop 1
	v_permlane32_swap_b32_e32 v132, v133
	s_and_saveexec_b64 s[0:1], s[4:5]
	s_cbranch_execz .LBB0_586
	s_lshl_b32 s6, s26, 11
	s_add_i32 s6, s27, s6
	v_mul_f32_e32 v134, 0x3c800000, v131
	s_waitcnt lgkmcnt(0)
	v_add_f32_e32 v135, v132, v133
	v_lshl_add_u32 v131, v170, 5, s6
	ds_write_b64 v131, v[134:135] offset:5632

.LBB0_610:
	s_or_b64 exec, exec, s[22:23]
	s_lshl_b32 s0, s17, 5
	s_lshl_b32 s1, s18, 8
	s_or_b32 s0, s1, s0
	v_lshrrev_b32_e32 v130, 2, v148
	v_and_or_b32 v162, v130, 12, s0
	s_lshl_b32 s0, s16, 5
	s_and_b32 s0, s0, 0xfffffc00
	v_add_u32_e32 v148, s0, v162
	v_readlane_b32 s0, v251, 45
	v_add_u32_e32 v150, s19, v152
	v_readlane_b32 s40, v251, 25
	v_ashrrev_i32_e32 v149, 31, v148
	v_readlane_b32 s1, v251, 46
	v_ashrrev_i32_e32 v151, 31, v150
	v_readlane_b32 s41, v251, 26
	v_lshl_add_u64 v[138:139], v[148:149], 2, s[0:1]
	v_ashrrev_i32_e32 v163, 31, v162
	v_lshlrev_b64 v[130:131], 12, v[150:151]
	s_mov_b64 s[0:1], s[40:41]
	v_lshl_add_u64 v[130:131], s[0:1], 0, v[130:131]
	v_lshlrev_b64 v[168:169], 2, v[162:163]
	s_waitcnt lgkmcnt(0)
	s_barrier
	v_lshl_add_u64 v[172:173], v[130:131], 0, v[168:169]
	global_load_dwordx4 v[154:157], v[172:173], off
	global_load_dwordx4 v[134:137], v[138:139], off
	s_waitcnt lgkmcnt(0)
	global_load_dwordx4 v[130:133], v[138:139], off offset:64
	global_load_dwordx4 v[158:161], v[172:173], off offset:64
	global_load_dwordx4 v[164:167], v[172:173], off offset:512
	global_load_dwordx4 v[142:145], v[138:139], off offset:512
	s_nop 0
	global_load_dwordx4 v[138:141], v[138:139], off offset:576
	s_nop 0
	global_load_dwordx4 v[172:175], v[172:173], off offset:576
	v_lshl_add_u32 v184, v152, 3, 0
	ds_read_b64 v[176:177], v184 offset:8192
	v_add_u32_e32 v152, 16, v150
	v_ashrrev_i32_e32 v153, 31, v152
	v_lshlrev_b64 v[178:179], 12, v[152:153]
	v_lshl_add_u64 v[178:179], s[0:1], 0, v[178:179]
	s_waitcnt lgkmcnt(0)
	v_pk_mul_f32 v[126:127], v[126:127], v[176:177] op_sel:[0,1]
	v_pk_mul_f32 v[128:129], v[128:129], v[176:177] op_sel:[0,1]
	v_pk_mul_f32 v[122:123], v[122:123], v[176:177] op_sel:[0,1]
	v_pk_mul_f32 v[124:125], v[124:125], v[176:177] op_sel:[0,1]
	v_pk_mul_f32 v[180:181], v[118:119], v[176:177] op_sel:[0,1]
	v_pk_mul_f32 v[188:189], v[120:121], v[176:177] op_sel:[0,1]
	v_pk_mul_f32 v[114:115], v[114:115], v[176:177] op_sel:[0,1]
	v_pk_mul_f32 v[116:117], v[116:117], v[176:177] op_sel:[0,1]
	v_lshl_add_u64 v[178:179], v[178:179], 0, v[168:169]
	v_readlane_b32 s42, v251, 27
	v_readlane_b32 s43, v251, 28
	v_readlane_b32 s44, v251, 29
	v_readlane_b32 s45, v251, 30
	v_readlane_b32 s46, v251, 31
	v_readlane_b32 s47, v251, 32
	v_readlane_b32 s48, v251, 33
	v_readlane_b32 s49, v251, 34
	v_readlane_b32 s50, v251, 35
	v_readlane_b32 s51, v251, 36
	v_readlane_b32 s52, v251, 37
	v_readlane_b32 s53, v251, 38
	v_readlane_b32 s54, v251, 39
	v_readlane_b32 s55, v251, 40
	s_waitcnt vmcnt(0)
	v_pk_fma_f32 v[120:121], v[136:137], v[128:129], v[156:157]
	v_pk_fma_f32 v[118:119], v[134:135], v[126:127], v[154:155]
	v_pk_fma_f32 v[124:125], v[132:133], v[124:125], v[160:161]
	v_pk_fma_f32 v[122:123], v[130:131], v[122:123], v[158:159]
	v_pk_fma_f32 v[128:129], v[144:145], v[188:189], v[166:167]
	v_pk_fma_f32 v[126:127], v[142:143], v[180:181], v[164:165]
	v_pk_fma_f32 v[116:117], v[140:141], v[116:117], v[174:175]
	v_pk_fma_f32 v[114:115], v[138:139], v[114:115], v[172:173]
	v_add_u32_e32 v154, 32, v150
	global_load_dwordx4 v[156:159], v[178:179], off
	global_load_dwordx4 v[164:167], v[178:179], off offset:64
	global_load_dwordx4 v[172:175], v[178:179], off offset:512
	s_nop 0
	global_load_dwordx4 v[176:179], v[178:179], off offset:576
	ds_read_b64 v[160:161], v184 offset:8320
	v_ashrrev_i32_e32 v155, 31, v154
	v_lshlrev_b64 v[180:181], 12, v[154:155]
	v_lshl_add_u64 v[180:181], s[0:1], 0, v[180:181]
	v_lshl_add_u64 v[180:181], v[180:181], 0, v[168:169]
	s_waitcnt lgkmcnt(0)
	v_pk_mul_f32 v[110:111], v[110:111], v[160:161] op_sel:[0,1]
	v_pk_mul_f32 v[112:113], v[112:113], v[160:161] op_sel:[0,1]
	v_pk_mul_f32 v[106:107], v[106:107], v[160:161] op_sel:[0,1]
	v_pk_mul_f32 v[108:109], v[108:109], v[160:161] op_sel:[0,1]
	v_pk_mul_f32 v[102:103], v[102:103], v[160:161] op_sel:[0,1]
	v_pk_mul_f32 v[104:105], v[104:105], v[160:161] op_sel:[0,1]
	v_pk_mul_f32 v[98:99], v[98:99], v[160:161] op_sel:[0,1]
	v_pk_mul_f32 v[100:101], v[100:101], v[160:161] op_sel:[0,1]
	v_mov_b32_e32 v196, v118
	v_mov_b32_e32 v197, v121
	v_mov_b32_e32 v204, v123
	v_mov_b32_e32 v205, v124
	v_mov_b32_e32 v206, v122
	v_mov_b32_e32 v207, v125
	v_add_f32_e32 v209, v126, v127
	v_add_f32_e32 v213, v128, v129
	v_mov_b32_e32 v208, v114
	v_mov_b32_e32 v212, v115
	v_mov_b32_e32 v214, v117
	s_waitcnt vmcnt(3)
	v_pk_fma_f32 v[112:113], v[136:137], v[112:113], v[158:159]
	v_pk_fma_f32 v[110:111], v[134:135], v[110:111], v[156:157]
	s_waitcnt vmcnt(2)
	v_pk_fma_f32 v[108:109], v[132:133], v[108:109], v[166:167]
	v_pk_fma_f32 v[106:107], v[130:131], v[106:107], v[164:165]
	s_waitcnt vmcnt(1)
	v_pk_fma_f32 v[104:105], v[144:145], v[104:105], v[174:175]
	v_pk_fma_f32 v[102:103], v[142:143], v[102:103], v[172:173]
	s_waitcnt vmcnt(0)
	v_pk_fma_f32 v[100:101], v[140:141], v[100:101], v[178:179]
	v_pk_fma_f32 v[98:99], v[138:139], v[98:99], v[176:177]
	v_add_u32_e32 v156, 48, v150
	global_load_dwordx4 v[158:161], v[180:181], off
	global_load_dwordx4 v[164:167], v[180:181], off offset:64
	global_load_dwordx4 v[172:175], v[180:181], off offset:512
	global_load_dwordx4 v[176:179], v[180:181], off offset:576
	ds_read_b64 v[180:181], v184 offset:8448
	v_ashrrev_i32_e32 v157, 31, v156
	v_lshlrev_b64 v[188:189], 12, v[156:157]
	v_lshl_add_u64 v[188:189], s[0:1], 0, v[188:189]
	v_lshl_add_u64 v[188:189], v[188:189], 0, v[168:169]
	s_waitcnt lgkmcnt(0)
	v_pk_mul_f32 v[94:95], v[94:95], v[180:181] op_sel:[0,1]
	v_pk_mul_f32 v[96:97], v[96:97], v[180:181] op_sel:[0,1]
	v_pk_mul_f32 v[90:91], v[90:91], v[180:181] op_sel:[0,1]
	v_pk_mul_f32 v[92:93], v[92:93], v[180:181] op_sel:[0,1]
	v_pk_mul_f32 v[86:87], v[86:87], v[180:181] op_sel:[0,1]
	v_pk_mul_f32 v[88:89], v[88:89], v[180:181] op_sel:[0,1]
	v_pk_mul_f32 v[82:83], v[82:83], v[180:181] op_sel:[0,1]
	v_pk_mul_f32 v[84:85], v[84:85], v[180:181] op_sel:[0,1]
	s_waitcnt vmcnt(3)
	v_pk_fma_f32 v[96:97], v[136:137], v[96:97], v[160:161]
	v_pk_fma_f32 v[94:95], v[134:135], v[94:95], v[158:159]
	s_waitcnt vmcnt(2)
	v_pk_fma_f32 v[92:93], v[132:133], v[92:93], v[166:167]
	v_pk_fma_f32 v[90:91], v[130:131], v[90:91], v[164:165]
	s_waitcnt vmcnt(1)
	v_pk_fma_f32 v[88:89], v[144:145], v[88:89], v[174:175]
	v_pk_fma_f32 v[86:87], v[142:143], v[86:87], v[172:173]
	s_waitcnt vmcnt(0)
	v_pk_fma_f32 v[84:85], v[140:141], v[84:85], v[178:179]
	v_pk_fma_f32 v[82:83], v[138:139], v[82:83], v[176:177]
	v_add_u32_e32 v158, 0x80, v150
	global_load_dwordx4 v[164:167], v[188:189], off
	global_load_dwordx4 v[172:175], v[188:189], off offset:64
	global_load_dwordx4 v[176:179], v[188:189], off offset:512
	s_nop 0
	global_load_dwordx4 v[188:191], v[188:189], off offset:576
	ds_read_b64 v[160:161], v184 offset:8576
	v_ashrrev_i32_e32 v159, 31, v158
	v_lshlrev_b64 v[180:181], 12, v[158:159]
	v_lshl_add_u64 v[180:181], s[0:1], 0, v[180:181]
	v_lshl_add_u64 v[180:181], v[180:181], 0, v[168:169]
	s_waitcnt lgkmcnt(0)
	v_pk_mul_f32 v[78:79], v[78:79], v[160:161] op_sel:[0,1]
	v_pk_mul_f32 v[80:81], v[80:81], v[160:161] op_sel:[0,1]
	v_pk_mul_f32 v[74:75], v[74:75], v[160:161] op_sel:[0,1]
	v_pk_mul_f32 v[76:77], v[76:77], v[160:161] op_sel:[0,1]
	v_pk_mul_f32 v[70:71], v[70:71], v[160:161] op_sel:[0,1]
	v_pk_mul_f32 v[72:73], v[72:73], v[160:161] op_sel:[0,1]
	v_pk_mul_f32 v[66:67], v[66:67], v[160:161] op_sel:[0,1]
	v_pk_mul_f32 v[68:69], v[68:69], v[160:161] op_sel:[0,1]
	v_add_u32_e32 v160, 0x90, v150
	v_ashrrev_i32_e32 v161, 31, v160
	v_lshlrev_b64 v[192:193], 12, v[160:161]
	v_lshl_add_u64 v[192:193], s[0:1], 0, v[192:193]
	v_lshl_add_u64 v[192:193], v[192:193], 0, v[168:169]
	s_waitcnt vmcnt(3)
	v_pk_fma_f32 v[80:81], v[136:137], v[80:81], v[166:167]
	v_pk_fma_f32 v[78:79], v[134:135], v[78:79], v[164:165]
	s_waitcnt vmcnt(2)
	v_pk_fma_f32 v[76:77], v[132:133], v[76:77], v[174:175]
	v_pk_fma_f32 v[74:75], v[130:131], v[74:75], v[172:173]
	s_waitcnt vmcnt(1)
	v_pk_fma_f32 v[72:73], v[144:145], v[72:73], v[178:179]
	v_pk_fma_f32 v[70:71], v[142:143], v[70:71], v[176:177]
	s_waitcnt vmcnt(0)
	v_pk_fma_f32 v[68:69], v[140:141], v[68:69], v[190:191]
	v_pk_fma_f32 v[66:67], v[138:139], v[66:67], v[188:189]
	s_nop 0
	global_load_dwordx4 v[164:167], v[180:181], off
	global_load_dwordx4 v[172:175], v[180:181], off offset:64
	global_load_dwordx4 v[176:179], v[180:181], off offset:512
	global_load_dwordx4 v[188:191], v[180:181], off offset:576
	ds_read_b64 v[180:181], v184 offset:9216
	s_waitcnt lgkmcnt(0)
	v_pk_mul_f32 v[62:63], v[62:63], v[180:181] op_sel:[0,1]
	v_pk_mul_f32 v[64:65], v[64:65], v[180:181] op_sel:[0,1]
	v_pk_mul_f32 v[58:59], v[58:59], v[180:181] op_sel:[0,1]
	v_pk_mul_f32 v[60:61], v[60:61], v[180:181] op_sel:[0,1]
	v_pk_mul_f32 v[54:55], v[54:55], v[180:181] op_sel:[0,1]
	v_pk_mul_f32 v[56:57], v[56:57], v[180:181] op_sel:[0,1]
	v_pk_mul_f32 v[50:51], v[50:51], v[180:181] op_sel:[0,1]
	v_pk_mul_f32 v[52:53], v[52:53], v[180:181] op_sel:[0,1]
	s_waitcnt vmcnt(3)
	v_pk_fma_f32 v[64:65], v[136:137], v[64:65], v[166:167]
	v_pk_fma_f32 v[62:63], v[134:135], v[62:63], v[164:165]
	s_waitcnt vmcnt(2)
	v_pk_fma_f32 v[60:61], v[132:133], v[60:61], v[174:175]
	v_pk_fma_f32 v[58:59], v[130:131], v[58:59], v[172:173]
	s_waitcnt vmcnt(1)
	v_pk_fma_f32 v[56:57], v[144:145], v[56:57], v[178:179]
	v_pk_fma_f32 v[54:55], v[142:143], v[54:55], v[176:177]
	s_waitcnt vmcnt(0)
	v_pk_fma_f32 v[52:53], v[140:141], v[52:53], v[190:191]
	v_pk_fma_f32 v[50:51], v[138:139], v[50:51], v[188:189]
	v_add_u32_e32 v164, 0xa0, v150
	global_load_dwordx4 v[172:175], v[192:193], off
	global_load_dwordx4 v[176:179], v[192:193], off offset:64
	global_load_dwordx4 v[188:191], v[192:193], off offset:512
	s_nop 0
	global_load_dwordx4 v[192:195], v[192:193], off offset:576
	ds_read_b64 v[166:167], v184 offset:9344
	v_ashrrev_i32_e32 v165, 31, v164
	v_lshlrev_b64 v[180:181], 12, v[164:165]
	v_lshl_add_u64 v[180:181], s[0:1], 0, v[180:181]
	v_lshl_add_u64 v[180:181], v[180:181], 0, v[168:169]
	s_waitcnt lgkmcnt(0)
	v_pk_mul_f32 v[46:47], v[46:47], v[166:167] op_sel:[0,1]
	v_pk_mul_f32 v[48:49], v[48:49], v[166:167] op_sel:[0,1]
	v_pk_mul_f32 v[42:43], v[42:43], v[166:167] op_sel:[0,1]
	v_pk_mul_f32 v[44:45], v[44:45], v[166:167] op_sel:[0,1]
	v_pk_mul_f32 v[38:39], v[38:39], v[166:167] op_sel:[0,1]
	v_pk_mul_f32 v[40:41], v[40:41], v[166:167] op_sel:[0,1]
	v_pk_mul_f32 v[34:35], v[34:35], v[166:167] op_sel:[0,1]
	v_pk_mul_f32 v[36:37], v[36:37], v[166:167] op_sel:[0,1]
	v_add_u32_e32 v166, 0xb0, v150
	v_ashrrev_i32_e32 v167, 31, v166
	s_waitcnt vmcnt(3)
	v_pk_fma_f32 v[48:49], v[136:137], v[48:49], v[174:175]
	v_pk_fma_f32 v[46:47], v[134:135], v[46:47], v[172:173]
	s_waitcnt vmcnt(2)
	v_pk_fma_f32 v[44:45], v[132:133], v[44:45], v[178:179]
	v_pk_fma_f32 v[42:43], v[130:131], v[42:43], v[176:177]
	s_waitcnt vmcnt(1)
	v_pk_fma_f32 v[40:41], v[144:145], v[40:41], v[190:191]
	v_pk_fma_f32 v[38:39], v[142:143], v[38:39], v[188:189]
	s_waitcnt vmcnt(0)
	v_pk_fma_f32 v[36:37], v[140:141], v[36:37], v[194:195]
	v_pk_fma_f32 v[34:35], v[138:139], v[34:35], v[192:193]
	s_nop 0
	global_load_dwordx4 v[172:175], v[180:181], off
	global_load_dwordx4 v[176:179], v[180:181], off offset:64
	global_load_dwordx4 v[188:191], v[180:181], off offset:512
	global_load_dwordx4 v[192:195], v[180:181], off offset:576
	ds_read_b64 v[210:211], v184 offset:9472
	v_lshlrev_b64 v[180:181], 12, v[166:167]
	v_lshl_add_u64 v[180:181], s[0:1], 0, v[180:181]
	v_lshl_add_u64 v[168:169], v[180:181], 0, v[168:169]
	v_mov_b32_e32 v180, v119
	s_waitcnt lgkmcnt(0)
	v_pk_mul_f32 v[30:31], v[30:31], v[210:211] op_sel:[0,1]
	v_pk_mul_f32 v[32:33], v[32:33], v[210:211] op_sel:[0,1]
	v_pk_mul_f32 v[26:27], v[26:27], v[210:211] op_sel:[0,1]
	v_pk_mul_f32 v[28:29], v[28:29], v[210:211] op_sel:[0,1]
	v_pk_mul_f32 v[22:23], v[22:23], v[210:211] op_sel:[0,1]
	v_pk_mul_f32 v[24:25], v[24:25], v[210:211] op_sel:[0,1]
	v_pk_mul_f32 v[18:19], v[18:19], v[210:211] op_sel:[0,1]
	v_pk_mul_f32 v[20:21], v[20:21], v[210:211] op_sel:[0,1]
	v_mov_b32_e32 v181, v120
	s_waitcnt vmcnt(3)
	v_pk_fma_f32 v[32:33], v[136:137], v[32:33], v[174:175]
	v_pk_fma_f32 v[30:31], v[134:135], v[30:31], v[172:173]
	s_waitcnt vmcnt(2)
	v_pk_fma_f32 v[28:29], v[132:133], v[28:29], v[178:179]
	v_pk_fma_f32 v[26:27], v[130:131], v[26:27], v[176:177]
	s_waitcnt vmcnt(1)
	v_pk_fma_f32 v[24:25], v[144:145], v[24:25], v[190:191]
	v_pk_fma_f32 v[22:23], v[142:143], v[22:23], v[188:189]
	s_waitcnt vmcnt(0)
	v_pk_fma_f32 v[20:21], v[140:141], v[20:21], v[194:195]
	v_pk_fma_f32 v[18:19], v[138:139], v[18:19], v[192:193]
	v_pk_add_f32 v[172:173], v[180:181], v[196:197]
	global_load_dwordx4 v[174:177], v[168:169], off
	global_load_dwordx4 v[178:181], v[168:169], off offset:64
	global_load_dwordx4 v[188:191], v[168:169], off offset:512
	global_load_dwordx4 v[192:195], v[168:169], off offset:576
	v_pk_add_f32 v[196:197], v[204:205], v[206:207]
	v_add_f32_e32 v172, v172, v173
	v_pk_add_f32 v[168:169], v[196:197], v[196:197] op_sel_hi:[0,1]
	v_add_f32_e32 v215, 0, v172
	v_mov_b32_e32 v168, v116
	v_pk_add_f32 v[204:205], v[208:209], v[212:213]
	v_pk_add_f32 v[168:169], v[168:169], v[214:215]
	s_nop 0
	v_pk_add_f32 v[168:169], v[204:205], v[168:169]
	s_nop 0
	v_add_f32_e32 v168, v168, v169
	v_mov_b32_e32 v169, v168
	s_nop 1
	v_permlane16_swap_b32_e32 v168, v169
	s_waitcnt lgkmcnt(0)
	v_add_f32_e32 v168, v168, v169
	v_mov_b32_e32 v169, v168
	s_nop 1
	v_permlane32_swap_b32_e32 v168, v169
	s_waitcnt lgkmcnt(0)
	v_add_f32_e32 v168, v168, v169
	v_fmamk_f32 v172, v168, 0xbc800000, v121
	v_fmamk_f32 v187, v168, 0xbc800000, v119
	v_fmamk_f32 v197, v168, 0xbc800000, v125
	v_fmamk_f32 v205, v168, 0xbc800000, v123
	v_fmamk_f32 v169, v168, 0xbc800000, v120
	v_fmamk_f32 v173, v168, 0xbc800000, v118
	v_fmamk_f32 v196, v168, 0xbc800000, v124
	v_fmamk_f32 v204, v168, 0xbc800000, v122
	v_fmamk_f32 v207, v168, 0xbc800000, v129
	v_fmamk_f32 v209, v168, 0xbc800000, v127
	v_mul_f32_e32 v187, v187, v187
	v_mul_f32_e32 v172, v172, v172
	v_mul_f32_e32 v205, v205, v205
	v_mul_f32_e32 v197, v197, v197
	v_fmamk_f32 v206, v168, 0xbc800000, v128
	v_fmamk_f32 v208, v168, 0xbc800000, v126
	v_fmamk_f32 v211, v168, 0xbc800000, v117
	v_fmamk_f32 v213, v168, 0xbc800000, v115
	v_mul_f32_e32 v209, v209, v209
	v_mul_f32_e32 v207, v207, v207
	v_fmac_f32_e32 v187, v173, v173
	v_fmac_f32_e32 v172, v169, v169
	v_fmac_f32_e32 v205, v204, v204
	v_fmac_f32_e32 v197, v196, v196
	v_fmamk_f32 v210, v168, 0xbc800000, v116
	v_fmamk_f32 v212, v168, 0xbc800000, v114
	v_mul_f32_e32 v213, v213, v213
	v_mul_f32_e32 v211, v211, v211
	v_fmac_f32_e32 v209, v208, v208
	v_fmac_f32_e32 v207, v206, v206
	v_add_f32_e32 v169, v187, v172
	v_add_f32_e32 v172, v205, v197
	v_fmac_f32_e32 v213, v212, v212
	v_fmac_f32_e32 v211, v210, v210
	v_add_f32_e32 v173, v209, v207
	v_add_f32_e32 v169, v169, v172
	v_add_f32_e32 v187, v213, v211
	v_add_f32_e32 v169, v173, v169
	v_add_f32_e32 v169, v187, v169
	v_mov_b32_e32 v172, v169
	s_nop 1
	v_permlane16_swap_b32_e32 v169, v172
	ds_read_b64 v[196:197], v184 offset:9600
	s_waitcnt lgkmcnt(1)
	v_add_f32_e32 v169, v169, v172
	ds_bpermute_b32 v172, v202, v169
	s_waitcnt lgkmcnt(1)
	v_pk_mul_f32 v[14:15], v[14:15], v[196:197] op_sel:[0,1]
	v_pk_mul_f32 v[16:17], v[16:17], v[196:197] op_sel:[0,1]
	v_pk_mul_f32 v[10:11], v[10:11], v[196:197] op_sel:[0,1]
	v_pk_mul_f32 v[12:13], v[12:13], v[196:197] op_sel:[0,1]
	v_pk_mul_f32 v[6:7], v[6:7], v[196:197] op_sel:[0,1]
	v_pk_mul_f32 v[8:9], v[8:9], v[196:197] op_sel:[0,1]
	v_pk_mul_f32 v[2:3], v[2:3], v[196:197] op_sel:[0,1]
	v_pk_mul_f32 v[4:5], v[4:5], v[196:197] op_sel:[0,1]
	s_waitcnt vmcnt(3)
	v_pk_fma_f32 v[16:17], v[136:137], v[16:17], v[176:177]
	v_pk_fma_f32 v[14:15], v[134:135], v[14:15], v[174:175]
	s_waitcnt vmcnt(2)
	v_pk_fma_f32 v[12:13], v[132:133], v[12:13], v[180:181]
	v_pk_fma_f32 v[10:11], v[130:131], v[10:11], v[178:179]
	s_waitcnt vmcnt(1)
	v_pk_fma_f32 v[8:9], v[144:145], v[8:9], v[190:191]
	v_pk_fma_f32 v[6:7], v[142:143], v[6:7], v[188:189]
	s_waitcnt vmcnt(0)
	v_pk_fma_f32 v[4:5], v[140:141], v[4:5], v[194:195]
	v_pk_fma_f32 v[2:3], v[138:139], v[2:3], v[192:193]
	s_nop 0
	s_and_saveexec_b64 s[0:1], s[4:5]
	s_cbranch_execz .LBB0_612
	s_lshl_b32 s17, s26, 11
	s_add_i32 s17, s27, s17
	v_mul_f32_e32 v130, 0x3c800000, v168
	s_waitcnt lgkmcnt(0)
	v_add_f32_e32 v131, v169, v172
	v_lshl_add_u32 v132, v170, 5, s17
	ds_write_b64 v132, v[130:131]
.LBB0_612:
	s_or_b64 exec, exec, s[0:1]
	v_mov_b32_e32 v130, v111
	v_mov_b32_e32 v131, v112
	v_mov_b32_e32 v132, v110
	v_mov_b32_e32 v133, v113
	v_pk_add_f32 v[130:131], v[130:131], v[132:133]
	v_mov_b32_e32 v132, v107
	v_mov_b32_e32 v133, v108
	v_mov_b32_e32 v134, v106
	v_mov_b32_e32 v135, v109
	v_pk_add_f32 v[132:133], v[132:133], v[134:135]
	v_add_f32_e32 v130, v130, v131
	v_pk_add_f32 v[132:133], v[132:133], v[132:133] op_sel_hi:[0,1]
	v_add_f32_e32 v131, 0, v130
	v_add_f32_e32 v135, v102, v103
	v_add_f32_e32 v137, v104, v105
	v_mov_b32_e32 v134, v98
	v_mov_b32_e32 v136, v99
	v_mov_b32_e32 v132, v100
	v_mov_b32_e32 v130, v101
	v_pk_add_f32 v[134:135], v[134:135], v[136:137]
	v_pk_add_f32 v[130:131], v[132:133], v[130:131]
	s_nop 0
	v_pk_add_f32 v[130:131], v[134:135], v[130:131]
	s_nop 0
	v_add_f32_e32 v130, v130, v131
	v_mov_b32_e32 v131, v130
	s_nop 1
	v_permlane16_swap_b32_e32 v130, v131
	s_waitcnt lgkmcnt(0)
	v_add_f32_e32 v130, v130, v131
	v_mov_b32_e32 v131, v130
	s_nop 1
	v_permlane32_swap_b32_e32 v130, v131
	s_waitcnt lgkmcnt(0)
	v_add_f32_e32 v130, v130, v131
	v_fmamk_f32 v132, v130, 0xbc800000, v113
	v_fmamk_f32 v134, v130, 0xbc800000, v111
	v_fmamk_f32 v131, v130, 0xbc800000, v112
	v_fmamk_f32 v133, v130, 0xbc800000, v110
	v_mul_f32_e32 v134, v134, v134
	v_mul_f32_e32 v132, v132, v132
	v_fmac_f32_e32 v134, v133, v133
	v_fmac_f32_e32 v132, v131, v131
	v_fmamk_f32 v133, v130, 0xbc800000, v109
	v_fmamk_f32 v135, v130, 0xbc800000, v107
	v_add_f32_e32 v131, v134, v132
	v_fmamk_f32 v132, v130, 0xbc800000, v108
	v_fmamk_f32 v134, v130, 0xbc800000, v106
	v_mul_f32_e32 v135, v135, v135
	v_mul_f32_e32 v133, v133, v133
	v_fmac_f32_e32 v135, v134, v134
	v_fmac_f32_e32 v133, v132, v132
	v_add_f32_e32 v132, v135, v133
	v_fmamk_f32 v133, v130, 0xbc800000, v105
	v_fmamk_f32 v135, v130, 0xbc800000, v103
	v_add_f32_e32 v131, v131, v132
	v_fmamk_f32 v132, v130, 0xbc800000, v104
	v_fmamk_f32 v134, v130, 0xbc800000, v102
	v_mul_f32_e32 v135, v135, v135
	v_mul_f32_e32 v133, v133, v133
	v_fmac_f32_e32 v135, v134, v134
	v_fmac_f32_e32 v133, v132, v132
	v_add_f32_e32 v132, v135, v133
	v_fmamk_f32 v133, v130, 0xbc800000, v101
	v_fmamk_f32 v135, v130, 0xbc800000, v99
	v_add_f32_e32 v131, v132, v131
	v_fmamk_f32 v132, v130, 0xbc800000, v100
	v_fmamk_f32 v134, v130, 0xbc800000, v98
	v_mul_f32_e32 v135, v135, v135
	v_mul_f32_e32 v133, v133, v133
	v_fmac_f32_e32 v135, v134, v134
	v_fmac_f32_e32 v133, v132, v132
	v_add_f32_e32 v132, v135, v133
	v_add_f32_e32 v131, v132, v131
	v_mov_b32_e32 v132, v131
	s_nop 1
	v_permlane16_swap_b32_e32 v131, v132
	s_waitcnt lgkmcnt(0)
	v_add_f32_e32 v131, v131, v132
	v_mov_b32_e32 v132, v131
	s_nop 1
	v_permlane32_swap_b32_e32 v131, v132
	s_and_saveexec_b64 s[0:1], s[4:5]
	s_cbranch_execz .LBB0_614
	s_lshl_b32 s17, s26, 11
	s_add_i32 s17, s27, s17
	v_mul_f32_e32 v130, 0x3c800000, v130
	s_waitcnt lgkmcnt(0)
	v_add_f32_e32 v131, v131, v132
	v_lshl_add_u32 v132, v170, 5, s17
	ds_write_b64 v132, v[130:131] offset:512
.LBB0_614:
	s_or_b64 exec, exec, s[0:1]
	v_mov_b32_e32 v130, v95
	v_mov_b32_e32 v131, v96
	s_waitcnt lgkmcnt(0)
	v_mov_b32_e32 v132, v94
	v_mov_b32_e32 v133, v97
	v_pk_add_f32 v[130:131], v[130:131], v[132:133]
	v_mov_b32_e32 v132, v91
	v_mov_b32_e32 v133, v92
	v_mov_b32_e32 v134, v90
	v_mov_b32_e32 v135, v93
	v_pk_add_f32 v[132:133], v[132:133], v[134:135]
	v_add_f32_e32 v130, v130, v131
	v_pk_add_f32 v[132:133], v[132:133], v[132:133] op_sel_hi:[0,1]
	v_add_f32_e32 v131, 0, v130
	v_add_f32_e32 v135, v86, v87
	v_add_f32_e32 v137, v88, v89
	v_mov_b32_e32 v134, v82
	v_mov_b32_e32 v136, v83
	v_mov_b32_e32 v132, v84
	v_mov_b32_e32 v130, v85
	v_pk_add_f32 v[134:135], v[134:135], v[136:137]
	v_pk_add_f32 v[130:131], v[132:133], v[130:131]
	s_nop 0
	v_pk_add_f32 v[130:131], v[134:135], v[130:131]
	s_nop 0
	v_add_f32_e32 v130, v130, v131
	v_mov_b32_e32 v131, v130
	s_nop 1
	v_permlane16_swap_b32_e32 v130, v131
	s_waitcnt lgkmcnt(0)
	v_add_f32_e32 v130, v130, v131
	v_mov_b32_e32 v131, v130
	s_nop 1
	v_permlane32_swap_b32_e32 v130, v131
	s_waitcnt lgkmcnt(0)
	v_add_f32_e32 v130, v130, v131
	v_fmamk_f32 v132, v130, 0xbc800000, v97
	v_fmamk_f32 v134, v130, 0xbc800000, v95
	v_fmamk_f32 v131, v130, 0xbc800000, v96
	v_fmamk_f32 v133, v130, 0xbc800000, v94
	v_mul_f32_e32 v134, v134, v134
	v_mul_f32_e32 v132, v132, v132
	v_fmac_f32_e32 v134, v133, v133
	v_fmac_f32_e32 v132, v131, v131
	v_fmamk_f32 v133, v130, 0xbc800000, v93
	v_fmamk_f32 v135, v130, 0xbc800000, v91
	v_add_f32_e32 v131, v134, v132
	v_fmamk_f32 v132, v130, 0xbc800000, v92
	v_fmamk_f32 v134, v130, 0xbc800000, v90
	v_mul_f32_e32 v135, v135, v135
	v_mul_f32_e32 v133, v133, v133
	v_fmac_f32_e32 v135, v134, v134
	v_fmac_f32_e32 v133, v132, v132
	v_add_f32_e32 v132, v135, v133
	v_fmamk_f32 v133, v130, 0xbc800000, v89
	v_fmamk_f32 v135, v130, 0xbc800000, v87
	v_add_f32_e32 v131, v131, v132
	v_fmamk_f32 v132, v130, 0xbc800000, v88
	v_fmamk_f32 v134, v130, 0xbc800000, v86
	v_mul_f32_e32 v135, v135, v135
	v_mul_f32_e32 v133, v133, v133
	v_fmac_f32_e32 v135, v134, v134
	v_fmac_f32_e32 v133, v132, v132
	v_add_f32_e32 v132, v135, v133
	v_fmamk_f32 v133, v130, 0xbc800000, v85
	v_fmamk_f32 v135, v130, 0xbc800000, v83
	v_add_f32_e32 v131, v132, v131
	v_fmamk_f32 v132, v130, 0xbc800000, v84
	v_fmamk_f32 v134, v130, 0xbc800000, v82
	v_mul_f32_e32 v135, v135, v135
	v_mul_f32_e32 v133, v133, v133
	v_fmac_f32_e32 v135, v134, v134
	v_fmac_f32_e32 v133, v132, v132
	v_add_f32_e32 v132, v135, v133
	v_add_f32_e32 v131, v132, v131
	v_mov_b32_e32 v132, v131
	s_nop 1
	v_permlane16_swap_b32_e32 v131, v132
	s_waitcnt lgkmcnt(0)
	v_add_f32_e32 v131, v131, v132
	v_mov_b32_e32 v132, v131
	s_nop 1
	v_permlane32_swap_b32_e32 v131, v132
	s_and_saveexec_b64 s[0:1], s[4:5]
	s_cbranch_execz .LBB0_616
	s_lshl_b32 s17, s26, 11
	s_add_i32 s17, s27, s17
	v_mul_f32_e32 v130, 0x3c800000, v130
	s_waitcnt lgkmcnt(0)
	v_add_f32_e32 v131, v131, v132
	v_lshl_add_u32 v132, v170, 5, s17
	ds_write_b64 v132, v[130:131] offset:1024
.LBB0_616:
	s_or_b64 exec, exec, s[0:1]
	v_mov_b32_e32 v130, v79
	v_mov_b32_e32 v131, v80
	s_waitcnt lgkmcnt(0)
	v_mov_b32_e32 v132, v78
	v_mov_b32_e32 v133, v81
	v_pk_add_f32 v[130:131], v[130:131], v[132:133]
	v_mov_b32_e32 v132, v75
	v_mov_b32_e32 v133, v76
	v_mov_b32_e32 v134, v74
	v_mov_b32_e32 v135, v77
	v_pk_add_f32 v[132:133], v[132:133], v[134:135]
	v_add_f32_e32 v130, v130, v131
	v_pk_add_f32 v[132:133], v[132:133], v[132:133] op_sel_hi:[0,1]
	v_add_f32_e32 v131, 0, v130
	v_add_f32_e32 v135, v70, v71
	v_add_f32_e32 v137, v72, v73
	v_mov_b32_e32 v134, v66
	v_mov_b32_e32 v136, v67
	v_mov_b32_e32 v132, v68
	v_mov_b32_e32 v130, v69
	v_pk_add_f32 v[134:135], v[134:135], v[136:137]
	v_pk_add_f32 v[130:131], v[132:133], v[130:131]
	s_nop 0
	v_pk_add_f32 v[130:131], v[134:135], v[130:131]
	s_nop 0
	v_add_f32_e32 v130, v130, v131
	v_mov_b32_e32 v131, v130
	s_nop 1
	v_permlane16_swap_b32_e32 v130, v131
	s_waitcnt lgkmcnt(0)
	v_add_f32_e32 v130, v130, v131
	v_mov_b32_e32 v131, v130
	s_nop 1
	v_permlane32_swap_b32_e32 v130, v131
	s_waitcnt lgkmcnt(0)
	v_add_f32_e32 v130, v130, v131
	v_fmamk_f32 v132, v130, 0xbc800000, v81
	v_fmamk_f32 v134, v130, 0xbc800000, v79
	v_fmamk_f32 v131, v130, 0xbc800000, v80
	v_fmamk_f32 v133, v130, 0xbc800000, v78
	v_mul_f32_e32 v134, v134, v134
	v_mul_f32_e32 v132, v132, v132
	v_fmac_f32_e32 v134, v133, v133
	v_fmac_f32_e32 v132, v131, v131
	v_fmamk_f32 v133, v130, 0xbc800000, v77
	v_fmamk_f32 v135, v130, 0xbc800000, v75
	v_add_f32_e32 v131, v134, v132
	v_fmamk_f32 v132, v130, 0xbc800000, v76
	v_fmamk_f32 v134, v130, 0xbc800000, v74
	v_mul_f32_e32 v135, v135, v135
	v_mul_f32_e32 v133, v133, v133
	v_fmac_f32_e32 v135, v134, v134
	v_fmac_f32_e32 v133, v132, v132
	v_add_f32_e32 v132, v135, v133
	v_fmamk_f32 v133, v130, 0xbc800000, v73
	v_fmamk_f32 v135, v130, 0xbc800000, v71
	v_add_f32_e32 v131, v131, v132
	v_fmamk_f32 v132, v130, 0xbc800000, v72
	v_fmamk_f32 v134, v130, 0xbc800000, v70
	v_mul_f32_e32 v135, v135, v135
	v_mul_f32_e32 v133, v133, v133
	v_fmac_f32_e32 v135, v134, v134
	v_fmac_f32_e32 v133, v132, v132
	v_add_f32_e32 v132, v135, v133
	v_fmamk_f32 v133, v130, 0xbc800000, v69
	v_fmamk_f32 v135, v130, 0xbc800000, v67
	v_add_f32_e32 v131, v132, v131
	v_fmamk_f32 v132, v130, 0xbc800000, v68
	v_fmamk_f32 v134, v130, 0xbc800000, v66
	v_mul_f32_e32 v135, v135, v135
	v_mul_f32_e32 v133, v133, v133
	v_fmac_f32_e32 v135, v134, v134
	v_fmac_f32_e32 v133, v132, v132
	v_add_f32_e32 v132, v135, v133
	v_add_f32_e32 v131, v132, v131
	v_mov_b32_e32 v132, v131
	s_nop 1
	v_permlane16_swap_b32_e32 v131, v132
	s_waitcnt lgkmcnt(0)
	v_add_f32_e32 v131, v131, v132
	v_mov_b32_e32 v132, v131
	s_nop 1
	v_permlane32_swap_b32_e32 v131, v132
	s_and_saveexec_b64 s[0:1], s[4:5]
	s_cbranch_execz .LBB0_618
	s_lshl_b32 s17, s26, 11
	s_add_i32 s17, s27, s17
	v_mul_f32_e32 v130, 0x3c800000, v130
	s_waitcnt lgkmcnt(0)
	v_add_f32_e32 v131, v131, v132
	v_lshl_add_u32 v132, v170, 5, s17
	ds_write_b64 v132, v[130:131] offset:1536
.LBB0_618:
	s_or_b64 exec, exec, s[0:1]
	v_mov_b32_e32 v130, v63
	v_mov_b32_e32 v131, v64
	s_waitcnt lgkmcnt(0)
	v_mov_b32_e32 v132, v62
	v_mov_b32_e32 v133, v65
	v_pk_add_f32 v[130:131], v[130:131], v[132:133]
	v_mov_b32_e32 v132, v59
	v_mov_b32_e32 v133, v60
	v_mov_b32_e32 v134, v58
	v_mov_b32_e32 v135, v61
	v_pk_add_f32 v[132:133], v[132:133], v[134:135]
	v_add_f32_e32 v130, v130, v131
	v_pk_add_f32 v[132:133], v[132:133], v[132:133] op_sel_hi:[0,1]
	v_add_f32_e32 v131, 0, v130
	v_add_f32_e32 v135, v54, v55
	v_add_f32_e32 v137, v56, v57
	v_mov_b32_e32 v134, v50
	v_mov_b32_e32 v136, v51
	v_mov_b32_e32 v132, v52
	v_mov_b32_e32 v130, v53
	v_pk_add_f32 v[134:135], v[134:135], v[136:137]
	v_pk_add_f32 v[130:131], v[132:133], v[130:131]
	s_nop 0
	v_pk_add_f32 v[130:131], v[134:135], v[130:131]
	s_nop 0
	v_add_f32_e32 v130, v130, v131
	v_mov_b32_e32 v131, v130
	s_nop 1
	v_permlane16_swap_b32_e32 v130, v131
	s_waitcnt lgkmcnt(0)
	v_add_f32_e32 v130, v130, v131
	v_mov_b32_e32 v131, v130
	s_nop 1
	v_permlane32_swap_b32_e32 v130, v131
	s_waitcnt lgkmcnt(0)
	v_add_f32_e32 v130, v130, v131
	v_fmamk_f32 v132, v130, 0xbc800000, v65
	v_fmamk_f32 v134, v130, 0xbc800000, v63
	v_fmamk_f32 v131, v130, 0xbc800000, v64
	v_fmamk_f32 v133, v130, 0xbc800000, v62
	v_mul_f32_e32 v134, v134, v134
	v_mul_f32_e32 v132, v132, v132
	v_fmac_f32_e32 v134, v133, v133
	v_fmac_f32_e32 v132, v131, v131
	v_fmamk_f32 v133, v130, 0xbc800000, v61
	v_fmamk_f32 v135, v130, 0xbc800000, v59
	v_add_f32_e32 v131, v134, v132
	v_fmamk_f32 v132, v130, 0xbc800000, v60
	v_fmamk_f32 v134, v130, 0xbc800000, v58
	v_mul_f32_e32 v135, v135, v135
	v_mul_f32_e32 v133, v133, v133
	v_fmac_f32_e32 v135, v134, v134
	v_fmac_f32_e32 v133, v132, v132
	v_add_f32_e32 v132, v135, v133
	v_fmamk_f32 v133, v130, 0xbc800000, v57
	v_fmamk_f32 v135, v130, 0xbc800000, v55
	v_add_f32_e32 v131, v131, v132
	v_fmamk_f32 v132, v130, 0xbc800000, v56
	v_fmamk_f32 v134, v130, 0xbc800000, v54
	v_mul_f32_e32 v135, v135, v135
	v_mul_f32_e32 v133, v133, v133
	v_fmac_f32_e32 v135, v134, v134
	v_fmac_f32_e32 v133, v132, v132
	v_add_f32_e32 v132, v135, v133
	v_fmamk_f32 v133, v130, 0xbc800000, v53
	v_fmamk_f32 v135, v130, 0xbc800000, v51
	v_add_f32_e32 v131, v132, v131
	v_fmamk_f32 v132, v130, 0xbc800000, v52
	v_fmamk_f32 v134, v130, 0xbc800000, v50
	v_mul_f32_e32 v135, v135, v135
	v_mul_f32_e32 v133, v133, v133
	v_fmac_f32_e32 v135, v134, v134
	v_fmac_f32_e32 v133, v132, v132
	v_add_f32_e32 v132, v135, v133
	v_add_f32_e32 v131, v132, v131
	v_mov_b32_e32 v132, v131
	s_nop 1
	v_permlane16_swap_b32_e32 v131, v132
	s_waitcnt lgkmcnt(0)
	v_add_f32_e32 v131, v131, v132
	v_mov_b32_e32 v132, v131
	s_nop 1
	v_permlane32_swap_b32_e32 v131, v132
	s_and_saveexec_b64 s[0:1], s[4:5]
	s_cbranch_execz .LBB0_620
	s_lshl_b32 s17, s26, 11
	s_add_i32 s17, s27, s17
	v_mul_f32_e32 v130, 0x3c800000, v130
	s_waitcnt lgkmcnt(0)
	v_add_f32_e32 v131, v131, v132
	v_lshl_add_u32 v132, v170, 5, s17
	ds_write_b64 v132, v[130:131] offset:4096
.LBB0_620:
	s_or_b64 exec, exec, s[0:1]
	v_mov_b32_e32 v130, v47
	v_mov_b32_e32 v131, v48
	s_waitcnt lgkmcnt(0)
	v_mov_b32_e32 v132, v46
	v_mov_b32_e32 v133, v49
	v_pk_add_f32 v[130:131], v[130:131], v[132:133]
	v_mov_b32_e32 v132, v43
	v_mov_b32_e32 v133, v44
	v_mov_b32_e32 v134, v42
	v_mov_b32_e32 v135, v45
	v_pk_add_f32 v[132:133], v[132:133], v[134:135]
	v_add_f32_e32 v130, v130, v131
	v_pk_add_f32 v[132:133], v[132:133], v[132:133] op_sel_hi:[0,1]
	v_add_f32_e32 v131, 0, v130
	v_add_f32_e32 v135, v38, v39
	v_add_f32_e32 v137, v40, v41
	v_mov_b32_e32 v134, v34
	v_mov_b32_e32 v136, v35
	v_mov_b32_e32 v132, v36
	v_mov_b32_e32 v130, v37
	v_pk_add_f32 v[134:135], v[134:135], v[136:137]
	v_pk_add_f32 v[130:131], v[132:133], v[130:131]
	s_nop 0
	v_pk_add_f32 v[130:131], v[134:135], v[130:131]
	s_nop 0
	v_add_f32_e32 v130, v130, v131
	v_mov_b32_e32 v131, v130
	s_nop 1
	v_permlane16_swap_b32_e32 v130, v131
	s_waitcnt lgkmcnt(0)
	v_add_f32_e32 v130, v130, v131
	v_mov_b32_e32 v131, v130
	s_nop 1
	v_permlane32_swap_b32_e32 v130, v131
	s_waitcnt lgkmcnt(0)
	v_add_f32_e32 v130, v130, v131
	v_fmamk_f32 v132, v130, 0xbc800000, v49
	v_fmamk_f32 v134, v130, 0xbc800000, v47
	v_fmamk_f32 v131, v130, 0xbc800000, v48
	v_fmamk_f32 v133, v130, 0xbc800000, v46
	v_mul_f32_e32 v134, v134, v134
	v_mul_f32_e32 v132, v132, v132
	v_fmac_f32_e32 v134, v133, v133
	v_fmac_f32_e32 v132, v131, v131
	v_fmamk_f32 v133, v130, 0xbc800000, v45
	v_fmamk_f32 v135, v130, 0xbc800000, v43
	v_add_f32_e32 v131, v134, v132
	v_fmamk_f32 v132, v130, 0xbc800000, v44
	v_fmamk_f32 v134, v130, 0xbc800000, v42
	v_mul_f32_e32 v135, v135, v135
	v_mul_f32_e32 v133, v133, v133
	v_fmac_f32_e32 v135, v134, v134
	v_fmac_f32_e32 v133, v132, v132
	v_add_f32_e32 v132, v135, v133
	v_fmamk_f32 v133, v130, 0xbc800000, v41
	v_fmamk_f32 v135, v130, 0xbc800000, v39
	v_add_f32_e32 v131, v131, v132
	v_fmamk_f32 v132, v130, 0xbc800000, v40
	v_fmamk_f32 v134, v130, 0xbc800000, v38
	v_mul_f32_e32 v135, v135, v135
	v_mul_f32_e32 v133, v133, v133
	v_fmac_f32_e32 v135, v134, v134
	v_fmac_f32_e32 v133, v132, v132
	v_add_f32_e32 v132, v135, v133
	v_fmamk_f32 v133, v130, 0xbc800000, v37
	v_fmamk_f32 v135, v130, 0xbc800000, v35
	v_add_f32_e32 v131, v132, v131
	v_fmamk_f32 v132, v130, 0xbc800000, v36
	v_fmamk_f32 v134, v130, 0xbc800000, v34
	v_mul_f32_e32 v135, v135, v135
	v_mul_f32_e32 v133, v133, v133
	v_fmac_f32_e32 v135, v134, v134
	v_fmac_f32_e32 v133, v132, v132
	v_add_f32_e32 v132, v135, v133
	v_add_f32_e32 v131, v132, v131
	v_mov_b32_e32 v132, v131
	s_nop 1
	v_permlane16_swap_b32_e32 v131, v132
	s_waitcnt lgkmcnt(0)
	v_add_f32_e32 v131, v131, v132
	v_mov_b32_e32 v132, v131
	s_nop 1
	v_permlane32_swap_b32_e32 v131, v132
	s_and_saveexec_b64 s[0:1], s[4:5]
	s_cbranch_execz .LBB0_622
	s_lshl_b32 s17, s26, 11
	s_add_i32 s17, s27, s17
	v_mul_f32_e32 v130, 0x3c800000, v130
	s_waitcnt lgkmcnt(0)
	v_add_f32_e32 v131, v131, v132
	v_lshl_add_u32 v132, v170, 5, s17
	ds_write_b64 v132, v[130:131] offset:4608
.LBB0_622:
	s_or_b64 exec, exec, s[0:1]
	v_mov_b32_e32 v130, v31
	v_mov_b32_e32 v131, v32
	s_waitcnt lgkmcnt(0)
	v_mov_b32_e32 v132, v30
	v_mov_b32_e32 v133, v33
	v_pk_add_f32 v[130:131], v[130:131], v[132:133]
	v_mov_b32_e32 v132, v27
	v_mov_b32_e32 v133, v28
	v_mov_b32_e32 v134, v26
	v_mov_b32_e32 v135, v29
	v_pk_add_f32 v[132:133], v[132:133], v[134:135]
	v_add_f32_e32 v130, v130, v131
	v_pk_add_f32 v[132:133], v[132:133], v[132:133] op_sel_hi:[0,1]
	v_add_f32_e32 v131, 0, v130
	v_add_f32_e32 v135, v22, v23
	v_add_f32_e32 v137, v24, v25
	v_mov_b32_e32 v134, v18
	v_mov_b32_e32 v136, v19
	v_mov_b32_e32 v132, v20
	v_mov_b32_e32 v130, v21
	v_pk_add_f32 v[134:135], v[134:135], v[136:137]
	v_pk_add_f32 v[130:131], v[132:133], v[130:131]
	s_nop 0
	v_pk_add_f32 v[130:131], v[134:135], v[130:131]
	s_nop 0
	v_add_f32_e32 v130, v130, v131
	v_mov_b32_e32 v131, v130
	s_nop 1
	v_permlane16_swap_b32_e32 v130, v131
	s_waitcnt lgkmcnt(0)
	v_add_f32_e32 v130, v130, v131
	v_mov_b32_e32 v131, v130
	s_nop 1
	v_permlane32_swap_b32_e32 v130, v131
	s_waitcnt lgkmcnt(0)
	v_add_f32_e32 v130, v130, v131
	v_fmamk_f32 v132, v130, 0xbc800000, v33
	v_fmamk_f32 v134, v130, 0xbc800000, v31
	v_fmamk_f32 v131, v130, 0xbc800000, v32
	v_fmamk_f32 v133, v130, 0xbc800000, v30
	v_mul_f32_e32 v134, v134, v134
	v_mul_f32_e32 v132, v132, v132
	v_fmac_f32_e32 v134, v133, v133
	v_fmac_f32_e32 v132, v131, v131
	v_fmamk_f32 v133, v130, 0xbc800000, v29
	v_fmamk_f32 v135, v130, 0xbc800000, v27
	v_add_f32_e32 v131, v134, v132
	v_fmamk_f32 v132, v130, 0xbc800000, v28
	v_fmamk_f32 v134, v130, 0xbc800000, v26
	v_mul_f32_e32 v135, v135, v135
	v_mul_f32_e32 v133, v133, v133
	v_fmac_f32_e32 v135, v134, v134
	v_fmac_f32_e32 v133, v132, v132
	v_add_f32_e32 v132, v135, v133
	v_fmamk_f32 v133, v130, 0xbc800000, v25
	v_fmamk_f32 v135, v130, 0xbc800000, v23
	v_add_f32_e32 v131, v131, v132
	v_fmamk_f32 v132, v130, 0xbc800000, v24
	v_fmamk_f32 v134, v130, 0xbc800000, v22
	v_mul_f32_e32 v135, v135, v135
	v_mul_f32_e32 v133, v133, v133
	v_fmac_f32_e32 v135, v134, v134
	v_fmac_f32_e32 v133, v132, v132
	v_add_f32_e32 v132, v135, v133
	v_fmamk_f32 v133, v130, 0xbc800000, v21
	v_fmamk_f32 v135, v130, 0xbc800000, v19
	v_add_f32_e32 v131, v132, v131
	v_fmamk_f32 v132, v130, 0xbc800000, v20
	v_fmamk_f32 v134, v130, 0xbc800000, v18
	v_mul_f32_e32 v135, v135, v135
	v_mul_f32_e32 v133, v133, v133
	v_fmac_f32_e32 v135, v134, v134
	v_fmac_f32_e32 v133, v132, v132
	v_add_f32_e32 v132, v135, v133
	v_add_f32_e32 v131, v132, v131
	v_mov_b32_e32 v132, v131
	s_nop 1
	v_permlane16_swap_b32_e32 v131, v132
	s_waitcnt lgkmcnt(0)
	v_add_f32_e32 v131, v131, v132
	v_mov_b32_e32 v132, v131
	s_nop 1
	v_permlane32_swap_b32_e32 v131, v132
	s_and_saveexec_b64 s[0:1], s[4:5]
	s_cbranch_execz .LBB0_624
	s_lshl_b32 s17, s26, 11
	s_add_i32 s17, s27, s17
	v_mul_f32_e32 v130, 0x3c800000, v130
	s_waitcnt lgkmcnt(0)
	v_add_f32_e32 v131, v131, v132
	v_lshl_add_u32 v132, v170, 5, s17
	ds_write_b64 v132, v[130:131] offset:5120
.LBB0_624:
	s_or_b64 exec, exec, s[0:1]
	v_mov_b32_e32 v130, v15
	v_mov_b32_e32 v131, v16
	s_waitcnt lgkmcnt(0)
	v_mov_b32_e32 v132, v14
	v_mov_b32_e32 v133, v17
	v_pk_add_f32 v[130:131], v[130:131], v[132:133]
	v_mov_b32_e32 v132, v11
	v_mov_b32_e32 v133, v12
	v_mov_b32_e32 v134, v10
	v_mov_b32_e32 v135, v13
	v_pk_add_f32 v[132:133], v[132:133], v[134:135]
	v_add_f32_e32 v130, v130, v131
	v_pk_add_f32 v[132:133], v[132:133], v[132:133] op_sel_hi:[0,1]
	v_add_f32_e32 v131, 0, v130
	v_add_f32_e32 v135, v6, v7
	v_add_f32_e32 v137, v8, v9
	v_mov_b32_e32 v134, v2
	v_mov_b32_e32 v136, v3
	v_mov_b32_e32 v132, v4
	v_mov_b32_e32 v130, v5
	v_pk_add_f32 v[134:135], v[134:135], v[136:137]
	v_pk_add_f32 v[130:131], v[132:133], v[130:131]
	s_nop 0
	v_pk_add_f32 v[130:131], v[134:135], v[130:131]
	s_nop 0
	v_add_f32_e32 v130, v130, v131
	v_mov_b32_e32 v131, v130
	s_nop 1
	v_permlane16_swap_b32_e32 v130, v131
	s_waitcnt lgkmcnt(0)
	v_add_f32_e32 v130, v130, v131
	v_mov_b32_e32 v131, v130
	s_nop 1
	v_permlane32_swap_b32_e32 v130, v131
	s_waitcnt lgkmcnt(0)
	v_add_f32_e32 v130, v130, v131
	v_fmamk_f32 v132, v130, 0xbc800000, v17
	v_fmamk_f32 v134, v130, 0xbc800000, v15
	v_fmamk_f32 v131, v130, 0xbc800000, v16
	v_fmamk_f32 v133, v130, 0xbc800000, v14
	v_mul_f32_e32 v134, v134, v134
	v_mul_f32_e32 v132, v132, v132
	v_fmac_f32_e32 v134, v133, v133
	v_fmac_f32_e32 v132, v131, v131
	v_fmamk_f32 v133, v130, 0xbc800000, v13
	v_fmamk_f32 v135, v130, 0xbc800000, v11
	v_add_f32_e32 v131, v134, v132
	v_fmamk_f32 v132, v130, 0xbc800000, v12
	v_fmamk_f32 v134, v130, 0xbc800000, v10
	v_mul_f32_e32 v135, v135, v135
	v_mul_f32_e32 v133, v133, v133
	v_fmac_f32_e32 v135, v134, v134
	v_fmac_f32_e32 v133, v132, v132
	v_add_f32_e32 v132, v135, v133
	v_fmamk_f32 v133, v130, 0xbc800000, v9
	v_fmamk_f32 v135, v130, 0xbc800000, v7
	v_add_f32_e32 v131, v131, v132
	v_fmamk_f32 v132, v130, 0xbc800000, v8
	v_fmamk_f32 v134, v130, 0xbc800000, v6
	v_mul_f32_e32 v135, v135, v135
	v_mul_f32_e32 v133, v133, v133
	v_fmac_f32_e32 v135, v134, v134
	v_fmac_f32_e32 v133, v132, v132
	v_add_f32_e32 v132, v135, v133
	v_fmamk_f32 v133, v130, 0xbc800000, v5
	v_fmamk_f32 v135, v130, 0xbc800000, v3
	v_add_f32_e32 v131, v132, v131
	v_fmamk_f32 v132, v130, 0xbc800000, v4
	v_fmamk_f32 v134, v130, 0xbc800000, v2
	v_mul_f32_e32 v135, v135, v135
	v_mul_f32_e32 v133, v133, v133
	v_fmac_f32_e32 v135, v134, v134
	v_fmac_f32_e32 v133, v132, v132
	v_add_f32_e32 v132, v135, v133
	v_add_f32_e32 v131, v132, v131
	v_mov_b32_e32 v132, v131
	s_nop 1
	v_permlane16_swap_b32_e32 v131, v132
	s_waitcnt lgkmcnt(0)
	v_add_f32_e32 v131, v131, v132
	v_mov_b32_e32 v132, v131
	s_nop 1
	v_permlane32_swap_b32_e32 v131, v132
	s_and_saveexec_b64 s[0:1], s[4:5]
	s_cbranch_execz .LBB0_626
	s_lshl_b32 s4, s26, 11
	s_add_i32 s27, s27, s4
	v_mul_f32_e32 v130, 0x3c800000, v130
	s_waitcnt lgkmcnt(0)
	v_add_f32_e32 v131, v131, v132
	v_lshl_add_u32 v132, v170, 5, s27
	ds_write_b64 v132, v[130:131] offset:5632

.LBB0_856:
	v_mov_b32_e32 v130, v127
	v_mov_b32_e32 v131, v128
	v_mov_b32_e32 v132, v126
	v_mov_b32_e32 v133, v129
	v_pk_add_f32 v[130:131], v[130:131], v[132:133]
	v_mov_b32_e32 v132, v123
	v_mov_b32_e32 v133, v124
	v_mov_b32_e32 v134, v122
	v_mov_b32_e32 v135, v125
	v_pk_add_f32 v[132:133], v[132:133], v[134:135]
	v_add_f32_e32 v130, v130, v131
	v_pk_add_f32 v[132:133], v[132:133], v[132:133] op_sel_hi:[0,1]
	v_add_f32_e32 v131, 0, v130
	v_add_f32_e32 v135, v118, v119
	v_add_f32_e32 v137, v120, v121
	v_mov_b32_e32 v134, v114
	v_mov_b32_e32 v136, v115
	v_mov_b32_e32 v132, v116
	v_mov_b32_e32 v130, v117
	v_pk_add_f32 v[134:135], v[134:135], v[136:137]
	v_pk_add_f32 v[130:131], v[132:133], v[130:131]
	v_mov_b32_e32 v133, v126
	v_pk_add_f32 v[130:131], v[134:135], v[130:131]
	v_mov_b32_e32 v134, v127
	v_add_f32_e32 v130, v130, v131
	v_mov_b32_e32 v131, v130
	s_nop 1
	v_permlane16_swap_b32_e32 v130, v131
	v_mov_b32_e32 v135, v123
	s_lshl_b32 s0, s30, 3
	s_add_i32 s28, s0, 0
	s_barrier
	s_waitcnt lgkmcnt(0)
	v_add_f32_e32 v130, v130, v131
	v_mov_b32_e32 v131, v130
	s_nop 1
	v_permlane32_swap_b32_e32 v130, v131
	s_waitcnt lgkmcnt(0)
	v_add_f32_e32 v131, v130, v131
	v_fmamk_f32 v132, v131, 0xbc800000, v129
	v_fmac_f32_e32 v134, 0xbc800000, v131
	v_fmamk_f32 v130, v131, 0xbc800000, v128
	v_fmac_f32_e32 v133, 0xbc800000, v131
	v_mul_f32_e32 v134, v134, v134
	v_mul_f32_e32 v132, v132, v132
	v_fmac_f32_e32 v134, v133, v133
	v_fmac_f32_e32 v132, v130, v130
	v_add_f32_e32 v130, v134, v132
	v_fmamk_f32 v133, v131, 0xbc800000, v125
	v_mov_b32_e32 v134, v122
	v_fmac_f32_e32 v135, 0xbc800000, v131
	v_fmamk_f32 v132, v131, 0xbc800000, v124
	v_fmac_f32_e32 v134, 0xbc800000, v131
	v_mul_f32_e32 v135, v135, v135
	v_mul_f32_e32 v133, v133, v133
	v_fmac_f32_e32 v135, v134, v134
	v_fmac_f32_e32 v133, v132, v132
	v_add_f32_e32 v132, v135, v133
	v_mov_b32_e32 v135, v119
	v_fmamk_f32 v133, v131, 0xbc800000, v121
	v_mov_b32_e32 v134, v118
	v_fmac_f32_e32 v135, 0xbc800000, v131
	v_add_f32_e32 v130, v130, v132
	v_fmamk_f32 v132, v131, 0xbc800000, v120
	v_fmac_f32_e32 v134, 0xbc800000, v131
	v_mul_f32_e32 v135, v135, v135
	v_mul_f32_e32 v133, v133, v133
	v_fmac_f32_e32 v135, v134, v134
	v_fmac_f32_e32 v133, v132, v132
	v_add_f32_e32 v132, v135, v133
	v_mov_b32_e32 v135, v115
	v_fmamk_f32 v133, v131, 0xbc800000, v117
	v_mov_b32_e32 v134, v114
	v_fmac_f32_e32 v135, 0xbc800000, v131
	v_add_f32_e32 v130, v132, v130
	v_fmamk_f32 v132, v131, 0xbc800000, v116
	v_fmac_f32_e32 v134, 0xbc800000, v131
	v_mul_f32_e32 v135, v135, v135
	v_mul_f32_e32 v133, v133, v133
	v_fmac_f32_e32 v135, v134, v134
	v_fmac_f32_e32 v133, v132, v132
	v_add_f32_e32 v132, v135, v133
	v_add_f32_e32 v132, v132, v130
	v_mov_b32_e32 v133, v132
	s_nop 1
	v_permlane16_swap_b32_e32 v132, v133
	v_and_b32_e32 v130, 63, v148
	v_cmp_gt_u32_e64 s[6:7], 16, v130
	s_waitcnt lgkmcnt(0)
	v_add_f32_e32 v132, v132, v133
	v_mov_b32_e32 v133, v132
	s_nop 1
	v_permlane32_swap_b32_e32 v132, v133
	s_and_saveexec_b64 s[0:1], s[6:7]
	s_cbranch_execz .LBB0_858
	s_lshl_b32 s8, s27, 11
	s_add_i32 s8, s28, s8
	v_mul_f32_e32 v134, 0x3c800000, v131
	s_waitcnt lgkmcnt(0)
	v_add_f32_e32 v135, v132, v133
	v_lshl_add_u32 v131, v170, 5, s8
	ds_write_b64 v131, v[134:135]
.LBB0_858:
	s_or_b64 exec, exec, s[0:1]
	v_mov_b32_e32 v132, v111
	s_waitcnt lgkmcnt(0)
	v_mov_b32_e32 v133, v112
	v_mov_b32_e32 v134, v110
	v_mov_b32_e32 v135, v113
	v_pk_add_f32 v[132:133], v[132:133], v[134:135]
	v_mov_b32_e32 v134, v107
	v_mov_b32_e32 v135, v108
	v_mov_b32_e32 v136, v106
	v_mov_b32_e32 v137, v109
	v_pk_add_f32 v[134:135], v[134:135], v[136:137]
	v_add_f32_e32 v131, v132, v133
	v_pk_add_f32 v[134:135], v[134:135], v[134:135] op_sel_hi:[0,1]
	v_add_f32_e32 v133, 0, v131
	v_add_f32_e32 v137, v102, v103
	v_add_f32_e32 v139, v104, v105
	v_mov_b32_e32 v136, v98
	v_mov_b32_e32 v138, v99
	v_mov_b32_e32 v134, v100
	v_mov_b32_e32 v132, v101
	v_pk_add_f32 v[136:137], v[136:137], v[138:139]
	v_pk_add_f32 v[132:133], v[134:135], v[132:133]
	v_mov_b32_e32 v135, v111
	v_pk_add_f32 v[132:133], v[136:137], v[132:133]
	v_mov_b32_e32 v134, v110
	v_add_f32_e32 v131, v132, v133
	v_mov_b32_e32 v132, v131
	s_nop 1
	v_permlane16_swap_b32_e32 v131, v132
	v_mov_b32_e32 v136, v107
	s_waitcnt lgkmcnt(0)
	v_add_f32_e32 v131, v131, v132
	v_mov_b32_e32 v132, v131
	s_nop 1
	v_permlane32_swap_b32_e32 v131, v132
	s_waitcnt lgkmcnt(0)
	v_add_f32_e32 v131, v131, v132
	v_fmamk_f32 v133, v131, 0xbc800000, v113
	v_fmac_f32_e32 v135, 0xbc800000, v131
	v_fmamk_f32 v132, v131, 0xbc800000, v112
	v_fmac_f32_e32 v134, 0xbc800000, v131
	v_mul_f32_e32 v135, v135, v135
	v_mul_f32_e32 v133, v133, v133
	v_fmac_f32_e32 v135, v134, v134
	v_fmac_f32_e32 v133, v132, v132
	v_add_f32_e32 v132, v135, v133
	v_fmamk_f32 v134, v131, 0xbc800000, v109
	v_mov_b32_e32 v135, v106
	v_fmac_f32_e32 v136, 0xbc800000, v131
	v_fmamk_f32 v133, v131, 0xbc800000, v108
	v_fmac_f32_e32 v135, 0xbc800000, v131
	v_mul_f32_e32 v136, v136, v136
	v_mul_f32_e32 v134, v134, v134
	v_fmac_f32_e32 v136, v135, v135
	v_fmac_f32_e32 v134, v133, v133
	v_add_f32_e32 v133, v136, v134
	v_mov_b32_e32 v136, v103
	v_fmamk_f32 v134, v131, 0xbc800000, v105
	v_mov_b32_e32 v135, v102
	v_fmac_f32_e32 v136, 0xbc800000, v131
	v_add_f32_e32 v132, v132, v133
	v_fmamk_f32 v133, v131, 0xbc800000, v104
	v_fmac_f32_e32 v135, 0xbc800000, v131
	v_mul_f32_e32 v136, v136, v136
	v_mul_f32_e32 v134, v134, v134
	v_fmac_f32_e32 v136, v135, v135
	v_fmac_f32_e32 v134, v133, v133
	v_add_f32_e32 v133, v136, v134
	v_mov_b32_e32 v136, v99
	v_fmamk_f32 v134, v131, 0xbc800000, v101
	v_mov_b32_e32 v135, v98
	v_fmac_f32_e32 v136, 0xbc800000, v131
	v_add_f32_e32 v132, v133, v132
	v_fmamk_f32 v133, v131, 0xbc800000, v100
	v_fmac_f32_e32 v135, 0xbc800000, v131
	v_mul_f32_e32 v136, v136, v136
	v_mul_f32_e32 v134, v134, v134
	v_fmac_f32_e32 v136, v135, v135
	v_fmac_f32_e32 v134, v133, v133
	v_add_f32_e32 v133, v136, v134
	v_add_f32_e32 v132, v133, v132
	v_mov_b32_e32 v133, v132
	s_nop 1
	v_permlane16_swap_b32_e32 v132, v133
	s_waitcnt lgkmcnt(0)
	v_add_f32_e32 v132, v132, v133
	v_mov_b32_e32 v133, v132
	s_nop 1
	v_permlane32_swap_b32_e32 v132, v133
	s_and_saveexec_b64 s[0:1], s[6:7]
	s_cbranch_execz .LBB0_860
	s_lshl_b32 s8, s27, 11
	s_add_i32 s8, s28, s8
	v_mul_f32_e32 v134, 0x3c800000, v131
	s_waitcnt lgkmcnt(0)
	v_add_f32_e32 v135, v132, v133
	v_lshl_add_u32 v131, v170, 5, s8
	ds_write_b64 v131, v[134:135] offset:512
.LBB0_860:
	s_or_b64 exec, exec, s[0:1]
	v_mov_b32_e32 v132, v95
	s_waitcnt lgkmcnt(0)
	v_mov_b32_e32 v133, v96
	v_mov_b32_e32 v134, v94
	v_mov_b32_e32 v135, v97
	v_pk_add_f32 v[132:133], v[132:133], v[134:135]
	v_mov_b32_e32 v134, v91
	v_mov_b32_e32 v135, v92
	v_mov_b32_e32 v136, v90
	v_mov_b32_e32 v137, v93
	v_pk_add_f32 v[134:135], v[134:135], v[136:137]
	v_add_f32_e32 v131, v132, v133
	v_pk_add_f32 v[134:135], v[134:135], v[134:135] op_sel_hi:[0,1]
	v_add_f32_e32 v133, 0, v131
	v_add_f32_e32 v137, v86, v87
	v_add_f32_e32 v139, v88, v89
	v_mov_b32_e32 v136, v82
	v_mov_b32_e32 v138, v83
	v_mov_b32_e32 v134, v84
	v_mov_b32_e32 v132, v85
	v_pk_add_f32 v[136:137], v[136:137], v[138:139]
	v_pk_add_f32 v[132:133], v[134:135], v[132:133]
	v_mov_b32_e32 v135, v95
	v_pk_add_f32 v[132:133], v[136:137], v[132:133]
	v_mov_b32_e32 v134, v94
	v_add_f32_e32 v131, v132, v133
	v_mov_b32_e32 v132, v131
	s_nop 1
	v_permlane16_swap_b32_e32 v131, v132
	v_mov_b32_e32 v136, v91
	s_waitcnt lgkmcnt(0)
	v_add_f32_e32 v131, v131, v132
	v_mov_b32_e32 v132, v131
	s_nop 1
	v_permlane32_swap_b32_e32 v131, v132
	s_waitcnt lgkmcnt(0)
	v_add_f32_e32 v131, v131, v132
	v_fmamk_f32 v133, v131, 0xbc800000, v97
	v_fmac_f32_e32 v135, 0xbc800000, v131
	v_fmamk_f32 v132, v131, 0xbc800000, v96
	v_fmac_f32_e32 v134, 0xbc800000, v131
	v_mul_f32_e32 v135, v135, v135
	v_mul_f32_e32 v133, v133, v133
	v_fmac_f32_e32 v135, v134, v134
	v_fmac_f32_e32 v133, v132, v132
	v_add_f32_e32 v132, v135, v133
	v_fmamk_f32 v134, v131, 0xbc800000, v93
	v_mov_b32_e32 v135, v90
	v_fmac_f32_e32 v136, 0xbc800000, v131
	v_fmamk_f32 v133, v131, 0xbc800000, v92
	v_fmac_f32_e32 v135, 0xbc800000, v131
	v_mul_f32_e32 v136, v136, v136
	v_mul_f32_e32 v134, v134, v134
	v_fmac_f32_e32 v136, v135, v135
	v_fmac_f32_e32 v134, v133, v133
	v_add_f32_e32 v133, v136, v134
	v_mov_b32_e32 v136, v87
	v_fmamk_f32 v134, v131, 0xbc800000, v89
	v_mov_b32_e32 v135, v86
	v_fmac_f32_e32 v136, 0xbc800000, v131
	v_add_f32_e32 v132, v132, v133
	v_fmamk_f32 v133, v131, 0xbc800000, v88
	v_fmac_f32_e32 v135, 0xbc800000, v131
	v_mul_f32_e32 v136, v136, v136
	v_mul_f32_e32 v134, v134, v134
	v_fmac_f32_e32 v136, v135, v135
	v_fmac_f32_e32 v134, v133, v133
	v_add_f32_e32 v133, v136, v134
	v_mov_b32_e32 v136, v83
	v_fmamk_f32 v134, v131, 0xbc800000, v85
	v_mov_b32_e32 v135, v82
	v_fmac_f32_e32 v136, 0xbc800000, v131
	v_add_f32_e32 v132, v133, v132
	v_fmamk_f32 v133, v131, 0xbc800000, v84
	v_fmac_f32_e32 v135, 0xbc800000, v131
	v_mul_f32_e32 v136, v136, v136
	v_mul_f32_e32 v134, v134, v134
	v_fmac_f32_e32 v136, v135, v135
	v_fmac_f32_e32 v134, v133, v133
	v_add_f32_e32 v133, v136, v134
	v_add_f32_e32 v132, v133, v132
	v_mov_b32_e32 v133, v132
	s_nop 1
	v_permlane16_swap_b32_e32 v132, v133
	s_waitcnt lgkmcnt(0)
	v_add_f32_e32 v132, v132, v133
	v_mov_b32_e32 v133, v132
	s_nop 1
	v_permlane32_swap_b32_e32 v132, v133
	s_and_saveexec_b64 s[0:1], s[6:7]
	s_cbranch_execz .LBB0_862
	s_lshl_b32 s8, s27, 11
	s_add_i32 s8, s28, s8
	v_mul_f32_e32 v134, 0x3c800000, v131
	s_waitcnt lgkmcnt(0)
	v_add_f32_e32 v135, v132, v133
	v_lshl_add_u32 v131, v170, 5, s8
	ds_write_b64 v131, v[134:135] offset:1024
.LBB0_862:
	s_or_b64 exec, exec, s[0:1]
	v_mov_b32_e32 v132, v79
	s_waitcnt lgkmcnt(0)
	v_mov_b32_e32 v133, v80
	v_mov_b32_e32 v134, v78
	v_mov_b32_e32 v135, v81
	v_pk_add_f32 v[132:133], v[132:133], v[134:135]
	v_mov_b32_e32 v134, v75
	v_mov_b32_e32 v135, v76
	v_mov_b32_e32 v136, v74
	v_mov_b32_e32 v137, v77
	v_pk_add_f32 v[134:135], v[134:135], v[136:137]
	v_add_f32_e32 v131, v132, v133
	v_pk_add_f32 v[134:135], v[134:135], v[134:135] op_sel_hi:[0,1]
	v_add_f32_e32 v133, 0, v131
	v_add_f32_e32 v137, v70, v71
	v_add_f32_e32 v139, v72, v73
	v_mov_b32_e32 v136, v66
	v_mov_b32_e32 v138, v67
	v_mov_b32_e32 v134, v68
	v_mov_b32_e32 v132, v69
	v_pk_add_f32 v[136:137], v[136:137], v[138:139]
	v_pk_add_f32 v[132:133], v[134:135], v[132:133]
	v_mov_b32_e32 v135, v79
	v_pk_add_f32 v[132:133], v[136:137], v[132:133]
	v_mov_b32_e32 v134, v78
	v_add_f32_e32 v131, v132, v133
	v_mov_b32_e32 v132, v131
	s_nop 1
	v_permlane16_swap_b32_e32 v131, v132
	v_mov_b32_e32 v136, v75
	s_waitcnt lgkmcnt(0)
	v_add_f32_e32 v131, v131, v132
	v_mov_b32_e32 v132, v131
	s_nop 1
	v_permlane32_swap_b32_e32 v131, v132
	s_waitcnt lgkmcnt(0)
	v_add_f32_e32 v131, v131, v132
	v_fmamk_f32 v133, v131, 0xbc800000, v81
	v_fmac_f32_e32 v135, 0xbc800000, v131
	v_fmamk_f32 v132, v131, 0xbc800000, v80
	v_fmac_f32_e32 v134, 0xbc800000, v131
	v_mul_f32_e32 v135, v135, v135
	v_mul_f32_e32 v133, v133, v133
	v_fmac_f32_e32 v135, v134, v134
	v_fmac_f32_e32 v133, v132, v132
	v_add_f32_e32 v132, v135, v133
	v_fmamk_f32 v134, v131, 0xbc800000, v77
	v_mov_b32_e32 v135, v74
	v_fmac_f32_e32 v136, 0xbc800000, v131
	v_fmamk_f32 v133, v131, 0xbc800000, v76
	v_fmac_f32_e32 v135, 0xbc800000, v131
	v_mul_f32_e32 v136, v136, v136
	v_mul_f32_e32 v134, v134, v134
	v_fmac_f32_e32 v136, v135, v135
	v_fmac_f32_e32 v134, v133, v133
	v_add_f32_e32 v133, v136, v134
	v_mov_b32_e32 v136, v71
	v_fmamk_f32 v134, v131, 0xbc800000, v73
	v_mov_b32_e32 v135, v70
	v_fmac_f32_e32 v136, 0xbc800000, v131
	v_add_f32_e32 v132, v132, v133
	v_fmamk_f32 v133, v131, 0xbc800000, v72
	v_fmac_f32_e32 v135, 0xbc800000, v131
	v_mul_f32_e32 v136, v136, v136
	v_mul_f32_e32 v134, v134, v134
	v_fmac_f32_e32 v136, v135, v135
	v_fmac_f32_e32 v134, v133, v133
	v_add_f32_e32 v133, v136, v134
	v_mov_b32_e32 v136, v67
	v_fmamk_f32 v134, v131, 0xbc800000, v69
	v_mov_b32_e32 v135, v66
	v_fmac_f32_e32 v136, 0xbc800000, v131
	v_add_f32_e32 v132, v133, v132
	v_fmamk_f32 v133, v131, 0xbc800000, v68
	v_fmac_f32_e32 v135, 0xbc800000, v131
	v_mul_f32_e32 v136, v136, v136
	v_mul_f32_e32 v134, v134, v134
	v_fmac_f32_e32 v136, v135, v135
	v_fmac_f32_e32 v134, v133, v133
	v_add_f32_e32 v133, v136, v134
	v_add_f32_e32 v132, v133, v132
	v_mov_b32_e32 v133, v132
	s_nop 1
	v_permlane16_swap_b32_e32 v132, v133
	s_waitcnt lgkmcnt(0)
	v_add_f32_e32 v132, v132, v133
	v_mov_b32_e32 v133, v132
	s_nop 1
	v_permlane32_swap_b32_e32 v132, v133
	s_and_saveexec_b64 s[0:1], s[6:7]
	s_cbranch_execz .LBB0_864
	s_lshl_b32 s8, s27, 11
	s_add_i32 s8, s28, s8
	v_mul_f32_e32 v134, 0x3c800000, v131
	s_waitcnt lgkmcnt(0)
	v_add_f32_e32 v135, v132, v133
	v_lshl_add_u32 v131, v170, 5, s8
	ds_write_b64 v131, v[134:135] offset:1536
.LBB0_864:
	s_or_b64 exec, exec, s[0:1]
	v_mov_b32_e32 v132, v63
	s_waitcnt lgkmcnt(0)
	v_mov_b32_e32 v133, v64
	v_mov_b32_e32 v134, v62
	v_mov_b32_e32 v135, v65
	v_pk_add_f32 v[132:133], v[132:133], v[134:135]
	v_mov_b32_e32 v134, v59
	v_mov_b32_e32 v135, v60
	v_mov_b32_e32 v136, v58
	v_mov_b32_e32 v137, v61
	v_pk_add_f32 v[134:135], v[134:135], v[136:137]
	v_add_f32_e32 v131, v132, v133
	v_pk_add_f32 v[134:135], v[134:135], v[134:135] op_sel_hi:[0,1]
	v_add_f32_e32 v133, 0, v131
	v_add_f32_e32 v137, v54, v55
	v_add_f32_e32 v139, v56, v57
	v_mov_b32_e32 v136, v50
	v_mov_b32_e32 v138, v51
	v_mov_b32_e32 v134, v52
	v_mov_b32_e32 v132, v53
	v_pk_add_f32 v[136:137], v[136:137], v[138:139]
	v_pk_add_f32 v[132:133], v[134:135], v[132:133]
	v_mov_b32_e32 v135, v63
	v_pk_add_f32 v[132:133], v[136:137], v[132:133]
	v_mov_b32_e32 v134, v62
	v_add_f32_e32 v131, v132, v133
	v_mov_b32_e32 v132, v131
	s_nop 1
	v_permlane16_swap_b32_e32 v131, v132
	v_mov_b32_e32 v136, v59
	s_waitcnt lgkmcnt(0)
	v_add_f32_e32 v131, v131, v132
	v_mov_b32_e32 v132, v131
	s_nop 1
	v_permlane32_swap_b32_e32 v131, v132
	s_waitcnt lgkmcnt(0)
	v_add_f32_e32 v131, v131, v132
	v_fmamk_f32 v133, v131, 0xbc800000, v65
	v_fmac_f32_e32 v135, 0xbc800000, v131
	v_fmamk_f32 v132, v131, 0xbc800000, v64
	v_fmac_f32_e32 v134, 0xbc800000, v131
	v_mul_f32_e32 v135, v135, v135
	v_mul_f32_e32 v133, v133, v133
	v_fmac_f32_e32 v135, v134, v134
	v_fmac_f32_e32 v133, v132, v132
	v_add_f32_e32 v132, v135, v133
	v_fmamk_f32 v134, v131, 0xbc800000, v61
	v_mov_b32_e32 v135, v58
	v_fmac_f32_e32 v136, 0xbc800000, v131
	v_fmamk_f32 v133, v131, 0xbc800000, v60
	v_fmac_f32_e32 v135, 0xbc800000, v131
	v_mul_f32_e32 v136, v136, v136
	v_mul_f32_e32 v134, v134, v134
	v_fmac_f32_e32 v136, v135, v135
	v_fmac_f32_e32 v134, v133, v133
	v_add_f32_e32 v133, v136, v134
	v_mov_b32_e32 v136, v55
	v_fmamk_f32 v134, v131, 0xbc800000, v57
	v_mov_b32_e32 v135, v54
	v_fmac_f32_e32 v136, 0xbc800000, v131
	v_add_f32_e32 v132, v132, v133
	v_fmamk_f32 v133, v131, 0xbc800000, v56
	v_fmac_f32_e32 v135, 0xbc800000, v131
	v_mul_f32_e32 v136, v136, v136
	v_mul_f32_e32 v134, v134, v134
	v_fmac_f32_e32 v136, v135, v135
	v_fmac_f32_e32 v134, v133, v133
	v_add_f32_e32 v133, v136, v134
	v_mov_b32_e32 v136, v51
	v_fmamk_f32 v134, v131, 0xbc800000, v53
	v_mov_b32_e32 v135, v50
	v_fmac_f32_e32 v136, 0xbc800000, v131
	v_add_f32_e32 v132, v133, v132
	v_fmamk_f32 v133, v131, 0xbc800000, v52
	v_fmac_f32_e32 v135, 0xbc800000, v131
	v_mul_f32_e32 v136, v136, v136
	v_mul_f32_e32 v134, v134, v134
	v_fmac_f32_e32 v136, v135, v135
	v_fmac_f32_e32 v134, v133, v133
	v_add_f32_e32 v133, v136, v134
	v_add_f32_e32 v132, v133, v132
	v_mov_b32_e32 v133, v132
	s_nop 1
	v_permlane16_swap_b32_e32 v132, v133
	s_waitcnt lgkmcnt(0)
	v_add_f32_e32 v132, v132, v133
	v_mov_b32_e32 v133, v132
	s_nop 1
	v_permlane32_swap_b32_e32 v132, v133
	s_and_saveexec_b64 s[0:1], s[6:7]
	s_cbranch_execz .LBB0_866
	s_lshl_b32 s8, s27, 11
	s_add_i32 s8, s28, s8
	v_mul_f32_e32 v134, 0x3c800000, v131
	s_waitcnt lgkmcnt(0)
	v_add_f32_e32 v135, v132, v133
	v_lshl_add_u32 v131, v170, 5, s8
	ds_write_b64 v131, v[134:135] offset:4096
.LBB0_866:
	s_or_b64 exec, exec, s[0:1]
	v_mov_b32_e32 v132, v47
	s_waitcnt lgkmcnt(0)
	v_mov_b32_e32 v133, v48
	v_mov_b32_e32 v134, v46
	v_mov_b32_e32 v135, v49
	v_pk_add_f32 v[132:133], v[132:133], v[134:135]
	v_mov_b32_e32 v134, v43
	v_mov_b32_e32 v135, v44
	v_mov_b32_e32 v136, v42
	v_mov_b32_e32 v137, v45
	v_pk_add_f32 v[134:135], v[134:135], v[136:137]
	v_add_f32_e32 v131, v132, v133
	v_pk_add_f32 v[134:135], v[134:135], v[134:135] op_sel_hi:[0,1]
	v_add_f32_e32 v133, 0, v131
	v_add_f32_e32 v137, v38, v39
	v_add_f32_e32 v139, v40, v41
	v_mov_b32_e32 v136, v34
	v_mov_b32_e32 v138, v35
	v_mov_b32_e32 v134, v36
	v_mov_b32_e32 v132, v37
	v_pk_add_f32 v[136:137], v[136:137], v[138:139]
	v_pk_add_f32 v[132:133], v[134:135], v[132:133]
	v_mov_b32_e32 v135, v47
	v_pk_add_f32 v[132:133], v[136:137], v[132:133]
	v_mov_b32_e32 v134, v46
	v_add_f32_e32 v131, v132, v133
	v_mov_b32_e32 v132, v131
	s_nop 1
	v_permlane16_swap_b32_e32 v131, v132
	v_mov_b32_e32 v136, v43
	s_waitcnt lgkmcnt(0)
	v_add_f32_e32 v131, v131, v132
	v_mov_b32_e32 v132, v131
	s_nop 1
	v_permlane32_swap_b32_e32 v131, v132
	s_waitcnt lgkmcnt(0)
	v_add_f32_e32 v131, v131, v132
	v_fmamk_f32 v133, v131, 0xbc800000, v49
	v_fmac_f32_e32 v135, 0xbc800000, v131
	v_fmamk_f32 v132, v131, 0xbc800000, v48
	v_fmac_f32_e32 v134, 0xbc800000, v131
	v_mul_f32_e32 v135, v135, v135
	v_mul_f32_e32 v133, v133, v133
	v_fmac_f32_e32 v135, v134, v134
	v_fmac_f32_e32 v133, v132, v132
	v_add_f32_e32 v132, v135, v133
	v_fmamk_f32 v134, v131, 0xbc800000, v45
	v_mov_b32_e32 v135, v42
	v_fmac_f32_e32 v136, 0xbc800000, v131
	v_fmamk_f32 v133, v131, 0xbc800000, v44
	v_fmac_f32_e32 v135, 0xbc800000, v131
	v_mul_f32_e32 v136, v136, v136
	v_mul_f32_e32 v134, v134, v134
	v_fmac_f32_e32 v136, v135, v135
	v_fmac_f32_e32 v134, v133, v133
	v_add_f32_e32 v133, v136, v134
	v_mov_b32_e32 v136, v39
	v_fmamk_f32 v134, v131, 0xbc800000, v41
	v_mov_b32_e32 v135, v38
	v_fmac_f32_e32 v136, 0xbc800000, v131
	v_add_f32_e32 v132, v132, v133
	v_fmamk_f32 v133, v131, 0xbc800000, v40
	v_fmac_f32_e32 v135, 0xbc800000, v131
	v_mul_f32_e32 v136, v136, v136
	v_mul_f32_e32 v134, v134, v134
	v_fmac_f32_e32 v136, v135, v135
	v_fmac_f32_e32 v134, v133, v133
	v_add_f32_e32 v133, v136, v134
	v_mov_b32_e32 v136, v35
	v_fmamk_f32 v134, v131, 0xbc800000, v37
	v_mov_b32_e32 v135, v34
	v_fmac_f32_e32 v136, 0xbc800000, v131
	v_add_f32_e32 v132, v133, v132
	v_fmamk_f32 v133, v131, 0xbc800000, v36
	v_fmac_f32_e32 v135, 0xbc800000, v131
	v_mul_f32_e32 v136, v136, v136
	v_mul_f32_e32 v134, v134, v134
	v_fmac_f32_e32 v136, v135, v135
	v_fmac_f32_e32 v134, v133, v133
	v_add_f32_e32 v133, v136, v134
	v_add_f32_e32 v132, v133, v132
	v_mov_b32_e32 v133, v132
	s_nop 1
	v_permlane16_swap_b32_e32 v132, v133
	s_waitcnt lgkmcnt(0)
	v_add_f32_e32 v132, v132, v133
	v_mov_b32_e32 v133, v132
	s_nop 1
	v_permlane32_swap_b32_e32 v132, v133
	s_and_saveexec_b64 s[0:1], s[6:7]
	s_cbranch_execz .LBB0_868
	s_lshl_b32 s8, s27, 11
	s_add_i32 s8, s28, s8
	v_mul_f32_e32 v134, 0x3c800000, v131
	s_waitcnt lgkmcnt(0)
	v_add_f32_e32 v135, v132, v133
	v_lshl_add_u32 v131, v170, 5, s8
	ds_write_b64 v131, v[134:135] offset:4608
.LBB0_868:
	s_or_b64 exec, exec, s[0:1]
	v_mov_b32_e32 v132, v31
	s_waitcnt lgkmcnt(0)
	v_mov_b32_e32 v133, v32
	v_mov_b32_e32 v134, v30
	v_mov_b32_e32 v135, v33
	v_pk_add_f32 v[132:133], v[132:133], v[134:135]
	v_mov_b32_e32 v134, v27
	v_mov_b32_e32 v135, v28
	v_mov_b32_e32 v136, v26
	v_mov_b32_e32 v137, v29
	v_pk_add_f32 v[134:135], v[134:135], v[136:137]
	v_add_f32_e32 v131, v132, v133
	v_pk_add_f32 v[134:135], v[134:135], v[134:135] op_sel_hi:[0,1]
	v_add_f32_e32 v133, 0, v131
	v_add_f32_e32 v137, v22, v23
	v_add_f32_e32 v139, v24, v25
	v_mov_b32_e32 v136, v18
	v_mov_b32_e32 v138, v19
	v_mov_b32_e32 v134, v20
	v_mov_b32_e32 v132, v21
	v_pk_add_f32 v[136:137], v[136:137], v[138:139]
	v_pk_add_f32 v[132:133], v[134:135], v[132:133]
	v_mov_b32_e32 v135, v31
	v_pk_add_f32 v[132:133], v[136:137], v[132:133]
	v_mov_b32_e32 v134, v30
	v_add_f32_e32 v131, v132, v133
	v_mov_b32_e32 v132, v131
	s_nop 1
	v_permlane16_swap_b32_e32 v131, v132
	v_mov_b32_e32 v136, v27
	s_waitcnt lgkmcnt(0)
	v_add_f32_e32 v131, v131, v132
	v_mov_b32_e32 v132, v131
	s_nop 1
	v_permlane32_swap_b32_e32 v131, v132
	s_waitcnt lgkmcnt(0)
	v_add_f32_e32 v131, v131, v132
	v_fmamk_f32 v133, v131, 0xbc800000, v33
	v_fmac_f32_e32 v135, 0xbc800000, v131
	v_fmamk_f32 v132, v131, 0xbc800000, v32
	v_fmac_f32_e32 v134, 0xbc800000, v131
	v_mul_f32_e32 v135, v135, v135
	v_mul_f32_e32 v133, v133, v133
	v_fmac_f32_e32 v135, v134, v134
	v_fmac_f32_e32 v133, v132, v132
	v_add_f32_e32 v132, v135, v133
	v_fmamk_f32 v134, v131, 0xbc800000, v29
	v_mov_b32_e32 v135, v26
	v_fmac_f32_e32 v136, 0xbc800000, v131
	v_fmamk_f32 v133, v131, 0xbc800000, v28
	v_fmac_f32_e32 v135, 0xbc800000, v131
	v_mul_f32_e32 v136, v136, v136
	v_mul_f32_e32 v134, v134, v134
	v_fmac_f32_e32 v136, v135, v135
	v_fmac_f32_e32 v134, v133, v133
	v_add_f32_e32 v133, v136, v134
	v_mov_b32_e32 v136, v23
	v_fmamk_f32 v134, v131, 0xbc800000, v25
	v_mov_b32_e32 v135, v22
	v_fmac_f32_e32 v136, 0xbc800000, v131
	v_add_f32_e32 v132, v132, v133
	v_fmamk_f32 v133, v131, 0xbc800000, v24
	v_fmac_f32_e32 v135, 0xbc800000, v131
	v_mul_f32_e32 v136, v136, v136
	v_mul_f32_e32 v134, v134, v134
	v_fmac_f32_e32 v136, v135, v135
	v_fmac_f32_e32 v134, v133, v133
	v_add_f32_e32 v133, v136, v134
	v_mov_b32_e32 v136, v19
	v_fmamk_f32 v134, v131, 0xbc800000, v21
	v_mov_b32_e32 v135, v18
	v_fmac_f32_e32 v136, 0xbc800000, v131
	v_add_f32_e32 v132, v133, v132
	v_fmamk_f32 v133, v131, 0xbc800000, v20
	v_fmac_f32_e32 v135, 0xbc800000, v131
	v_mul_f32_e32 v136, v136, v136
	v_mul_f32_e32 v134, v134, v134
	v_fmac_f32_e32 v136, v135, v135
	v_fmac_f32_e32 v134, v133, v133
	v_add_f32_e32 v133, v136, v134
	v_add_f32_e32 v132, v133, v132
	v_mov_b32_e32 v133, v132
	s_nop 1
	v_permlane16_swap_b32_e32 v132, v133
	s_waitcnt lgkmcnt(0)
	v_add_f32_e32 v132, v132, v133
	v_mov_b32_e32 v133, v132
	s_nop 1
	v_permlane32_swap_b32_e32 v132, v133
	s_and_saveexec_b64 s[0:1], s[6:7]
	s_cbranch_execz .LBB0_870
	s_lshl_b32 s8, s27, 11
	s_add_i32 s8, s28, s8
	v_mul_f32_e32 v134, 0x3c800000, v131
	s_waitcnt lgkmcnt(0)
	v_add_f32_e32 v135, v132, v133
	v_lshl_add_u32 v131, v170, 5, s8
	ds_write_b64 v131, v[134:135] offset:5120
.LBB0_870:
	s_or_b64 exec, exec, s[0:1]
	v_mov_b32_e32 v132, v15
	s_waitcnt lgkmcnt(0)
	v_mov_b32_e32 v133, v16
	v_mov_b32_e32 v134, v14
	v_mov_b32_e32 v135, v17
	v_pk_add_f32 v[132:133], v[132:133], v[134:135]
	v_mov_b32_e32 v134, v11
	v_mov_b32_e32 v135, v12
	v_mov_b32_e32 v136, v10
	v_mov_b32_e32 v137, v13
	v_pk_add_f32 v[134:135], v[134:135], v[136:137]
	v_add_f32_e32 v131, v132, v133
	v_pk_add_f32 v[134:135], v[134:135], v[134:135] op_sel_hi:[0,1]
	v_add_f32_e32 v133, 0, v131
	v_add_f32_e32 v137, v6, v7
	v_add_f32_e32 v139, v8, v9
	v_mov_b32_e32 v136, v2
	v_mov_b32_e32 v138, v3
	v_mov_b32_e32 v134, v4
	v_mov_b32_e32 v132, v5
	v_pk_add_f32 v[136:137], v[136:137], v[138:139]
	v_pk_add_f32 v[132:133], v[134:135], v[132:133]
	v_mov_b32_e32 v135, v15
	v_pk_add_f32 v[132:133], v[136:137], v[132:133]
	v_mov_b32_e32 v134, v14
	v_add_f32_e32 v131, v132, v133
	v_mov_b32_e32 v132, v131
	s_nop 1
	v_permlane16_swap_b32_e32 v131, v132
	v_mov_b32_e32 v136, v11
	s_waitcnt lgkmcnt(0)
	v_add_f32_e32 v131, v131, v132
	v_mov_b32_e32 v132, v131
	s_nop 1
	v_permlane32_swap_b32_e32 v131, v132
	s_waitcnt lgkmcnt(0)
	v_add_f32_e32 v131, v131, v132
	v_fmamk_f32 v133, v131, 0xbc800000, v17
	v_fmac_f32_e32 v135, 0xbc800000, v131
	v_fmamk_f32 v132, v131, 0xbc800000, v16
	v_fmac_f32_e32 v134, 0xbc800000, v131
	v_mul_f32_e32 v135, v135, v135
	v_mul_f32_e32 v133, v133, v133
	v_fmac_f32_e32 v135, v134, v134
	v_fmac_f32_e32 v133, v132, v132
	v_add_f32_e32 v132, v135, v133
	v_fmamk_f32 v134, v131, 0xbc800000, v13
	v_mov_b32_e32 v135, v10
	v_fmac_f32_e32 v136, 0xbc800000, v131
	v_fmamk_f32 v133, v131, 0xbc800000, v12
	v_fmac_f32_e32 v135, 0xbc800000, v131
	v_mul_f32_e32 v136, v136, v136
	v_mul_f32_e32 v134, v134, v134
	v_fmac_f32_e32 v136, v135, v135
	v_fmac_f32_e32 v134, v133, v133
	v_add_f32_e32 v133, v136, v134
	v_mov_b32_e32 v136, v7
	v_fmamk_f32 v134, v131, 0xbc800000, v9
	v_mov_b32_e32 v135, v6
	v_fmac_f32_e32 v136, 0xbc800000, v131
	v_add_f32_e32 v132, v132, v133
	v_fmamk_f32 v133, v131, 0xbc800000, v8
	v_fmac_f32_e32 v135, 0xbc800000, v131
	v_mul_f32_e32 v136, v136, v136
	v_mul_f32_e32 v134, v134, v134
	v_fmac_f32_e32 v136, v135, v135
	v_fmac_f32_e32 v134, v133, v133
	v_add_f32_e32 v133, v136, v134
	v_mov_b32_e32 v136, v3
	v_fmamk_f32 v134, v131, 0xbc800000, v5
	v_mov_b32_e32 v135, v2
	v_fmac_f32_e32 v136, 0xbc800000, v131
	v_add_f32_e32 v132, v133, v132
	v_fmamk_f32 v133, v131, 0xbc800000, v4
	v_fmac_f32_e32 v135, 0xbc800000, v131
	v_mul_f32_e32 v136, v136, v136
	v_mul_f32_e32 v134, v134, v134
	v_fmac_f32_e32 v136, v135, v135
	v_fmac_f32_e32 v134, v133, v133
	v_add_f32_e32 v133, v136, v134
	v_add_f32_e32 v132, v133, v132
	v_mov_b32_e32 v133, v132
	s_nop 1
	v_permlane16_swap_b32_e32 v132, v133
	s_waitcnt lgkmcnt(0)
	v_add_f32_e32 v132, v132, v133
	v_mov_b32_e32 v133, v132
	s_nop 1
	v_permlane32_swap_b32_e32 v132, v133
	s_and_saveexec_b64 s[0:1], s[6:7]
	s_cbranch_execz .LBB0_872
	s_lshl_b32 s8, s27, 11
	s_add_i32 s8, s28, s8
	v_mul_f32_e32 v134, 0x3c800000, v131
	s_waitcnt lgkmcnt(0)
	v_add_f32_e32 v135, v132, v133
	v_lshl_add_u32 v131, v170, 5, s8
	ds_write_b64 v131, v[134:135] offset:5632

.LBB0_896:
	s_or_b64 exec, exec, s[20:21]
	s_lshl_b32 s0, s30, 5
	s_lshl_b32 s1, s16, 8
	s_or_b32 s0, s1, s0
	v_lshrrev_b32_e32 v130, 2, v148
	v_and_or_b32 v162, v130, 12, s0
	v_add_u32_e32 v150, s17, v152
	s_lshl_b32 s0, s26, 5
	v_ashrrev_i32_e32 v151, 31, v150
	s_and_b32 s0, s0, 0xfffffc00
	v_ashrrev_i32_e32 v163, 31, v162
	v_lshlrev_b64 v[130:131], 11, v[150:151]
	v_add_u32_e32 v132, s0, v162
	v_lshl_add_u64 v[130:131], s[56:57], 0, v[130:131]
	v_lshlrev_b64 v[168:169], 1, v[162:163]
	s_waitcnt lgkmcnt(0)
	v_ashrrev_i32_e32 v133, 31, v132
	s_waitcnt lgkmcnt(0)
	s_barrier
	v_lshl_add_u64 v[130:131], v[130:131], 0, v[168:169]
	v_lshl_add_u64 v[148:149], v[132:133], 2, s[34:35]
	s_mov_b32 s17, 0x106000
	global_load_dwordx2 v[154:155], v[130:131], off
	global_load_dwordx2 v[156:157], v[130:131], off offset:32
	global_load_dwordx2 v[158:159], v[130:131], off offset:256
	global_load_dwordx2 v[160:161], v[130:131], off offset:288
	v_add_co_u32_e32 v130, vcc, s17, v148
	s_mov_b64 s[0:1], 0x106000
	s_nop 0
	v_addc_co_u32_e32 v131, vcc, 0, v149, vcc
	global_load_dwordx4 v[138:141], v[130:131], off
	v_lshl_add_u64 v[130:131], v[148:149], 0, s[0:1]
	global_load_dwordx4 v[142:145], v[130:131], off offset:64
	global_load_dwordx4 v[134:137], v[130:131], off offset:512
	s_nop 0
	global_load_dwordx4 v[130:133], v[130:131], off offset:576
	v_lshl_add_u32 v185, v152, 3, 0
	ds_read_b64 v[164:165], v185 offset:8192
	v_add_u32_e32 v152, 16, v150
	v_ashrrev_i32_e32 v153, 31, v152
	v_lshlrev_b64 v[166:167], 11, v[152:153]
	v_lshl_add_u64 v[166:167], s[56:57], 0, v[166:167]
	s_waitcnt lgkmcnt(0)
	v_pk_mul_f32 v[128:129], v[128:129], v[164:165] op_sel:[0,1]
	v_pk_mul_f32 v[126:127], v[126:127], v[164:165] op_sel:[0,1]
	v_pk_mul_f32 v[122:123], v[122:123], v[164:165] op_sel:[0,1]
	v_pk_mul_f32 v[124:125], v[124:125], v[164:165] op_sel:[0,1]
	v_pk_mul_f32 v[172:173], v[118:119], v[164:165] op_sel:[0,1]
	v_pk_mul_f32 v[174:175], v[120:121], v[164:165] op_sel:[0,1]
	v_pk_mul_f32 v[114:115], v[114:115], v[164:165] op_sel:[0,1]
	v_pk_mul_f32 v[116:117], v[116:117], v[164:165] op_sel:[0,1]
	v_lshl_add_u64 v[166:167], v[166:167], 0, v[168:169]
	s_waitcnt vmcnt(0)
	v_lshlrev_b32_e32 v118, 16, v154
	v_and_b32_e32 v119, 0xffff0000, v154
	v_lshlrev_b32_e32 v120, 16, v155
	v_and_b32_e32 v121, 0xffff0000, v155
	v_lshlrev_b32_e32 v154, 16, v156
	v_and_b32_e32 v155, 0xffff0000, v156
	v_lshlrev_b32_e32 v156, 16, v157
	v_and_b32_e32 v157, 0xffff0000, v157
	v_lshlrev_b32_e32 v164, 16, v158
	v_and_b32_e32 v165, 0xffff0000, v158
	v_lshlrev_b32_e32 v158, 16, v159
	v_and_b32_e32 v159, 0xffff0000, v159
	v_lshlrev_b32_e32 v176, 16, v160
	v_and_b32_e32 v177, 0xffff0000, v160
	v_lshlrev_b32_e32 v160, 16, v161
	v_and_b32_e32 v161, 0xffff0000, v161
	v_pk_fma_f32 v[118:119], v[138:139], v[126:127], v[118:119]
	v_pk_fma_f32 v[120:121], v[140:141], v[128:129], v[120:121]
	v_pk_fma_f32 v[124:125], v[144:145], v[124:125], v[156:157]
	v_pk_fma_f32 v[122:123], v[142:143], v[122:123], v[154:155]
	v_pk_fma_f32 v[128:129], v[136:137], v[174:175], v[158:159]
	v_pk_fma_f32 v[126:127], v[134:135], v[172:173], v[164:165]
	v_pk_fma_f32 v[116:117], v[132:133], v[116:117], v[160:161]
	v_pk_fma_f32 v[114:115], v[130:131], v[114:115], v[176:177]
	v_add_u32_e32 v154, 32, v150
	global_load_dwordx2 v[156:157], v[166:167], off
	global_load_dwordx2 v[158:159], v[166:167], off offset:32
	global_load_dwordx2 v[160:161], v[166:167], off offset:256
	global_load_dwordx2 v[164:165], v[166:167], off offset:288
	ds_read_b64 v[166:167], v185 offset:8320
	v_ashrrev_i32_e32 v155, 31, v154
	v_lshlrev_b64 v[172:173], 11, v[154:155]
	v_lshl_add_u64 v[172:173], s[56:57], 0, v[172:173]
	v_lshl_add_u64 v[172:173], v[172:173], 0, v[168:169]
	s_waitcnt lgkmcnt(0)
	v_pk_mul_f32 v[110:111], v[110:111], v[166:167] op_sel:[0,1]
	v_pk_mul_f32 v[112:113], v[112:113], v[166:167] op_sel:[0,1]
	v_pk_mul_f32 v[106:107], v[106:107], v[166:167] op_sel:[0,1]
	v_pk_mul_f32 v[108:109], v[108:109], v[166:167] op_sel:[0,1]
	v_pk_mul_f32 v[102:103], v[102:103], v[166:167] op_sel:[0,1]
	v_pk_mul_f32 v[104:105], v[104:105], v[166:167] op_sel:[0,1]
	v_pk_mul_f32 v[98:99], v[98:99], v[166:167] op_sel:[0,1]
	v_pk_mul_f32 v[100:101], v[100:101], v[166:167] op_sel:[0,1]
	v_add_f32_e32 v195, v126, v127
	v_add_f32_e32 v205, v128, v129
	v_mov_b32_e32 v194, v114
	v_mov_b32_e32 v204, v115
	v_mov_b32_e32 v206, v117
	s_waitcnt vmcnt(3)
	v_lshlrev_b32_e32 v166, 16, v156
	v_and_b32_e32 v167, 0xffff0000, v156
	v_lshlrev_b32_e32 v156, 16, v157
	v_and_b32_e32 v157, 0xffff0000, v157
	s_waitcnt vmcnt(2)
	v_lshlrev_b32_e32 v174, 16, v158
	v_and_b32_e32 v175, 0xffff0000, v158
	v_lshlrev_b32_e32 v158, 16, v159
	v_and_b32_e32 v159, 0xffff0000, v159
	s_waitcnt vmcnt(1)
	v_lshlrev_b32_e32 v176, 16, v160
	v_and_b32_e32 v177, 0xffff0000, v160
	v_lshlrev_b32_e32 v160, 16, v161
	v_and_b32_e32 v161, 0xffff0000, v161
	s_waitcnt vmcnt(0)
	v_lshlrev_b32_e32 v178, 16, v164
	v_and_b32_e32 v179, 0xffff0000, v164
	v_lshlrev_b32_e32 v164, 16, v165
	v_and_b32_e32 v165, 0xffff0000, v165
	v_pk_fma_f32 v[112:113], v[140:141], v[112:113], v[156:157]
	v_pk_fma_f32 v[110:111], v[138:139], v[110:111], v[166:167]
	v_pk_fma_f32 v[108:109], v[144:145], v[108:109], v[158:159]
	v_pk_fma_f32 v[106:107], v[142:143], v[106:107], v[174:175]
	v_pk_fma_f32 v[104:105], v[136:137], v[104:105], v[160:161]
	v_pk_fma_f32 v[102:103], v[134:135], v[102:103], v[176:177]
	v_pk_fma_f32 v[100:101], v[132:133], v[100:101], v[164:165]
	v_pk_fma_f32 v[98:99], v[130:131], v[98:99], v[178:179]
	v_add_u32_e32 v156, 48, v150
	global_load_dwordx2 v[158:159], v[172:173], off
	global_load_dwordx2 v[160:161], v[172:173], off offset:32
	global_load_dwordx2 v[164:165], v[172:173], off offset:256
	global_load_dwordx2 v[166:167], v[172:173], off offset:288
	ds_read_b64 v[172:173], v185 offset:8448
	v_ashrrev_i32_e32 v157, 31, v156
	v_lshlrev_b64 v[174:175], 11, v[156:157]
	v_lshl_add_u64 v[174:175], s[56:57], 0, v[174:175]
	v_lshl_add_u64 v[174:175], v[174:175], 0, v[168:169]
	s_waitcnt lgkmcnt(0)
	v_pk_mul_f32 v[94:95], v[94:95], v[172:173] op_sel:[0,1]
	v_pk_mul_f32 v[96:97], v[96:97], v[172:173] op_sel:[0,1]
	v_pk_mul_f32 v[90:91], v[90:91], v[172:173] op_sel:[0,1]
	v_pk_mul_f32 v[92:93], v[92:93], v[172:173] op_sel:[0,1]
	v_pk_mul_f32 v[86:87], v[86:87], v[172:173] op_sel:[0,1]
	v_pk_mul_f32 v[88:89], v[88:89], v[172:173] op_sel:[0,1]
	v_pk_mul_f32 v[82:83], v[82:83], v[172:173] op_sel:[0,1]
	v_pk_mul_f32 v[84:85], v[84:85], v[172:173] op_sel:[0,1]
	s_waitcnt vmcnt(3)
	v_lshlrev_b32_e32 v172, 16, v158
	v_and_b32_e32 v173, 0xffff0000, v158
	v_lshlrev_b32_e32 v158, 16, v159
	v_and_b32_e32 v159, 0xffff0000, v159
	s_waitcnt vmcnt(2)
	v_lshlrev_b32_e32 v176, 16, v160
	v_and_b32_e32 v177, 0xffff0000, v160
	v_lshlrev_b32_e32 v160, 16, v161
	v_and_b32_e32 v161, 0xffff0000, v161
	s_waitcnt vmcnt(1)
	v_lshlrev_b32_e32 v178, 16, v164
	v_and_b32_e32 v179, 0xffff0000, v164
	v_lshlrev_b32_e32 v164, 16, v165
	v_and_b32_e32 v165, 0xffff0000, v165
	s_waitcnt vmcnt(0)
	v_lshlrev_b32_e32 v180, 16, v166
	v_and_b32_e32 v181, 0xffff0000, v166
	v_lshlrev_b32_e32 v166, 16, v167
	v_and_b32_e32 v167, 0xffff0000, v167
	v_pk_fma_f32 v[96:97], v[140:141], v[96:97], v[158:159]
	v_pk_fma_f32 v[94:95], v[138:139], v[94:95], v[172:173]
	v_pk_fma_f32 v[92:93], v[144:145], v[92:93], v[160:161]
	v_pk_fma_f32 v[90:91], v[142:143], v[90:91], v[176:177]
	v_pk_fma_f32 v[88:89], v[136:137], v[88:89], v[164:165]
	v_pk_fma_f32 v[86:87], v[134:135], v[86:87], v[178:179]
	v_pk_fma_f32 v[84:85], v[132:133], v[84:85], v[166:167]
	v_pk_fma_f32 v[82:83], v[130:131], v[82:83], v[180:181]
	v_add_u32_e32 v158, 0x80, v150
	global_load_dwordx2 v[160:161], v[174:175], off
	global_load_dwordx2 v[164:165], v[174:175], off offset:32
	global_load_dwordx2 v[166:167], v[174:175], off offset:256
	global_load_dwordx2 v[172:173], v[174:175], off offset:288
	ds_read_b64 v[174:175], v185 offset:8576
	v_ashrrev_i32_e32 v159, 31, v158
	v_lshlrev_b64 v[176:177], 11, v[158:159]
	v_lshl_add_u64 v[176:177], s[56:57], 0, v[176:177]
	v_lshl_add_u64 v[176:177], v[176:177], 0, v[168:169]
	s_waitcnt lgkmcnt(0)
	v_pk_mul_f32 v[78:79], v[78:79], v[174:175] op_sel:[0,1]
	v_pk_mul_f32 v[80:81], v[80:81], v[174:175] op_sel:[0,1]
	v_pk_mul_f32 v[74:75], v[74:75], v[174:175] op_sel:[0,1]
	v_pk_mul_f32 v[76:77], v[76:77], v[174:175] op_sel:[0,1]
	v_pk_mul_f32 v[70:71], v[70:71], v[174:175] op_sel:[0,1]
	v_pk_mul_f32 v[72:73], v[72:73], v[174:175] op_sel:[0,1]
	v_pk_mul_f32 v[66:67], v[66:67], v[174:175] op_sel:[0,1]
	v_pk_mul_f32 v[68:69], v[68:69], v[174:175] op_sel:[0,1]
	s_waitcnt vmcnt(3)
	v_lshlrev_b32_e32 v174, 16, v160
	v_and_b32_e32 v175, 0xffff0000, v160
	v_lshlrev_b32_e32 v160, 16, v161
	v_and_b32_e32 v161, 0xffff0000, v161
	s_waitcnt vmcnt(2)
	v_lshlrev_b32_e32 v178, 16, v164
	v_and_b32_e32 v179, 0xffff0000, v164
	v_lshlrev_b32_e32 v164, 16, v165
	v_and_b32_e32 v165, 0xffff0000, v165
	s_waitcnt vmcnt(1)
	v_lshlrev_b32_e32 v180, 16, v166
	v_and_b32_e32 v181, 0xffff0000, v166
	v_lshlrev_b32_e32 v166, 16, v167
	v_and_b32_e32 v167, 0xffff0000, v167
	s_waitcnt vmcnt(0)
	v_lshlrev_b32_e32 v188, 16, v172
	v_and_b32_e32 v189, 0xffff0000, v172
	v_lshlrev_b32_e32 v172, 16, v173
	v_and_b32_e32 v173, 0xffff0000, v173
	v_pk_fma_f32 v[80:81], v[140:141], v[80:81], v[160:161]
	v_pk_fma_f32 v[78:79], v[138:139], v[78:79], v[174:175]
	v_pk_fma_f32 v[76:77], v[144:145], v[76:77], v[164:165]
	v_pk_fma_f32 v[74:75], v[142:143], v[74:75], v[178:179]
	v_pk_fma_f32 v[72:73], v[136:137], v[72:73], v[166:167]
	v_pk_fma_f32 v[70:71], v[134:135], v[70:71], v[180:181]
	v_pk_fma_f32 v[68:69], v[132:133], v[68:69], v[172:173]
	v_pk_fma_f32 v[66:67], v[130:131], v[66:67], v[188:189]
	v_add_u32_e32 v160, 0x90, v150
	global_load_dwordx2 v[164:165], v[176:177], off
	global_load_dwordx2 v[166:167], v[176:177], off offset:32
	global_load_dwordx2 v[172:173], v[176:177], off offset:256
	global_load_dwordx2 v[174:175], v[176:177], off offset:288
	ds_read_b64 v[176:177], v185 offset:9216
	v_ashrrev_i32_e32 v161, 31, v160
	v_lshlrev_b64 v[178:179], 11, v[160:161]
	v_lshl_add_u64 v[178:179], s[56:57], 0, v[178:179]
	v_lshl_add_u64 v[178:179], v[178:179], 0, v[168:169]
	s_waitcnt lgkmcnt(0)
	v_pk_mul_f32 v[62:63], v[62:63], v[176:177] op_sel:[0,1]
	v_pk_mul_f32 v[64:65], v[64:65], v[176:177] op_sel:[0,1]
	v_pk_mul_f32 v[58:59], v[58:59], v[176:177] op_sel:[0,1]
	v_pk_mul_f32 v[60:61], v[60:61], v[176:177] op_sel:[0,1]
	v_pk_mul_f32 v[54:55], v[54:55], v[176:177] op_sel:[0,1]
	v_pk_mul_f32 v[56:57], v[56:57], v[176:177] op_sel:[0,1]
	v_pk_mul_f32 v[50:51], v[50:51], v[176:177] op_sel:[0,1]
	v_pk_mul_f32 v[52:53], v[52:53], v[176:177] op_sel:[0,1]
	s_waitcnt vmcnt(3)
	v_lshlrev_b32_e32 v176, 16, v164
	v_and_b32_e32 v177, 0xffff0000, v164
	v_lshlrev_b32_e32 v164, 16, v165
	v_and_b32_e32 v165, 0xffff0000, v165
	s_waitcnt vmcnt(2)
	v_lshlrev_b32_e32 v180, 16, v166
	v_and_b32_e32 v181, 0xffff0000, v166
	v_lshlrev_b32_e32 v166, 16, v167
	v_and_b32_e32 v167, 0xffff0000, v167
	s_waitcnt vmcnt(1)
	v_lshlrev_b32_e32 v188, 16, v172
	v_and_b32_e32 v189, 0xffff0000, v172
	v_lshlrev_b32_e32 v172, 16, v173
	v_and_b32_e32 v173, 0xffff0000, v173
	s_waitcnt vmcnt(0)
	v_lshlrev_b32_e32 v190, 16, v174
	v_and_b32_e32 v191, 0xffff0000, v174
	v_lshlrev_b32_e32 v174, 16, v175
	v_and_b32_e32 v175, 0xffff0000, v175
	v_pk_fma_f32 v[64:65], v[140:141], v[64:65], v[164:165]
	v_pk_fma_f32 v[62:63], v[138:139], v[62:63], v[176:177]
	v_pk_fma_f32 v[60:61], v[144:145], v[60:61], v[166:167]
	v_pk_fma_f32 v[58:59], v[142:143], v[58:59], v[180:181]
	v_pk_fma_f32 v[56:57], v[136:137], v[56:57], v[172:173]
	v_pk_fma_f32 v[54:55], v[134:135], v[54:55], v[188:189]
	v_pk_fma_f32 v[52:53], v[132:133], v[52:53], v[174:175]
	v_pk_fma_f32 v[50:51], v[130:131], v[50:51], v[190:191]
	v_add_u32_e32 v164, 0xa0, v150
	global_load_dwordx2 v[166:167], v[178:179], off
	global_load_dwordx2 v[172:173], v[178:179], off offset:32
	global_load_dwordx2 v[174:175], v[178:179], off offset:256
	global_load_dwordx2 v[176:177], v[178:179], off offset:288
	ds_read_b64 v[178:179], v185 offset:9344
	v_ashrrev_i32_e32 v165, 31, v164
	v_lshlrev_b64 v[180:181], 11, v[164:165]
	v_lshl_add_u64 v[180:181], s[56:57], 0, v[180:181]
	v_lshl_add_u64 v[180:181], v[180:181], 0, v[168:169]
	s_waitcnt lgkmcnt(0)
	v_pk_mul_f32 v[46:47], v[46:47], v[178:179] op_sel:[0,1]
	v_pk_mul_f32 v[48:49], v[48:49], v[178:179] op_sel:[0,1]
	v_pk_mul_f32 v[42:43], v[42:43], v[178:179] op_sel:[0,1]
	v_pk_mul_f32 v[44:45], v[44:45], v[178:179] op_sel:[0,1]
	v_pk_mul_f32 v[38:39], v[38:39], v[178:179] op_sel:[0,1]
	v_pk_mul_f32 v[40:41], v[40:41], v[178:179] op_sel:[0,1]
	v_pk_mul_f32 v[34:35], v[34:35], v[178:179] op_sel:[0,1]
	v_pk_mul_f32 v[36:37], v[36:37], v[178:179] op_sel:[0,1]
	s_waitcnt vmcnt(3)
	v_lshlrev_b32_e32 v178, 16, v166
	v_and_b32_e32 v179, 0xffff0000, v166
	v_lshlrev_b32_e32 v166, 16, v167
	v_and_b32_e32 v167, 0xffff0000, v167
	s_waitcnt vmcnt(2)
	v_lshlrev_b32_e32 v188, 16, v172
	v_and_b32_e32 v189, 0xffff0000, v172
	v_lshlrev_b32_e32 v172, 16, v173
	v_and_b32_e32 v173, 0xffff0000, v173
	s_waitcnt vmcnt(1)
	v_lshlrev_b32_e32 v190, 16, v174
	v_and_b32_e32 v191, 0xffff0000, v174
	v_lshlrev_b32_e32 v174, 16, v175
	v_and_b32_e32 v175, 0xffff0000, v175
	s_waitcnt vmcnt(0)
	v_lshlrev_b32_e32 v192, 16, v176
	v_and_b32_e32 v193, 0xffff0000, v176
	v_lshlrev_b32_e32 v176, 16, v177
	v_and_b32_e32 v177, 0xffff0000, v177
	v_pk_fma_f32 v[48:49], v[140:141], v[48:49], v[166:167]
	v_pk_fma_f32 v[46:47], v[138:139], v[46:47], v[178:179]
	v_pk_fma_f32 v[44:45], v[144:145], v[44:45], v[172:173]
	v_pk_fma_f32 v[42:43], v[142:143], v[42:43], v[188:189]
	v_pk_fma_f32 v[40:41], v[136:137], v[40:41], v[174:175]
	v_pk_fma_f32 v[38:39], v[134:135], v[38:39], v[190:191]
	v_pk_fma_f32 v[36:37], v[132:133], v[36:37], v[176:177]
	v_pk_fma_f32 v[34:35], v[130:131], v[34:35], v[192:193]
	v_add_u32_e32 v166, 0xb0, v150
	global_load_dwordx2 v[172:173], v[180:181], off
	global_load_dwordx2 v[174:175], v[180:181], off offset:32
	global_load_dwordx2 v[176:177], v[180:181], off offset:256
	global_load_dwordx2 v[178:179], v[180:181], off offset:288
	ds_read_b64 v[196:197], v185 offset:9472
	v_ashrrev_i32_e32 v167, 31, v166
	v_lshlrev_b64 v[180:181], 11, v[166:167]
	v_lshl_add_u64 v[180:181], s[56:57], 0, v[180:181]
	v_lshl_add_u64 v[168:169], v[180:181], 0, v[168:169]
	v_mov_b32_e32 v180, v119
	v_mov_b32_e32 v181, v120
	v_mov_b32_e32 v188, v118
	v_mov_b32_e32 v189, v121
	v_mov_b32_e32 v190, v123
	v_mov_b32_e32 v191, v124
	v_mov_b32_e32 v192, v122
	v_mov_b32_e32 v193, v125
	s_waitcnt lgkmcnt(0)
	v_pk_mul_f32 v[30:31], v[30:31], v[196:197] op_sel:[0,1]
	v_pk_mul_f32 v[32:33], v[32:33], v[196:197] op_sel:[0,1]
	v_pk_mul_f32 v[26:27], v[26:27], v[196:197] op_sel:[0,1]
	v_pk_mul_f32 v[28:29], v[28:29], v[196:197] op_sel:[0,1]
	v_pk_mul_f32 v[22:23], v[22:23], v[196:197] op_sel:[0,1]
	v_pk_mul_f32 v[24:25], v[24:25], v[196:197] op_sel:[0,1]
	v_pk_mul_f32 v[18:19], v[18:19], v[196:197] op_sel:[0,1]
	v_pk_mul_f32 v[20:21], v[20:21], v[196:197] op_sel:[0,1]
	s_waitcnt vmcnt(3)
	v_lshlrev_b32_e32 v196, 16, v172
	v_and_b32_e32 v197, 0xffff0000, v172
	v_lshlrev_b32_e32 v172, 16, v173
	v_and_b32_e32 v173, 0xffff0000, v173
	s_waitcnt vmcnt(1)
	v_lshlrev_b32_e32 v210, 16, v176
	v_and_b32_e32 v211, 0xffff0000, v176
	v_lshlrev_b32_e32 v176, 16, v177
	v_and_b32_e32 v177, 0xffff0000, v177
	v_pk_fma_f32 v[32:33], v[140:141], v[32:33], v[172:173]
	v_pk_fma_f32 v[24:25], v[136:137], v[24:25], v[176:177]
	v_pk_add_f32 v[172:173], v[180:181], v[188:189]
	v_pk_add_f32 v[176:177], v[190:191], v[192:193]
	v_add_f32_e32 v188, v172, v173
	v_pk_add_f32 v[172:173], v[176:177], v[176:177] op_sel_hi:[0,1]
	v_lshlrev_b32_e32 v208, 16, v174
	v_and_b32_e32 v209, 0xffff0000, v174
	v_lshlrev_b32_e32 v174, 16, v175
	v_and_b32_e32 v175, 0xffff0000, v175
	s_waitcnt vmcnt(0)
	v_lshlrev_b32_e32 v212, 16, v178
	v_and_b32_e32 v213, 0xffff0000, v178
	v_lshlrev_b32_e32 v178, 16, v179
	v_and_b32_e32 v179, 0xffff0000, v179
	v_add_f32_e32 v207, 0, v188
	v_mov_b32_e32 v172, v116
	v_pk_fma_f32 v[30:31], v[138:139], v[30:31], v[196:197]
	v_pk_fma_f32 v[28:29], v[144:145], v[28:29], v[174:175]
	v_pk_fma_f32 v[26:27], v[142:143], v[26:27], v[208:209]
	v_pk_fma_f32 v[22:23], v[134:135], v[22:23], v[210:211]
	v_pk_fma_f32 v[20:21], v[132:133], v[20:21], v[178:179]
	v_pk_fma_f32 v[18:19], v[130:131], v[18:19], v[212:213]
	v_pk_add_f32 v[178:179], v[194:195], v[204:205]
	v_pk_add_f32 v[172:173], v[172:173], v[206:207]
	global_load_dwordx2 v[174:175], v[168:169], off
	global_load_dwordx2 v[180:181], v[168:169], off offset:32
	global_load_dwordx2 v[176:177], v[168:169], off offset:256
	v_pk_add_f32 v[172:173], v[178:179], v[172:173]
	global_load_dwordx2 v[178:179], v[168:169], off offset:288
	v_add_f32_e32 v168, v172, v173
	v_mov_b32_e32 v169, v168
	s_nop 1
	v_permlane16_swap_b32_e32 v168, v169
	s_waitcnt lgkmcnt(0)
	v_add_f32_e32 v168, v168, v169
	v_mov_b32_e32 v169, v168
	s_nop 1
	v_permlane32_swap_b32_e32 v168, v169
	s_waitcnt lgkmcnt(0)
	v_add_f32_e32 v168, v168, v169
	v_fmamk_f32 v172, v168, 0xbc800000, v121
	v_fmamk_f32 v188, v168, 0xbc800000, v119
	v_fmamk_f32 v190, v168, 0xbc800000, v125
	v_fmamk_f32 v192, v168, 0xbc800000, v123
	v_fmamk_f32 v169, v168, 0xbc800000, v120
	v_fmamk_f32 v173, v168, 0xbc800000, v118
	v_fmamk_f32 v189, v168, 0xbc800000, v124
	v_fmamk_f32 v191, v168, 0xbc800000, v122
	v_fmamk_f32 v194, v168, 0xbc800000, v129
	v_fmamk_f32 v196, v168, 0xbc800000, v127
	v_mul_f32_e32 v188, v188, v188
	v_mul_f32_e32 v172, v172, v172
	v_mul_f32_e32 v192, v192, v192
	v_mul_f32_e32 v190, v190, v190
	v_fmamk_f32 v193, v168, 0xbc800000, v128
	v_fmamk_f32 v195, v168, 0xbc800000, v126
	v_fmamk_f32 v200, v168, 0xbc800000, v117
	v_fmamk_f32 v205, v168, 0xbc800000, v115
	v_mul_f32_e32 v196, v196, v196
	v_mul_f32_e32 v194, v194, v194
	v_fmac_f32_e32 v188, v173, v173
	v_fmac_f32_e32 v172, v169, v169
	v_fmac_f32_e32 v192, v191, v191
	v_fmac_f32_e32 v190, v189, v189
	v_fmamk_f32 v197, v168, 0xbc800000, v116
	v_fmamk_f32 v204, v168, 0xbc800000, v114
	v_mul_f32_e32 v205, v205, v205
	v_mul_f32_e32 v200, v200, v200
	v_fmac_f32_e32 v196, v195, v195
	v_fmac_f32_e32 v194, v193, v193
	v_add_f32_e32 v169, v188, v172
	v_add_f32_e32 v172, v192, v190
	v_fmac_f32_e32 v205, v204, v204
	v_fmac_f32_e32 v200, v197, v197
	v_add_f32_e32 v173, v196, v194
	v_add_f32_e32 v169, v169, v172
	v_add_f32_e32 v188, v205, v200
	v_add_f32_e32 v169, v173, v169
	v_add_f32_e32 v169, v188, v169
	v_mov_b32_e32 v172, v169
	s_nop 1
	v_permlane16_swap_b32_e32 v169, v172
	ds_read_b64 v[188:189], v185 offset:9600
	s_waitcnt lgkmcnt(1)
	v_add_f32_e32 v169, v169, v172
	ds_bpermute_b32 v172, v202, v169
	s_waitcnt lgkmcnt(1)
	v_pk_mul_f32 v[14:15], v[14:15], v[188:189] op_sel:[0,1]
	v_pk_mul_f32 v[16:17], v[16:17], v[188:189] op_sel:[0,1]
	v_pk_mul_f32 v[10:11], v[10:11], v[188:189] op_sel:[0,1]
	v_pk_mul_f32 v[12:13], v[12:13], v[188:189] op_sel:[0,1]
	v_pk_mul_f32 v[6:7], v[6:7], v[188:189] op_sel:[0,1]
	v_pk_mul_f32 v[8:9], v[8:9], v[188:189] op_sel:[0,1]
	v_pk_mul_f32 v[2:3], v[2:3], v[188:189] op_sel:[0,1]
	v_pk_mul_f32 v[4:5], v[4:5], v[188:189] op_sel:[0,1]
	s_waitcnt vmcnt(3)
	v_lshlrev_b32_e32 v188, 16, v174
	v_and_b32_e32 v189, 0xffff0000, v174
	v_lshlrev_b32_e32 v174, 16, v175
	v_and_b32_e32 v175, 0xffff0000, v175
	s_waitcnt vmcnt(2)
	v_lshlrev_b32_e32 v190, 16, v180
	v_and_b32_e32 v191, 0xffff0000, v180
	v_lshlrev_b32_e32 v180, 16, v181
	v_and_b32_e32 v181, 0xffff0000, v181
	s_waitcnt vmcnt(1)
	v_lshlrev_b32_e32 v192, 16, v176
	v_and_b32_e32 v193, 0xffff0000, v176
	v_lshlrev_b32_e32 v176, 16, v177
	v_and_b32_e32 v177, 0xffff0000, v177
	s_waitcnt vmcnt(0)
	v_lshlrev_b32_e32 v194, 16, v178
	v_and_b32_e32 v195, 0xffff0000, v178
	v_lshlrev_b32_e32 v178, 16, v179
	v_and_b32_e32 v179, 0xffff0000, v179
	v_pk_fma_f32 v[16:17], v[140:141], v[16:17], v[174:175]
	v_pk_fma_f32 v[14:15], v[138:139], v[14:15], v[188:189]
	v_pk_fma_f32 v[12:13], v[144:145], v[12:13], v[180:181]
	v_pk_fma_f32 v[10:11], v[142:143], v[10:11], v[190:191]
	v_pk_fma_f32 v[8:9], v[136:137], v[8:9], v[176:177]
	v_pk_fma_f32 v[6:7], v[134:135], v[6:7], v[192:193]
	v_pk_fma_f32 v[4:5], v[132:133], v[4:5], v[178:179]
	v_pk_fma_f32 v[2:3], v[130:131], v[2:3], v[194:195]
	s_nop 0
	s_and_saveexec_b64 s[0:1], s[6:7]
	s_cbranch_execz .LBB0_898
	s_lshl_b32 s17, s27, 11
	s_add_i32 s17, s28, s17
	v_mul_f32_e32 v130, 0x3c800000, v168
	s_waitcnt lgkmcnt(0)
	v_add_f32_e32 v131, v169, v172
	v_lshl_add_u32 v132, v170, 5, s17
	ds_write_b64 v132, v[130:131]
.LBB0_898:
	s_or_b64 exec, exec, s[0:1]
	v_mov_b32_e32 v130, v111
	v_mov_b32_e32 v131, v112
	v_mov_b32_e32 v132, v110
	v_mov_b32_e32 v133, v113
	v_pk_add_f32 v[130:131], v[130:131], v[132:133]
	v_mov_b32_e32 v132, v107
	v_mov_b32_e32 v133, v108
	v_mov_b32_e32 v134, v106
	v_mov_b32_e32 v135, v109
	v_pk_add_f32 v[132:133], v[132:133], v[134:135]
	v_add_f32_e32 v130, v130, v131
	v_pk_add_f32 v[132:133], v[132:133], v[132:133] op_sel_hi:[0,1]
	v_add_f32_e32 v131, 0, v130
	v_add_f32_e32 v135, v102, v103
	v_add_f32_e32 v137, v104, v105
	v_mov_b32_e32 v134, v98
	v_mov_b32_e32 v136, v99
	v_mov_b32_e32 v132, v100
	v_mov_b32_e32 v130, v101
	v_pk_add_f32 v[134:135], v[134:135], v[136:137]
	v_pk_add_f32 v[130:131], v[132:133], v[130:131]
	s_nop 0
	v_pk_add_f32 v[130:131], v[134:135], v[130:131]
	s_nop 0
	v_add_f32_e32 v130, v130, v131
	v_mov_b32_e32 v131, v130
	s_nop 1
	v_permlane16_swap_b32_e32 v130, v131
	s_waitcnt lgkmcnt(0)
	v_add_f32_e32 v130, v130, v131
	v_mov_b32_e32 v131, v130
	s_nop 1
	v_permlane32_swap_b32_e32 v130, v131
	s_waitcnt lgkmcnt(0)
	v_add_f32_e32 v130, v130, v131
	v_fmamk_f32 v132, v130, 0xbc800000, v113
	v_fmamk_f32 v134, v130, 0xbc800000, v111
	v_fmamk_f32 v131, v130, 0xbc800000, v112
	v_fmamk_f32 v133, v130, 0xbc800000, v110
	v_mul_f32_e32 v134, v134, v134
	v_mul_f32_e32 v132, v132, v132
	v_fmac_f32_e32 v134, v133, v133
	v_fmac_f32_e32 v132, v131, v131
	v_fmamk_f32 v133, v130, 0xbc800000, v109
	v_fmamk_f32 v135, v130, 0xbc800000, v107
	v_add_f32_e32 v131, v134, v132
	v_fmamk_f32 v132, v130, 0xbc800000, v108
	v_fmamk_f32 v134, v130, 0xbc800000, v106
	v_mul_f32_e32 v135, v135, v135
	v_mul_f32_e32 v133, v133, v133
	v_fmac_f32_e32 v135, v134, v134
	v_fmac_f32_e32 v133, v132, v132
	v_add_f32_e32 v132, v135, v133
	v_fmamk_f32 v133, v130, 0xbc800000, v105
	v_fmamk_f32 v135, v130, 0xbc800000, v103
	v_add_f32_e32 v131, v131, v132
	v_fmamk_f32 v132, v130, 0xbc800000, v104
	v_fmamk_f32 v134, v130, 0xbc800000, v102
	v_mul_f32_e32 v135, v135, v135
	v_mul_f32_e32 v133, v133, v133
	v_fmac_f32_e32 v135, v134, v134
	v_fmac_f32_e32 v133, v132, v132
	v_add_f32_e32 v132, v135, v133
	v_fmamk_f32 v133, v130, 0xbc800000, v101
	v_fmamk_f32 v135, v130, 0xbc800000, v99
	v_add_f32_e32 v131, v132, v131
	v_fmamk_f32 v132, v130, 0xbc800000, v100
	v_fmamk_f32 v134, v130, 0xbc800000, v98
	v_mul_f32_e32 v135, v135, v135
	v_mul_f32_e32 v133, v133, v133
	v_fmac_f32_e32 v135, v134, v134
	v_fmac_f32_e32 v133, v132, v132
	v_add_f32_e32 v132, v135, v133
	v_add_f32_e32 v131, v132, v131
	v_mov_b32_e32 v132, v131
	s_nop 1
	v_permlane16_swap_b32_e32 v131, v132
	s_waitcnt lgkmcnt(0)
	v_add_f32_e32 v131, v131, v132
	v_mov_b32_e32 v132, v131
	s_nop 1
	v_permlane32_swap_b32_e32 v131, v132
	s_and_saveexec_b64 s[0:1], s[6:7]
	s_cbranch_execz .LBB0_900
	s_lshl_b32 s17, s27, 11
	s_add_i32 s17, s28, s17
	v_mul_f32_e32 v130, 0x3c800000, v130
	s_waitcnt lgkmcnt(0)
	v_add_f32_e32 v131, v131, v132
	v_lshl_add_u32 v132, v170, 5, s17
	ds_write_b64 v132, v[130:131] offset:512
.LBB0_900:
	s_or_b64 exec, exec, s[0:1]
	v_mov_b32_e32 v130, v95
	v_mov_b32_e32 v131, v96
	s_waitcnt lgkmcnt(0)
	v_mov_b32_e32 v132, v94
	v_mov_b32_e32 v133, v97
	v_pk_add_f32 v[130:131], v[130:131], v[132:133]
	v_mov_b32_e32 v132, v91
	v_mov_b32_e32 v133, v92
	v_mov_b32_e32 v134, v90
	v_mov_b32_e32 v135, v93
	v_pk_add_f32 v[132:133], v[132:133], v[134:135]
	v_add_f32_e32 v130, v130, v131
	v_pk_add_f32 v[132:133], v[132:133], v[132:133] op_sel_hi:[0,1]
	v_add_f32_e32 v131, 0, v130
	v_add_f32_e32 v135, v86, v87
	v_add_f32_e32 v137, v88, v89
	v_mov_b32_e32 v134, v82
	v_mov_b32_e32 v136, v83
	v_mov_b32_e32 v132, v84
	v_mov_b32_e32 v130, v85
	v_pk_add_f32 v[134:135], v[134:135], v[136:137]
	v_pk_add_f32 v[130:131], v[132:133], v[130:131]
	s_nop 0
	v_pk_add_f32 v[130:131], v[134:135], v[130:131]
	s_nop 0
	v_add_f32_e32 v130, v130, v131
	v_mov_b32_e32 v131, v130
	s_nop 1
	v_permlane16_swap_b32_e32 v130, v131
	s_waitcnt lgkmcnt(0)
	v_add_f32_e32 v130, v130, v131
	v_mov_b32_e32 v131, v130
	s_nop 1
	v_permlane32_swap_b32_e32 v130, v131
	s_waitcnt lgkmcnt(0)
	v_add_f32_e32 v130, v130, v131
	v_fmamk_f32 v132, v130, 0xbc800000, v97
	v_fmamk_f32 v134, v130, 0xbc800000, v95
	v_fmamk_f32 v131, v130, 0xbc800000, v96
	v_fmamk_f32 v133, v130, 0xbc800000, v94
	v_mul_f32_e32 v134, v134, v134
	v_mul_f32_e32 v132, v132, v132
	v_fmac_f32_e32 v134, v133, v133
	v_fmac_f32_e32 v132, v131, v131
	v_fmamk_f32 v133, v130, 0xbc800000, v93
	v_fmamk_f32 v135, v130, 0xbc800000, v91
	v_add_f32_e32 v131, v134, v132
	v_fmamk_f32 v132, v130, 0xbc800000, v92
	v_fmamk_f32 v134, v130, 0xbc800000, v90
	v_mul_f32_e32 v135, v135, v135
	v_mul_f32_e32 v133, v133, v133
	v_fmac_f32_e32 v135, v134, v134
	v_fmac_f32_e32 v133, v132, v132
	v_add_f32_e32 v132, v135, v133
	v_fmamk_f32 v133, v130, 0xbc800000, v89
	v_fmamk_f32 v135, v130, 0xbc800000, v87
	v_add_f32_e32 v131, v131, v132
	v_fmamk_f32 v132, v130, 0xbc800000, v88
	v_fmamk_f32 v134, v130, 0xbc800000, v86
	v_mul_f32_e32 v135, v135, v135
	v_mul_f32_e32 v133, v133, v133
	v_fmac_f32_e32 v135, v134, v134
	v_fmac_f32_e32 v133, v132, v132
	v_add_f32_e32 v132, v135, v133
	v_fmamk_f32 v133, v130, 0xbc800000, v85
	v_fmamk_f32 v135, v130, 0xbc800000, v83
	v_add_f32_e32 v131, v132, v131
	v_fmamk_f32 v132, v130, 0xbc800000, v84
	v_fmamk_f32 v134, v130, 0xbc800000, v82
	v_mul_f32_e32 v135, v135, v135
	v_mul_f32_e32 v133, v133, v133
	v_fmac_f32_e32 v135, v134, v134
	v_fmac_f32_e32 v133, v132, v132
	v_add_f32_e32 v132, v135, v133
	v_add_f32_e32 v131, v132, v131
	v_mov_b32_e32 v132, v131
	s_nop 1
	v_permlane16_swap_b32_e32 v131, v132
	s_waitcnt lgkmcnt(0)
	v_add_f32_e32 v131, v131, v132
	v_mov_b32_e32 v132, v131
	s_nop 1
	v_permlane32_swap_b32_e32 v131, v132
	s_and_saveexec_b64 s[0:1], s[6:7]
	s_cbranch_execz .LBB0_902
	s_lshl_b32 s17, s27, 11
	s_add_i32 s17, s28, s17
	v_mul_f32_e32 v130, 0x3c800000, v130
	s_waitcnt lgkmcnt(0)
	v_add_f32_e32 v131, v131, v132
	v_lshl_add_u32 v132, v170, 5, s17
	ds_write_b64 v132, v[130:131] offset:1024
.LBB0_902:
	s_or_b64 exec, exec, s[0:1]
	v_mov_b32_e32 v130, v79
	v_mov_b32_e32 v131, v80
	s_waitcnt lgkmcnt(0)
	v_mov_b32_e32 v132, v78
	v_mov_b32_e32 v133, v81
	v_pk_add_f32 v[130:131], v[130:131], v[132:133]
	v_mov_b32_e32 v132, v75
	v_mov_b32_e32 v133, v76
	v_mov_b32_e32 v134, v74
	v_mov_b32_e32 v135, v77
	v_pk_add_f32 v[132:133], v[132:133], v[134:135]
	v_add_f32_e32 v130, v130, v131
	v_pk_add_f32 v[132:133], v[132:133], v[132:133] op_sel_hi:[0,1]
	v_add_f32_e32 v131, 0, v130
	v_add_f32_e32 v135, v70, v71
	v_add_f32_e32 v137, v72, v73
	v_mov_b32_e32 v134, v66
	v_mov_b32_e32 v136, v67
	v_mov_b32_e32 v132, v68
	v_mov_b32_e32 v130, v69
	v_pk_add_f32 v[134:135], v[134:135], v[136:137]
	v_pk_add_f32 v[130:131], v[132:133], v[130:131]
	s_nop 0
	v_pk_add_f32 v[130:131], v[134:135], v[130:131]
	s_nop 0
	v_add_f32_e32 v130, v130, v131
	v_mov_b32_e32 v131, v130
	s_nop 1
	v_permlane16_swap_b32_e32 v130, v131
	s_waitcnt lgkmcnt(0)
	v_add_f32_e32 v130, v130, v131
	v_mov_b32_e32 v131, v130
	s_nop 1
	v_permlane32_swap_b32_e32 v130, v131
	s_waitcnt lgkmcnt(0)
	v_add_f32_e32 v130, v130, v131
	v_fmamk_f32 v132, v130, 0xbc800000, v81
	v_fmamk_f32 v134, v130, 0xbc800000, v79
	v_fmamk_f32 v131, v130, 0xbc800000, v80
	v_fmamk_f32 v133, v130, 0xbc800000, v78
	v_mul_f32_e32 v134, v134, v134
	v_mul_f32_e32 v132, v132, v132
	v_fmac_f32_e32 v134, v133, v133
	v_fmac_f32_e32 v132, v131, v131
	v_fmamk_f32 v133, v130, 0xbc800000, v77
	v_fmamk_f32 v135, v130, 0xbc800000, v75
	v_add_f32_e32 v131, v134, v132
	v_fmamk_f32 v132, v130, 0xbc800000, v76
	v_fmamk_f32 v134, v130, 0xbc800000, v74
	v_mul_f32_e32 v135, v135, v135
	v_mul_f32_e32 v133, v133, v133
	v_fmac_f32_e32 v135, v134, v134
	v_fmac_f32_e32 v133, v132, v132
	v_add_f32_e32 v132, v135, v133
	v_fmamk_f32 v133, v130, 0xbc800000, v73
	v_fmamk_f32 v135, v130, 0xbc800000, v71
	v_add_f32_e32 v131, v131, v132
	v_fmamk_f32 v132, v130, 0xbc800000, v72
	v_fmamk_f32 v134, v130, 0xbc800000, v70
	v_mul_f32_e32 v135, v135, v135
	v_mul_f32_e32 v133, v133, v133
	v_fmac_f32_e32 v135, v134, v134
	v_fmac_f32_e32 v133, v132, v132
	v_add_f32_e32 v132, v135, v133
	v_fmamk_f32 v133, v130, 0xbc800000, v69
	v_fmamk_f32 v135, v130, 0xbc800000, v67
	v_add_f32_e32 v131, v132, v131
	v_fmamk_f32 v132, v130, 0xbc800000, v68
	v_fmamk_f32 v134, v130, 0xbc800000, v66
	v_mul_f32_e32 v135, v135, v135
	v_mul_f32_e32 v133, v133, v133
	v_fmac_f32_e32 v135, v134, v134
	v_fmac_f32_e32 v133, v132, v132
	v_add_f32_e32 v132, v135, v133
	v_add_f32_e32 v131, v132, v131
	v_mov_b32_e32 v132, v131
	s_nop 1
	v_permlane16_swap_b32_e32 v131, v132
	s_waitcnt lgkmcnt(0)
	v_add_f32_e32 v131, v131, v132
	v_mov_b32_e32 v132, v131
	s_nop 1
	v_permlane32_swap_b32_e32 v131, v132
	s_and_saveexec_b64 s[0:1], s[6:7]
	s_cbranch_execz .LBB0_904
	s_lshl_b32 s17, s27, 11
	s_add_i32 s17, s28, s17
	v_mul_f32_e32 v130, 0x3c800000, v130
	s_waitcnt lgkmcnt(0)
	v_add_f32_e32 v131, v131, v132
	v_lshl_add_u32 v132, v170, 5, s17
	ds_write_b64 v132, v[130:131] offset:1536
.LBB0_904:
	s_or_b64 exec, exec, s[0:1]
	v_mov_b32_e32 v130, v63
	v_mov_b32_e32 v131, v64
	s_waitcnt lgkmcnt(0)
	v_mov_b32_e32 v132, v62
	v_mov_b32_e32 v133, v65
	v_pk_add_f32 v[130:131], v[130:131], v[132:133]
	v_mov_b32_e32 v132, v59
	v_mov_b32_e32 v133, v60
	v_mov_b32_e32 v134, v58
	v_mov_b32_e32 v135, v61
	v_pk_add_f32 v[132:133], v[132:133], v[134:135]
	v_add_f32_e32 v130, v130, v131
	v_pk_add_f32 v[132:133], v[132:133], v[132:133] op_sel_hi:[0,1]
	v_add_f32_e32 v131, 0, v130
	v_add_f32_e32 v135, v54, v55
	v_add_f32_e32 v137, v56, v57
	v_mov_b32_e32 v134, v50
	v_mov_b32_e32 v136, v51
	v_mov_b32_e32 v132, v52
	v_mov_b32_e32 v130, v53
	v_pk_add_f32 v[134:135], v[134:135], v[136:137]
	v_pk_add_f32 v[130:131], v[132:133], v[130:131]
	s_nop 0
	v_pk_add_f32 v[130:131], v[134:135], v[130:131]
	s_nop 0
	v_add_f32_e32 v130, v130, v131
	v_mov_b32_e32 v131, v130
	s_nop 1
	v_permlane16_swap_b32_e32 v130, v131
	s_waitcnt lgkmcnt(0)
	v_add_f32_e32 v130, v130, v131
	v_mov_b32_e32 v131, v130
	s_nop 1
	v_permlane32_swap_b32_e32 v130, v131
	s_waitcnt lgkmcnt(0)
	v_add_f32_e32 v130, v130, v131
	v_fmamk_f32 v132, v130, 0xbc800000, v65
	v_fmamk_f32 v134, v130, 0xbc800000, v63
	v_fmamk_f32 v131, v130, 0xbc800000, v64
	v_fmamk_f32 v133, v130, 0xbc800000, v62
	v_mul_f32_e32 v134, v134, v134
	v_mul_f32_e32 v132, v132, v132
	v_fmac_f32_e32 v134, v133, v133
	v_fmac_f32_e32 v132, v131, v131
	v_fmamk_f32 v133, v130, 0xbc800000, v61
	v_fmamk_f32 v135, v130, 0xbc800000, v59
	v_add_f32_e32 v131, v134, v132
	v_fmamk_f32 v132, v130, 0xbc800000, v60
	v_fmamk_f32 v134, v130, 0xbc800000, v58
	v_mul_f32_e32 v135, v135, v135
	v_mul_f32_e32 v133, v133, v133
	v_fmac_f32_e32 v135, v134, v134
	v_fmac_f32_e32 v133, v132, v132
	v_add_f32_e32 v132, v135, v133
	v_fmamk_f32 v133, v130, 0xbc800000, v57
	v_fmamk_f32 v135, v130, 0xbc800000, v55
	v_add_f32_e32 v131, v131, v132
	v_fmamk_f32 v132, v130, 0xbc800000, v56
	v_fmamk_f32 v134, v130, 0xbc800000, v54
	v_mul_f32_e32 v135, v135, v135
	v_mul_f32_e32 v133, v133, v133
	v_fmac_f32_e32 v135, v134, v134
	v_fmac_f32_e32 v133, v132, v132
	v_add_f32_e32 v132, v135, v133
	v_fmamk_f32 v133, v130, 0xbc800000, v53
	v_fmamk_f32 v135, v130, 0xbc800000, v51
	v_add_f32_e32 v131, v132, v131
	v_fmamk_f32 v132, v130, 0xbc800000, v52
	v_fmamk_f32 v134, v130, 0xbc800000, v50
	v_mul_f32_e32 v135, v135, v135
	v_mul_f32_e32 v133, v133, v133
	v_fmac_f32_e32 v135, v134, v134
	v_fmac_f32_e32 v133, v132, v132
	v_add_f32_e32 v132, v135, v133
	v_add_f32_e32 v131, v132, v131
	v_mov_b32_e32 v132, v131
	s_nop 1
	v_permlane16_swap_b32_e32 v131, v132
	s_waitcnt lgkmcnt(0)
	v_add_f32_e32 v131, v131, v132
	v_mov_b32_e32 v132, v131
	s_nop 1
	v_permlane32_swap_b32_e32 v131, v132
	s_and_saveexec_b64 s[0:1], s[6:7]
	s_cbranch_execz .LBB0_906
	s_lshl_b32 s17, s27, 11
	s_add_i32 s17, s28, s17
	v_mul_f32_e32 v130, 0x3c800000, v130
	s_waitcnt lgkmcnt(0)
	v_add_f32_e32 v131, v131, v132
	v_lshl_add_u32 v132, v170, 5, s17
	ds_write_b64 v132, v[130:131] offset:4096
.LBB0_906:
	s_or_b64 exec, exec, s[0:1]
	v_mov_b32_e32 v130, v47
	v_mov_b32_e32 v131, v48
	s_waitcnt lgkmcnt(0)
	v_mov_b32_e32 v132, v46
	v_mov_b32_e32 v133, v49
	v_pk_add_f32 v[130:131], v[130:131], v[132:133]
	v_mov_b32_e32 v132, v43
	v_mov_b32_e32 v133, v44
	v_mov_b32_e32 v134, v42
	v_mov_b32_e32 v135, v45
	v_pk_add_f32 v[132:133], v[132:133], v[134:135]
	v_add_f32_e32 v130, v130, v131
	v_pk_add_f32 v[132:133], v[132:133], v[132:133] op_sel_hi:[0,1]
	v_add_f32_e32 v131, 0, v130
	v_add_f32_e32 v135, v38, v39
	v_add_f32_e32 v137, v40, v41
	v_mov_b32_e32 v134, v34
	v_mov_b32_e32 v136, v35
	v_mov_b32_e32 v132, v36
	v_mov_b32_e32 v130, v37
	v_pk_add_f32 v[134:135], v[134:135], v[136:137]
	v_pk_add_f32 v[130:131], v[132:133], v[130:131]
	s_nop 0
	v_pk_add_f32 v[130:131], v[134:135], v[130:131]
	s_nop 0
	v_add_f32_e32 v130, v130, v131
	v_mov_b32_e32 v131, v130
	s_nop 1
	v_permlane16_swap_b32_e32 v130, v131
	s_waitcnt lgkmcnt(0)
	v_add_f32_e32 v130, v130, v131
	v_mov_b32_e32 v131, v130
	s_nop 1
	v_permlane32_swap_b32_e32 v130, v131
	s_waitcnt lgkmcnt(0)
	v_add_f32_e32 v130, v130, v131
	v_fmamk_f32 v132, v130, 0xbc800000, v49
	v_fmamk_f32 v134, v130, 0xbc800000, v47
	v_fmamk_f32 v131, v130, 0xbc800000, v48
	v_fmamk_f32 v133, v130, 0xbc800000, v46
	v_mul_f32_e32 v134, v134, v134
	v_mul_f32_e32 v132, v132, v132
	v_fmac_f32_e32 v134, v133, v133
	v_fmac_f32_e32 v132, v131, v131
	v_fmamk_f32 v133, v130, 0xbc800000, v45
	v_fmamk_f32 v135, v130, 0xbc800000, v43
	v_add_f32_e32 v131, v134, v132
	v_fmamk_f32 v132, v130, 0xbc800000, v44
	v_fmamk_f32 v134, v130, 0xbc800000, v42
	v_mul_f32_e32 v135, v135, v135
	v_mul_f32_e32 v133, v133, v133
	v_fmac_f32_e32 v135, v134, v134
	v_fmac_f32_e32 v133, v132, v132
	v_add_f32_e32 v132, v135, v133
	v_fmamk_f32 v133, v130, 0xbc800000, v41
	v_fmamk_f32 v135, v130, 0xbc800000, v39
	v_add_f32_e32 v131, v131, v132
	v_fmamk_f32 v132, v130, 0xbc800000, v40
	v_fmamk_f32 v134, v130, 0xbc800000, v38
	v_mul_f32_e32 v135, v135, v135
	v_mul_f32_e32 v133, v133, v133
	v_fmac_f32_e32 v135, v134, v134
	v_fmac_f32_e32 v133, v132, v132
	v_add_f32_e32 v132, v135, v133
	v_fmamk_f32 v133, v130, 0xbc800000, v37
	v_fmamk_f32 v135, v130, 0xbc800000, v35
	v_add_f32_e32 v131, v132, v131
	v_fmamk_f32 v132, v130, 0xbc800000, v36
	v_fmamk_f32 v134, v130, 0xbc800000, v34
	v_mul_f32_e32 v135, v135, v135
	v_mul_f32_e32 v133, v133, v133
	v_fmac_f32_e32 v135, v134, v134
	v_fmac_f32_e32 v133, v132, v132
	v_add_f32_e32 v132, v135, v133
	v_add_f32_e32 v131, v132, v131
	v_mov_b32_e32 v132, v131
	s_nop 1
	v_permlane16_swap_b32_e32 v131, v132
	s_waitcnt lgkmcnt(0)
	v_add_f32_e32 v131, v131, v132
	v_mov_b32_e32 v132, v131
	s_nop 1
	v_permlane32_swap_b32_e32 v131, v132
	s_and_saveexec_b64 s[0:1], s[6:7]
	s_cbranch_execz .LBB0_908
	s_lshl_b32 s17, s27, 11
	s_add_i32 s17, s28, s17
	v_mul_f32_e32 v130, 0x3c800000, v130
	s_waitcnt lgkmcnt(0)
	v_add_f32_e32 v131, v131, v132
	v_lshl_add_u32 v132, v170, 5, s17
	ds_write_b64 v132, v[130:131] offset:4608
.LBB0_908:
	s_or_b64 exec, exec, s[0:1]
	v_mov_b32_e32 v130, v31
	v_mov_b32_e32 v131, v32
	s_waitcnt lgkmcnt(0)
	v_mov_b32_e32 v132, v30
	v_mov_b32_e32 v133, v33
	v_pk_add_f32 v[130:131], v[130:131], v[132:133]
	v_mov_b32_e32 v132, v27
	v_mov_b32_e32 v133, v28
	v_mov_b32_e32 v134, v26
	v_mov_b32_e32 v135, v29
	v_pk_add_f32 v[132:133], v[132:133], v[134:135]
	v_add_f32_e32 v130, v130, v131
	v_pk_add_f32 v[132:133], v[132:133], v[132:133] op_sel_hi:[0,1]
	v_add_f32_e32 v131, 0, v130
	v_add_f32_e32 v135, v22, v23
	v_add_f32_e32 v137, v24, v25
	v_mov_b32_e32 v134, v18
	v_mov_b32_e32 v136, v19
	v_mov_b32_e32 v132, v20
	v_mov_b32_e32 v130, v21
	v_pk_add_f32 v[134:135], v[134:135], v[136:137]
	v_pk_add_f32 v[130:131], v[132:133], v[130:131]
	s_nop 0
	v_pk_add_f32 v[130:131], v[134:135], v[130:131]
	s_nop 0
	v_add_f32_e32 v130, v130, v131
	v_mov_b32_e32 v131, v130
	s_nop 1
	v_permlane16_swap_b32_e32 v130, v131
	s_waitcnt lgkmcnt(0)
	v_add_f32_e32 v130, v130, v131
	v_mov_b32_e32 v131, v130
	s_nop 1
	v_permlane32_swap_b32_e32 v130, v131
	s_waitcnt lgkmcnt(0)
	v_add_f32_e32 v130, v130, v131
	v_fmamk_f32 v132, v130, 0xbc800000, v33
	v_fmamk_f32 v134, v130, 0xbc800000, v31
	v_fmamk_f32 v131, v130, 0xbc800000, v32
	v_fmamk_f32 v133, v130, 0xbc800000, v30
	v_mul_f32_e32 v134, v134, v134
	v_mul_f32_e32 v132, v132, v132
	v_fmac_f32_e32 v134, v133, v133
	v_fmac_f32_e32 v132, v131, v131
	v_fmamk_f32 v133, v130, 0xbc800000, v29
	v_fmamk_f32 v135, v130, 0xbc800000, v27
	v_add_f32_e32 v131, v134, v132
	v_fmamk_f32 v132, v130, 0xbc800000, v28
	v_fmamk_f32 v134, v130, 0xbc800000, v26
	v_mul_f32_e32 v135, v135, v135
	v_mul_f32_e32 v133, v133, v133
	v_fmac_f32_e32 v135, v134, v134
	v_fmac_f32_e32 v133, v132, v132
	v_add_f32_e32 v132, v135, v133
	v_fmamk_f32 v133, v130, 0xbc800000, v25
	v_fmamk_f32 v135, v130, 0xbc800000, v23
	v_add_f32_e32 v131, v131, v132
	v_fmamk_f32 v132, v130, 0xbc800000, v24
	v_fmamk_f32 v134, v130, 0xbc800000, v22
	v_mul_f32_e32 v135, v135, v135
	v_mul_f32_e32 v133, v133, v133
	v_fmac_f32_e32 v135, v134, v134
	v_fmac_f32_e32 v133, v132, v132
	v_add_f32_e32 v132, v135, v133
	v_fmamk_f32 v133, v130, 0xbc800000, v21
	v_fmamk_f32 v135, v130, 0xbc800000, v19
	v_add_f32_e32 v131, v132, v131
	v_fmamk_f32 v132, v130, 0xbc800000, v20
	v_fmamk_f32 v134, v130, 0xbc800000, v18
	v_mul_f32_e32 v135, v135, v135
	v_mul_f32_e32 v133, v133, v133
	v_fmac_f32_e32 v135, v134, v134
	v_fmac_f32_e32 v133, v132, v132
	v_add_f32_e32 v132, v135, v133
	v_add_f32_e32 v131, v132, v131
	v_mov_b32_e32 v132, v131
	s_nop 1
	v_permlane16_swap_b32_e32 v131, v132
	s_waitcnt lgkmcnt(0)
	v_add_f32_e32 v131, v131, v132
	v_mov_b32_e32 v132, v131
	s_nop 1
	v_permlane32_swap_b32_e32 v131, v132
	s_and_saveexec_b64 s[0:1], s[6:7]
	s_cbranch_execz .LBB0_910
	s_lshl_b32 s17, s27, 11
	s_add_i32 s17, s28, s17
	v_mul_f32_e32 v130, 0x3c800000, v130
	s_waitcnt lgkmcnt(0)
	v_add_f32_e32 v131, v131, v132
	v_lshl_add_u32 v132, v170, 5, s17
	ds_write_b64 v132, v[130:131] offset:5120
.LBB0_910:
	s_or_b64 exec, exec, s[0:1]
	v_mov_b32_e32 v130, v15
	v_mov_b32_e32 v131, v16
	s_waitcnt lgkmcnt(0)
	v_mov_b32_e32 v132, v14
	v_mov_b32_e32 v133, v17
	v_pk_add_f32 v[130:131], v[130:131], v[132:133]
	v_mov_b32_e32 v132, v11
	v_mov_b32_e32 v133, v12
	v_mov_b32_e32 v134, v10
	v_mov_b32_e32 v135, v13
	v_pk_add_f32 v[132:133], v[132:133], v[134:135]
	v_add_f32_e32 v130, v130, v131
	v_pk_add_f32 v[132:133], v[132:133], v[132:133] op_sel_hi:[0,1]
	v_add_f32_e32 v131, 0, v130
	v_add_f32_e32 v135, v6, v7
	v_add_f32_e32 v137, v8, v9
	v_mov_b32_e32 v134, v2
	v_mov_b32_e32 v136, v3
	v_mov_b32_e32 v132, v4
	v_mov_b32_e32 v130, v5
	v_pk_add_f32 v[134:135], v[134:135], v[136:137]
	v_pk_add_f32 v[130:131], v[132:133], v[130:131]
	s_nop 0
	v_pk_add_f32 v[130:131], v[134:135], v[130:131]
	s_nop 0
	v_add_f32_e32 v130, v130, v131
	v_mov_b32_e32 v131, v130
	s_nop 1
	v_permlane16_swap_b32_e32 v130, v131
	s_waitcnt lgkmcnt(0)
	v_add_f32_e32 v130, v130, v131
	v_mov_b32_e32 v131, v130
	s_nop 1
	v_permlane32_swap_b32_e32 v130, v131
	s_waitcnt lgkmcnt(0)
	v_add_f32_e32 v130, v130, v131
	v_fmamk_f32 v132, v130, 0xbc800000, v17
	v_fmamk_f32 v134, v130, 0xbc800000, v15
	v_fmamk_f32 v131, v130, 0xbc800000, v16
	v_fmamk_f32 v133, v130, 0xbc800000, v14
	v_mul_f32_e32 v134, v134, v134
	v_mul_f32_e32 v132, v132, v132
	v_fmac_f32_e32 v134, v133, v133
	v_fmac_f32_e32 v132, v131, v131
	v_fmamk_f32 v133, v130, 0xbc800000, v13
	v_fmamk_f32 v135, v130, 0xbc800000, v11
	v_add_f32_e32 v131, v134, v132
	v_fmamk_f32 v132, v130, 0xbc800000, v12
	v_fmamk_f32 v134, v130, 0xbc800000, v10
	v_mul_f32_e32 v135, v135, v135
	v_mul_f32_e32 v133, v133, v133
	v_fmac_f32_e32 v135, v134, v134
	v_fmac_f32_e32 v133, v132, v132
	v_add_f32_e32 v132, v135, v133
	v_fmamk_f32 v133, v130, 0xbc800000, v9
	v_fmamk_f32 v135, v130, 0xbc800000, v7
	v_add_f32_e32 v131, v131, v132
	v_fmamk_f32 v132, v130, 0xbc800000, v8
	v_fmamk_f32 v134, v130, 0xbc800000, v6
	v_mul_f32_e32 v135, v135, v135
	v_mul_f32_e32 v133, v133, v133
	v_fmac_f32_e32 v135, v134, v134
	v_fmac_f32_e32 v133, v132, v132
	v_add_f32_e32 v132, v135, v133
	v_fmamk_f32 v133, v130, 0xbc800000, v5
	v_fmamk_f32 v135, v130, 0xbc800000, v3
	v_add_f32_e32 v131, v132, v131
	v_fmamk_f32 v132, v130, 0xbc800000, v4
	v_fmamk_f32 v134, v130, 0xbc800000, v2
	v_mul_f32_e32 v135, v135, v135
	v_mul_f32_e32 v133, v133, v133
	v_fmac_f32_e32 v135, v134, v134
	v_fmac_f32_e32 v133, v132, v132
	v_add_f32_e32 v132, v135, v133
	v_add_f32_e32 v131, v132, v131
	v_mov_b32_e32 v132, v131
	s_nop 1
	v_permlane16_swap_b32_e32 v131, v132
	s_waitcnt lgkmcnt(0)
	v_add_f32_e32 v131, v131, v132
	v_mov_b32_e32 v132, v131
	s_nop 1
	v_permlane32_swap_b32_e32 v131, v132
	s_and_saveexec_b64 s[0:1], s[6:7]
	s_cbranch_execz .LBB0_912
	s_lshl_b32 s6, s27, 11
	s_add_i32 s28, s28, s6
	v_mul_f32_e32 v130, 0x3c800000, v130
	s_waitcnt lgkmcnt(0)
	v_add_f32_e32 v131, v131, v132
	v_lshl_add_u32 v132, v170, 5, s28
	ds_write_b64 v132, v[130:131] offset:5632

.LBB0_1451:
	v_mov_b32_e32 v130, v127
	v_mov_b32_e32 v131, v128
	v_mov_b32_e32 v132, v126
	v_mov_b32_e32 v133, v129
	v_pk_add_f32 v[130:131], v[130:131], v[132:133]
	v_mov_b32_e32 v132, v123
	v_mov_b32_e32 v133, v124
	v_mov_b32_e32 v134, v122
	v_mov_b32_e32 v135, v125
	v_pk_add_f32 v[132:133], v[132:133], v[134:135]
	v_add_f32_e32 v130, v130, v131
	v_pk_add_f32 v[132:133], v[132:133], v[132:133] op_sel_hi:[0,1]
	v_add_f32_e32 v131, 0, v130
	v_add_f32_e32 v135, v118, v119
	v_add_f32_e32 v137, v120, v121
	v_mov_b32_e32 v134, v114
	v_mov_b32_e32 v136, v115
	v_mov_b32_e32 v132, v116
	v_mov_b32_e32 v130, v117
	v_pk_add_f32 v[134:135], v[134:135], v[136:137]
	v_pk_add_f32 v[130:131], v[132:133], v[130:131]
	v_mov_b32_e32 v133, v126
	v_pk_add_f32 v[130:131], v[134:135], v[130:131]
	v_mov_b32_e32 v134, v127
	v_add_f32_e32 v130, v130, v131
	v_mov_b32_e32 v131, v130
	s_nop 1
	v_permlane16_swap_b32_e32 v130, v131
	v_mov_b32_e32 v135, v123
	s_lshl_b32 s0, s40, 3
	s_add_i32 s17, s0, 0
	s_barrier
	s_waitcnt lgkmcnt(0)
	v_add_f32_e32 v130, v130, v131
	v_mov_b32_e32 v131, v130
	s_nop 1
	v_permlane32_swap_b32_e32 v130, v131
	s_waitcnt lgkmcnt(0)
	v_add_f32_e32 v131, v130, v131
	v_fmamk_f32 v132, v131, 0xbc800000, v129
	v_fmac_f32_e32 v134, 0xbc800000, v131
	v_fmamk_f32 v130, v131, 0xbc800000, v128
	v_fmac_f32_e32 v133, 0xbc800000, v131
	v_mul_f32_e32 v134, v134, v134
	v_mul_f32_e32 v132, v132, v132
	v_fmac_f32_e32 v134, v133, v133
	v_fmac_f32_e32 v132, v130, v130
	v_add_f32_e32 v130, v134, v132
	v_fmamk_f32 v133, v131, 0xbc800000, v125
	v_mov_b32_e32 v134, v122
	v_fmac_f32_e32 v135, 0xbc800000, v131
	v_fmamk_f32 v132, v131, 0xbc800000, v124
	v_fmac_f32_e32 v134, 0xbc800000, v131
	v_mul_f32_e32 v135, v135, v135
	v_mul_f32_e32 v133, v133, v133
	v_fmac_f32_e32 v135, v134, v134
	v_fmac_f32_e32 v133, v132, v132
	v_add_f32_e32 v132, v135, v133
	v_mov_b32_e32 v135, v119
	v_fmamk_f32 v133, v131, 0xbc800000, v121
	v_mov_b32_e32 v134, v118
	v_fmac_f32_e32 v135, 0xbc800000, v131
	v_add_f32_e32 v130, v130, v132
	v_fmamk_f32 v132, v131, 0xbc800000, v120
	v_fmac_f32_e32 v134, 0xbc800000, v131
	v_mul_f32_e32 v135, v135, v135
	v_mul_f32_e32 v133, v133, v133
	v_fmac_f32_e32 v135, v134, v134
	v_fmac_f32_e32 v133, v132, v132
	v_add_f32_e32 v132, v135, v133
	v_mov_b32_e32 v135, v115
	v_fmamk_f32 v133, v131, 0xbc800000, v117
	v_mov_b32_e32 v134, v114
	v_fmac_f32_e32 v135, 0xbc800000, v131
	v_add_f32_e32 v130, v132, v130
	v_fmamk_f32 v132, v131, 0xbc800000, v116
	v_fmac_f32_e32 v134, 0xbc800000, v131
	v_mul_f32_e32 v135, v135, v135
	v_mul_f32_e32 v133, v133, v133
	v_fmac_f32_e32 v135, v134, v134
	v_fmac_f32_e32 v133, v132, v132
	v_add_f32_e32 v132, v135, v133
	v_add_f32_e32 v132, v132, v130
	v_mov_b32_e32 v133, v132
	s_nop 1
	v_permlane16_swap_b32_e32 v132, v133
	v_and_b32_e32 v130, 63, v148
	v_cmp_gt_u32_e64 s[6:7], 16, v130
	s_waitcnt lgkmcnt(0)
	v_add_f32_e32 v132, v132, v133
	v_mov_b32_e32 v133, v132
	s_nop 1
	v_permlane32_swap_b32_e32 v132, v133
	s_and_saveexec_b64 s[0:1], s[6:7]
	s_cbranch_execz .LBB0_1453
	s_lshl_b32 s8, s33, 11
	s_add_i32 s8, s17, s8
	v_mul_f32_e32 v134, 0x3c800000, v131
	s_waitcnt lgkmcnt(0)
	v_add_f32_e32 v135, v132, v133
	v_lshl_add_u32 v131, v170, 5, s8
	ds_write_b64 v131, v[134:135]
.LBB0_1453:
	s_or_b64 exec, exec, s[0:1]
	v_mov_b32_e32 v132, v111
	s_waitcnt lgkmcnt(0)
	v_mov_b32_e32 v133, v112
	v_mov_b32_e32 v134, v110
	v_mov_b32_e32 v135, v113
	v_pk_add_f32 v[132:133], v[132:133], v[134:135]
	v_mov_b32_e32 v134, v107
	v_mov_b32_e32 v135, v108
	v_mov_b32_e32 v136, v106
	v_mov_b32_e32 v137, v109
	v_pk_add_f32 v[134:135], v[134:135], v[136:137]
	v_add_f32_e32 v131, v132, v133
	v_pk_add_f32 v[134:135], v[134:135], v[134:135] op_sel_hi:[0,1]
	v_add_f32_e32 v133, 0, v131
	v_add_f32_e32 v137, v102, v103
	v_add_f32_e32 v139, v104, v105
	v_mov_b32_e32 v136, v98
	v_mov_b32_e32 v138, v99
	v_mov_b32_e32 v134, v100
	v_mov_b32_e32 v132, v101
	v_pk_add_f32 v[136:137], v[136:137], v[138:139]
	v_pk_add_f32 v[132:133], v[134:135], v[132:133]
	v_mov_b32_e32 v135, v111
	v_pk_add_f32 v[132:133], v[136:137], v[132:133]
	v_mov_b32_e32 v134, v110
	v_add_f32_e32 v131, v132, v133
	v_mov_b32_e32 v132, v131
	s_nop 1
	v_permlane16_swap_b32_e32 v131, v132
	v_mov_b32_e32 v136, v107
	s_waitcnt lgkmcnt(0)
	v_add_f32_e32 v131, v131, v132
	v_mov_b32_e32 v132, v131
	s_nop 1
	v_permlane32_swap_b32_e32 v131, v132
	s_waitcnt lgkmcnt(0)
	v_add_f32_e32 v131, v131, v132
	v_fmamk_f32 v133, v131, 0xbc800000, v113
	v_fmac_f32_e32 v135, 0xbc800000, v131
	v_fmamk_f32 v132, v131, 0xbc800000, v112
	v_fmac_f32_e32 v134, 0xbc800000, v131
	v_mul_f32_e32 v135, v135, v135
	v_mul_f32_e32 v133, v133, v133
	v_fmac_f32_e32 v135, v134, v134
	v_fmac_f32_e32 v133, v132, v132
	v_add_f32_e32 v132, v135, v133
	v_fmamk_f32 v134, v131, 0xbc800000, v109
	v_mov_b32_e32 v135, v106
	v_fmac_f32_e32 v136, 0xbc800000, v131
	v_fmamk_f32 v133, v131, 0xbc800000, v108
	v_fmac_f32_e32 v135, 0xbc800000, v131
	v_mul_f32_e32 v136, v136, v136
	v_mul_f32_e32 v134, v134, v134
	v_fmac_f32_e32 v136, v135, v135
	v_fmac_f32_e32 v134, v133, v133
	v_add_f32_e32 v133, v136, v134
	v_mov_b32_e32 v136, v103
	v_fmamk_f32 v134, v131, 0xbc800000, v105
	v_mov_b32_e32 v135, v102
	v_fmac_f32_e32 v136, 0xbc800000, v131
	v_add_f32_e32 v132, v132, v133
	v_fmamk_f32 v133, v131, 0xbc800000, v104
	v_fmac_f32_e32 v135, 0xbc800000, v131
	v_mul_f32_e32 v136, v136, v136
	v_mul_f32_e32 v134, v134, v134
	v_fmac_f32_e32 v136, v135, v135
	v_fmac_f32_e32 v134, v133, v133
	v_add_f32_e32 v133, v136, v134
	v_mov_b32_e32 v136, v99
	v_fmamk_f32 v134, v131, 0xbc800000, v101
	v_mov_b32_e32 v135, v98
	v_fmac_f32_e32 v136, 0xbc800000, v131
	v_add_f32_e32 v132, v133, v132
	v_fmamk_f32 v133, v131, 0xbc800000, v100
	v_fmac_f32_e32 v135, 0xbc800000, v131
	v_mul_f32_e32 v136, v136, v136
	v_mul_f32_e32 v134, v134, v134
	v_fmac_f32_e32 v136, v135, v135
	v_fmac_f32_e32 v134, v133, v133
	v_add_f32_e32 v133, v136, v134
	v_add_f32_e32 v132, v133, v132
	v_mov_b32_e32 v133, v132
	s_nop 1
	v_permlane16_swap_b32_e32 v132, v133
	s_waitcnt lgkmcnt(0)
	v_add_f32_e32 v132, v132, v133
	v_mov_b32_e32 v133, v132
	s_nop 1
	v_permlane32_swap_b32_e32 v132, v133
	s_and_saveexec_b64 s[0:1], s[6:7]
	s_cbranch_execz .LBB0_1455
	s_lshl_b32 s8, s33, 11
	s_add_i32 s8, s17, s8
	v_mul_f32_e32 v134, 0x3c800000, v131
	s_waitcnt lgkmcnt(0)
	v_add_f32_e32 v135, v132, v133
	v_lshl_add_u32 v131, v170, 5, s8
	ds_write_b64 v131, v[134:135] offset:512
.LBB0_1455:
	s_or_b64 exec, exec, s[0:1]
	v_mov_b32_e32 v132, v95
	s_waitcnt lgkmcnt(0)
	v_mov_b32_e32 v133, v96
	v_mov_b32_e32 v134, v94
	v_mov_b32_e32 v135, v97
	v_pk_add_f32 v[132:133], v[132:133], v[134:135]
	v_mov_b32_e32 v134, v91
	v_mov_b32_e32 v135, v92
	v_mov_b32_e32 v136, v90
	v_mov_b32_e32 v137, v93
	v_pk_add_f32 v[134:135], v[134:135], v[136:137]
	v_add_f32_e32 v131, v132, v133
	v_pk_add_f32 v[134:135], v[134:135], v[134:135] op_sel_hi:[0,1]
	v_add_f32_e32 v133, 0, v131
	v_add_f32_e32 v137, v86, v87
	v_add_f32_e32 v139, v88, v89
	v_mov_b32_e32 v136, v82
	v_mov_b32_e32 v138, v83
	v_mov_b32_e32 v134, v84
	v_mov_b32_e32 v132, v85
	v_pk_add_f32 v[136:137], v[136:137], v[138:139]
	v_pk_add_f32 v[132:133], v[134:135], v[132:133]
	v_mov_b32_e32 v135, v95
	v_pk_add_f32 v[132:133], v[136:137], v[132:133]
	v_mov_b32_e32 v134, v94
	v_add_f32_e32 v131, v132, v133
	v_mov_b32_e32 v132, v131
	s_nop 1
	v_permlane16_swap_b32_e32 v131, v132
	v_mov_b32_e32 v136, v91
	s_waitcnt lgkmcnt(0)
	v_add_f32_e32 v131, v131, v132
	v_mov_b32_e32 v132, v131
	s_nop 1
	v_permlane32_swap_b32_e32 v131, v132
	s_waitcnt lgkmcnt(0)
	v_add_f32_e32 v131, v131, v132
	v_fmamk_f32 v133, v131, 0xbc800000, v97
	v_fmac_f32_e32 v135, 0xbc800000, v131
	v_fmamk_f32 v132, v131, 0xbc800000, v96
	v_fmac_f32_e32 v134, 0xbc800000, v131
	v_mul_f32_e32 v135, v135, v135
	v_mul_f32_e32 v133, v133, v133
	v_fmac_f32_e32 v135, v134, v134
	v_fmac_f32_e32 v133, v132, v132
	v_add_f32_e32 v132, v135, v133
	v_fmamk_f32 v134, v131, 0xbc800000, v93
	v_mov_b32_e32 v135, v90
	v_fmac_f32_e32 v136, 0xbc800000, v131
	v_fmamk_f32 v133, v131, 0xbc800000, v92
	v_fmac_f32_e32 v135, 0xbc800000, v131
	v_mul_f32_e32 v136, v136, v136
	v_mul_f32_e32 v134, v134, v134
	v_fmac_f32_e32 v136, v135, v135
	v_fmac_f32_e32 v134, v133, v133
	v_add_f32_e32 v133, v136, v134
	v_mov_b32_e32 v136, v87
	v_fmamk_f32 v134, v131, 0xbc800000, v89
	v_mov_b32_e32 v135, v86
	v_fmac_f32_e32 v136, 0xbc800000, v131
	v_add_f32_e32 v132, v132, v133
	v_fmamk_f32 v133, v131, 0xbc800000, v88
	v_fmac_f32_e32 v135, 0xbc800000, v131
	v_mul_f32_e32 v136, v136, v136
	v_mul_f32_e32 v134, v134, v134
	v_fmac_f32_e32 v136, v135, v135
	v_fmac_f32_e32 v134, v133, v133
	v_add_f32_e32 v133, v136, v134
	v_mov_b32_e32 v136, v83
	v_fmamk_f32 v134, v131, 0xbc800000, v85
	v_mov_b32_e32 v135, v82
	v_fmac_f32_e32 v136, 0xbc800000, v131
	v_add_f32_e32 v132, v133, v132
	v_fmamk_f32 v133, v131, 0xbc800000, v84
	v_fmac_f32_e32 v135, 0xbc800000, v131
	v_mul_f32_e32 v136, v136, v136
	v_mul_f32_e32 v134, v134, v134
	v_fmac_f32_e32 v136, v135, v135
	v_fmac_f32_e32 v134, v133, v133
	v_add_f32_e32 v133, v136, v134
	v_add_f32_e32 v132, v133, v132
	v_mov_b32_e32 v133, v132
	s_nop 1
	v_permlane16_swap_b32_e32 v132, v133
	s_waitcnt lgkmcnt(0)
	v_add_f32_e32 v132, v132, v133
	v_mov_b32_e32 v133, v132
	s_nop 1
	v_permlane32_swap_b32_e32 v132, v133
	s_and_saveexec_b64 s[0:1], s[6:7]
	s_cbranch_execz .LBB0_1457
	s_lshl_b32 s8, s33, 11
	s_add_i32 s8, s17, s8
	v_mul_f32_e32 v134, 0x3c800000, v131
	s_waitcnt lgkmcnt(0)
	v_add_f32_e32 v135, v132, v133
	v_lshl_add_u32 v131, v170, 5, s8
	ds_write_b64 v131, v[134:135] offset:1024
.LBB0_1457:
	s_or_b64 exec, exec, s[0:1]
	v_mov_b32_e32 v132, v79
	s_waitcnt lgkmcnt(0)
	v_mov_b32_e32 v133, v80
	v_mov_b32_e32 v134, v78
	v_mov_b32_e32 v135, v81
	v_pk_add_f32 v[132:133], v[132:133], v[134:135]
	v_mov_b32_e32 v134, v75
	v_mov_b32_e32 v135, v76
	v_mov_b32_e32 v136, v74
	v_mov_b32_e32 v137, v77
	v_pk_add_f32 v[134:135], v[134:135], v[136:137]
	v_add_f32_e32 v131, v132, v133
	v_pk_add_f32 v[134:135], v[134:135], v[134:135] op_sel_hi:[0,1]
	v_add_f32_e32 v133, 0, v131
	v_add_f32_e32 v137, v70, v71
	v_add_f32_e32 v139, v72, v73
	v_mov_b32_e32 v136, v66
	v_mov_b32_e32 v138, v67
	v_mov_b32_e32 v134, v68
	v_mov_b32_e32 v132, v69
	v_pk_add_f32 v[136:137], v[136:137], v[138:139]
	v_pk_add_f32 v[132:133], v[134:135], v[132:133]
	v_mov_b32_e32 v135, v79
	v_pk_add_f32 v[132:133], v[136:137], v[132:133]
	v_mov_b32_e32 v134, v78
	v_add_f32_e32 v131, v132, v133
	v_mov_b32_e32 v132, v131
	s_nop 1
	v_permlane16_swap_b32_e32 v131, v132
	v_mov_b32_e32 v136, v75
	s_waitcnt lgkmcnt(0)
	v_add_f32_e32 v131, v131, v132
	v_mov_b32_e32 v132, v131
	s_nop 1
	v_permlane32_swap_b32_e32 v131, v132
	s_waitcnt lgkmcnt(0)
	v_add_f32_e32 v131, v131, v132
	v_fmamk_f32 v133, v131, 0xbc800000, v81
	v_fmac_f32_e32 v135, 0xbc800000, v131
	v_fmamk_f32 v132, v131, 0xbc800000, v80
	v_fmac_f32_e32 v134, 0xbc800000, v131
	v_mul_f32_e32 v135, v135, v135
	v_mul_f32_e32 v133, v133, v133
	v_fmac_f32_e32 v135, v134, v134
	v_fmac_f32_e32 v133, v132, v132
	v_add_f32_e32 v132, v135, v133
	v_fmamk_f32 v134, v131, 0xbc800000, v77
	v_mov_b32_e32 v135, v74
	v_fmac_f32_e32 v136, 0xbc800000, v131
	v_fmamk_f32 v133, v131, 0xbc800000, v76
	v_fmac_f32_e32 v135, 0xbc800000, v131
	v_mul_f32_e32 v136, v136, v136
	v_mul_f32_e32 v134, v134, v134
	v_fmac_f32_e32 v136, v135, v135
	v_fmac_f32_e32 v134, v133, v133
	v_add_f32_e32 v133, v136, v134
	v_mov_b32_e32 v136, v71
	v_fmamk_f32 v134, v131, 0xbc800000, v73
	v_mov_b32_e32 v135, v70
	v_fmac_f32_e32 v136, 0xbc800000, v131
	v_add_f32_e32 v132, v132, v133
	v_fmamk_f32 v133, v131, 0xbc800000, v72
	v_fmac_f32_e32 v135, 0xbc800000, v131
	v_mul_f32_e32 v136, v136, v136
	v_mul_f32_e32 v134, v134, v134
	v_fmac_f32_e32 v136, v135, v135
	v_fmac_f32_e32 v134, v133, v133
	v_add_f32_e32 v133, v136, v134
	v_mov_b32_e32 v136, v67
	v_fmamk_f32 v134, v131, 0xbc800000, v69
	v_mov_b32_e32 v135, v66
	v_fmac_f32_e32 v136, 0xbc800000, v131
	v_add_f32_e32 v132, v133, v132
	v_fmamk_f32 v133, v131, 0xbc800000, v68
	v_fmac_f32_e32 v135, 0xbc800000, v131
	v_mul_f32_e32 v136, v136, v136
	v_mul_f32_e32 v134, v134, v134
	v_fmac_f32_e32 v136, v135, v135
	v_fmac_f32_e32 v134, v133, v133
	v_add_f32_e32 v133, v136, v134
	v_add_f32_e32 v132, v133, v132
	v_mov_b32_e32 v133, v132
	s_nop 1
	v_permlane16_swap_b32_e32 v132, v133
	s_waitcnt lgkmcnt(0)
	v_add_f32_e32 v132, v132, v133
	v_mov_b32_e32 v133, v132
	s_nop 1
	v_permlane32_swap_b32_e32 v132, v133
	s_and_saveexec_b64 s[0:1], s[6:7]
	s_cbranch_execz .LBB0_1459
	s_lshl_b32 s8, s33, 11
	s_add_i32 s8, s17, s8
	v_mul_f32_e32 v134, 0x3c800000, v131
	s_waitcnt lgkmcnt(0)
	v_add_f32_e32 v135, v132, v133
	v_lshl_add_u32 v131, v170, 5, s8
	ds_write_b64 v131, v[134:135] offset:1536
.LBB0_1459:
	s_or_b64 exec, exec, s[0:1]
	v_mov_b32_e32 v132, v63
	s_waitcnt lgkmcnt(0)
	v_mov_b32_e32 v133, v64
	v_mov_b32_e32 v134, v62
	v_mov_b32_e32 v135, v65
	v_pk_add_f32 v[132:133], v[132:133], v[134:135]
	v_mov_b32_e32 v134, v59
	v_mov_b32_e32 v135, v60
	v_mov_b32_e32 v136, v58
	v_mov_b32_e32 v137, v61
	v_pk_add_f32 v[134:135], v[134:135], v[136:137]
	v_add_f32_e32 v131, v132, v133
	v_pk_add_f32 v[134:135], v[134:135], v[134:135] op_sel_hi:[0,1]
	v_add_f32_e32 v133, 0, v131
	v_add_f32_e32 v137, v54, v55
	v_add_f32_e32 v139, v56, v57
	v_mov_b32_e32 v136, v50
	v_mov_b32_e32 v138, v51
	v_mov_b32_e32 v134, v52
	v_mov_b32_e32 v132, v53
	v_pk_add_f32 v[136:137], v[136:137], v[138:139]
	v_pk_add_f32 v[132:133], v[134:135], v[132:133]
	v_mov_b32_e32 v135, v63
	v_pk_add_f32 v[132:133], v[136:137], v[132:133]
	v_mov_b32_e32 v134, v62
	v_add_f32_e32 v131, v132, v133
	v_mov_b32_e32 v132, v131
	s_nop 1
	v_permlane16_swap_b32_e32 v131, v132
	v_mov_b32_e32 v136, v59
	s_waitcnt lgkmcnt(0)
	v_add_f32_e32 v131, v131, v132
	v_mov_b32_e32 v132, v131
	s_nop 1
	v_permlane32_swap_b32_e32 v131, v132
	s_waitcnt lgkmcnt(0)
	v_add_f32_e32 v131, v131, v132
	v_fmamk_f32 v133, v131, 0xbc800000, v65
	v_fmac_f32_e32 v135, 0xbc800000, v131
	v_fmamk_f32 v132, v131, 0xbc800000, v64
	v_fmac_f32_e32 v134, 0xbc800000, v131
	v_mul_f32_e32 v135, v135, v135
	v_mul_f32_e32 v133, v133, v133
	v_fmac_f32_e32 v135, v134, v134
	v_fmac_f32_e32 v133, v132, v132
	v_add_f32_e32 v132, v135, v133
	v_fmamk_f32 v134, v131, 0xbc800000, v61
	v_mov_b32_e32 v135, v58
	v_fmac_f32_e32 v136, 0xbc800000, v131
	v_fmamk_f32 v133, v131, 0xbc800000, v60
	v_fmac_f32_e32 v135, 0xbc800000, v131
	v_mul_f32_e32 v136, v136, v136
	v_mul_f32_e32 v134, v134, v134
	v_fmac_f32_e32 v136, v135, v135
	v_fmac_f32_e32 v134, v133, v133
	v_add_f32_e32 v133, v136, v134
	v_mov_b32_e32 v136, v55
	v_fmamk_f32 v134, v131, 0xbc800000, v57
	v_mov_b32_e32 v135, v54
	v_fmac_f32_e32 v136, 0xbc800000, v131
	v_add_f32_e32 v132, v132, v133
	v_fmamk_f32 v133, v131, 0xbc800000, v56
	v_fmac_f32_e32 v135, 0xbc800000, v131
	v_mul_f32_e32 v136, v136, v136
	v_mul_f32_e32 v134, v134, v134
	v_fmac_f32_e32 v136, v135, v135
	v_fmac_f32_e32 v134, v133, v133
	v_add_f32_e32 v133, v136, v134
	v_mov_b32_e32 v136, v51
	v_fmamk_f32 v134, v131, 0xbc800000, v53
	v_mov_b32_e32 v135, v50
	v_fmac_f32_e32 v136, 0xbc800000, v131
	v_add_f32_e32 v132, v133, v132
	v_fmamk_f32 v133, v131, 0xbc800000, v52
	v_fmac_f32_e32 v135, 0xbc800000, v131
	v_mul_f32_e32 v136, v136, v136
	v_mul_f32_e32 v134, v134, v134
	v_fmac_f32_e32 v136, v135, v135
	v_fmac_f32_e32 v134, v133, v133
	v_add_f32_e32 v133, v136, v134
	v_add_f32_e32 v132, v133, v132
	v_mov_b32_e32 v133, v132
	s_nop 1
	v_permlane16_swap_b32_e32 v132, v133
	s_waitcnt lgkmcnt(0)
	v_add_f32_e32 v132, v132, v133
	v_mov_b32_e32 v133, v132
	s_nop 1
	v_permlane32_swap_b32_e32 v132, v133
	s_and_saveexec_b64 s[0:1], s[6:7]
	s_cbranch_execz .LBB0_1461
	s_lshl_b32 s8, s33, 11
	s_add_i32 s8, s17, s8
	v_mul_f32_e32 v134, 0x3c800000, v131
	s_waitcnt lgkmcnt(0)
	v_add_f32_e32 v135, v132, v133
	v_lshl_add_u32 v131, v170, 5, s8
	ds_write_b64 v131, v[134:135] offset:4096
.LBB0_1461:
	s_or_b64 exec, exec, s[0:1]
	v_mov_b32_e32 v132, v47
	s_waitcnt lgkmcnt(0)
	v_mov_b32_e32 v133, v48
	v_mov_b32_e32 v134, v46
	v_mov_b32_e32 v135, v49
	v_pk_add_f32 v[132:133], v[132:133], v[134:135]
	v_mov_b32_e32 v134, v43
	v_mov_b32_e32 v135, v44
	v_mov_b32_e32 v136, v42
	v_mov_b32_e32 v137, v45
	v_pk_add_f32 v[134:135], v[134:135], v[136:137]
	v_add_f32_e32 v131, v132, v133
	v_pk_add_f32 v[134:135], v[134:135], v[134:135] op_sel_hi:[0,1]
	v_add_f32_e32 v133, 0, v131
	v_add_f32_e32 v137, v38, v39
	v_add_f32_e32 v139, v40, v41
	v_mov_b32_e32 v136, v34
	v_mov_b32_e32 v138, v35
	v_mov_b32_e32 v134, v36
	v_mov_b32_e32 v132, v37
	v_pk_add_f32 v[136:137], v[136:137], v[138:139]
	v_pk_add_f32 v[132:133], v[134:135], v[132:133]
	v_mov_b32_e32 v135, v47
	v_pk_add_f32 v[132:133], v[136:137], v[132:133]
	v_mov_b32_e32 v134, v46
	v_add_f32_e32 v131, v132, v133
	v_mov_b32_e32 v132, v131
	s_nop 1
	v_permlane16_swap_b32_e32 v131, v132
	v_mov_b32_e32 v136, v43
	s_waitcnt lgkmcnt(0)
	v_add_f32_e32 v131, v131, v132
	v_mov_b32_e32 v132, v131
	s_nop 1
	v_permlane32_swap_b32_e32 v131, v132
	s_waitcnt lgkmcnt(0)
	v_add_f32_e32 v131, v131, v132
	v_fmamk_f32 v133, v131, 0xbc800000, v49
	v_fmac_f32_e32 v135, 0xbc800000, v131
	v_fmamk_f32 v132, v131, 0xbc800000, v48
	v_fmac_f32_e32 v134, 0xbc800000, v131
	v_mul_f32_e32 v135, v135, v135
	v_mul_f32_e32 v133, v133, v133
	v_fmac_f32_e32 v135, v134, v134
	v_fmac_f32_e32 v133, v132, v132
	v_add_f32_e32 v132, v135, v133
	v_fmamk_f32 v134, v131, 0xbc800000, v45
	v_mov_b32_e32 v135, v42
	v_fmac_f32_e32 v136, 0xbc800000, v131
	v_fmamk_f32 v133, v131, 0xbc800000, v44
	v_fmac_f32_e32 v135, 0xbc800000, v131
	v_mul_f32_e32 v136, v136, v136
	v_mul_f32_e32 v134, v134, v134
	v_fmac_f32_e32 v136, v135, v135
	v_fmac_f32_e32 v134, v133, v133
	v_add_f32_e32 v133, v136, v134
	v_mov_b32_e32 v136, v39
	v_fmamk_f32 v134, v131, 0xbc800000, v41
	v_mov_b32_e32 v135, v38
	v_fmac_f32_e32 v136, 0xbc800000, v131
	v_add_f32_e32 v132, v132, v133
	v_fmamk_f32 v133, v131, 0xbc800000, v40
	v_fmac_f32_e32 v135, 0xbc800000, v131
	v_mul_f32_e32 v136, v136, v136
	v_mul_f32_e32 v134, v134, v134
	v_fmac_f32_e32 v136, v135, v135
	v_fmac_f32_e32 v134, v133, v133
	v_add_f32_e32 v133, v136, v134
	v_mov_b32_e32 v136, v35
	v_fmamk_f32 v134, v131, 0xbc800000, v37
	v_mov_b32_e32 v135, v34
	v_fmac_f32_e32 v136, 0xbc800000, v131
	v_add_f32_e32 v132, v133, v132
	v_fmamk_f32 v133, v131, 0xbc800000, v36
	v_fmac_f32_e32 v135, 0xbc800000, v131
	v_mul_f32_e32 v136, v136, v136
	v_mul_f32_e32 v134, v134, v134
	v_fmac_f32_e32 v136, v135, v135
	v_fmac_f32_e32 v134, v133, v133
	v_add_f32_e32 v133, v136, v134
	v_add_f32_e32 v132, v133, v132
	v_mov_b32_e32 v133, v132
	s_nop 1
	v_permlane16_swap_b32_e32 v132, v133
	s_waitcnt lgkmcnt(0)
	v_add_f32_e32 v132, v132, v133
	v_mov_b32_e32 v133, v132
	s_nop 1
	v_permlane32_swap_b32_e32 v132, v133
	s_and_saveexec_b64 s[0:1], s[6:7]
	s_cbranch_execz .LBB0_1463
	s_lshl_b32 s8, s33, 11
	s_add_i32 s8, s17, s8
	v_mul_f32_e32 v134, 0x3c800000, v131
	s_waitcnt lgkmcnt(0)
	v_add_f32_e32 v135, v132, v133
	v_lshl_add_u32 v131, v170, 5, s8
	ds_write_b64 v131, v[134:135] offset:4608
.LBB0_1463:
	s_or_b64 exec, exec, s[0:1]
	v_mov_b32_e32 v132, v31
	s_waitcnt lgkmcnt(0)
	v_mov_b32_e32 v133, v32
	v_mov_b32_e32 v134, v30
	v_mov_b32_e32 v135, v33
	v_pk_add_f32 v[132:133], v[132:133], v[134:135]
	v_mov_b32_e32 v134, v27
	v_mov_b32_e32 v135, v28
	v_mov_b32_e32 v136, v26
	v_mov_b32_e32 v137, v29
	v_pk_add_f32 v[134:135], v[134:135], v[136:137]
	v_add_f32_e32 v131, v132, v133
	v_pk_add_f32 v[134:135], v[134:135], v[134:135] op_sel_hi:[0,1]
	v_add_f32_e32 v133, 0, v131
	v_add_f32_e32 v137, v22, v23
	v_add_f32_e32 v139, v24, v25
	v_mov_b32_e32 v136, v18
	v_mov_b32_e32 v138, v19
	v_mov_b32_e32 v134, v20
	v_mov_b32_e32 v132, v21
	v_pk_add_f32 v[136:137], v[136:137], v[138:139]
	v_pk_add_f32 v[132:133], v[134:135], v[132:133]
	v_mov_b32_e32 v135, v31
	v_pk_add_f32 v[132:133], v[136:137], v[132:133]
	v_mov_b32_e32 v134, v30
	v_add_f32_e32 v131, v132, v133
	v_mov_b32_e32 v132, v131
	s_nop 1
	v_permlane16_swap_b32_e32 v131, v132
	v_mov_b32_e32 v136, v27
	s_waitcnt lgkmcnt(0)
	v_add_f32_e32 v131, v131, v132
	v_mov_b32_e32 v132, v131
	s_nop 1
	v_permlane32_swap_b32_e32 v131, v132
	s_waitcnt lgkmcnt(0)
	v_add_f32_e32 v131, v131, v132
	v_fmamk_f32 v133, v131, 0xbc800000, v33
	v_fmac_f32_e32 v135, 0xbc800000, v131
	v_fmamk_f32 v132, v131, 0xbc800000, v32
	v_fmac_f32_e32 v134, 0xbc800000, v131
	v_mul_f32_e32 v135, v135, v135
	v_mul_f32_e32 v133, v133, v133
	v_fmac_f32_e32 v135, v134, v134
	v_fmac_f32_e32 v133, v132, v132
	v_add_f32_e32 v132, v135, v133
	v_fmamk_f32 v134, v131, 0xbc800000, v29
	v_mov_b32_e32 v135, v26
	v_fmac_f32_e32 v136, 0xbc800000, v131
	v_fmamk_f32 v133, v131, 0xbc800000, v28
	v_fmac_f32_e32 v135, 0xbc800000, v131
	v_mul_f32_e32 v136, v136, v136
	v_mul_f32_e32 v134, v134, v134
	v_fmac_f32_e32 v136, v135, v135
	v_fmac_f32_e32 v134, v133, v133
	v_add_f32_e32 v133, v136, v134
	v_mov_b32_e32 v136, v23
	v_fmamk_f32 v134, v131, 0xbc800000, v25
	v_mov_b32_e32 v135, v22
	v_fmac_f32_e32 v136, 0xbc800000, v131
	v_add_f32_e32 v132, v132, v133
	v_fmamk_f32 v133, v131, 0xbc800000, v24
	v_fmac_f32_e32 v135, 0xbc800000, v131
	v_mul_f32_e32 v136, v136, v136
	v_mul_f32_e32 v134, v134, v134
	v_fmac_f32_e32 v136, v135, v135
	v_fmac_f32_e32 v134, v133, v133
	v_add_f32_e32 v133, v136, v134
	v_mov_b32_e32 v136, v19
	v_fmamk_f32 v134, v131, 0xbc800000, v21
	v_mov_b32_e32 v135, v18
	v_fmac_f32_e32 v136, 0xbc800000, v131
	v_add_f32_e32 v132, v133, v132
	v_fmamk_f32 v133, v131, 0xbc800000, v20
	v_fmac_f32_e32 v135, 0xbc800000, v131
	v_mul_f32_e32 v136, v136, v136
	v_mul_f32_e32 v134, v134, v134
	v_fmac_f32_e32 v136, v135, v135
	v_fmac_f32_e32 v134, v133, v133
	v_add_f32_e32 v133, v136, v134
	v_add_f32_e32 v132, v133, v132
	v_mov_b32_e32 v133, v132
	s_nop 1
	v_permlane16_swap_b32_e32 v132, v133
	s_waitcnt lgkmcnt(0)
	v_add_f32_e32 v132, v132, v133
	v_mov_b32_e32 v133, v132
	s_nop 1
	v_permlane32_swap_b32_e32 v132, v133
	s_and_saveexec_b64 s[0:1], s[6:7]
	s_cbranch_execz .LBB0_1465
	s_lshl_b32 s8, s33, 11
	s_add_i32 s8, s17, s8
	v_mul_f32_e32 v134, 0x3c800000, v131
	s_waitcnt lgkmcnt(0)
	v_add_f32_e32 v135, v132, v133
	v_lshl_add_u32 v131, v170, 5, s8
	ds_write_b64 v131, v[134:135] offset:5120
.LBB0_1465:
	s_or_b64 exec, exec, s[0:1]
	v_mov_b32_e32 v132, v15
	s_waitcnt lgkmcnt(0)
	v_mov_b32_e32 v133, v16
	v_mov_b32_e32 v134, v14
	v_mov_b32_e32 v135, v17
	v_pk_add_f32 v[132:133], v[132:133], v[134:135]
	v_mov_b32_e32 v134, v11
	v_mov_b32_e32 v135, v12
	v_mov_b32_e32 v136, v10
	v_mov_b32_e32 v137, v13
	v_pk_add_f32 v[134:135], v[134:135], v[136:137]
	v_add_f32_e32 v131, v132, v133
	v_pk_add_f32 v[134:135], v[134:135], v[134:135] op_sel_hi:[0,1]
	v_add_f32_e32 v133, 0, v131
	v_add_f32_e32 v137, v6, v7
	v_add_f32_e32 v139, v8, v9
	v_mov_b32_e32 v136, v2
	v_mov_b32_e32 v138, v3
	v_mov_b32_e32 v134, v4
	v_mov_b32_e32 v132, v5
	v_pk_add_f32 v[136:137], v[136:137], v[138:139]
	v_pk_add_f32 v[132:133], v[134:135], v[132:133]
	v_mov_b32_e32 v135, v15
	v_pk_add_f32 v[132:133], v[136:137], v[132:133]
	v_mov_b32_e32 v134, v14
	v_add_f32_e32 v131, v132, v133
	v_mov_b32_e32 v132, v131
	s_nop 1
	v_permlane16_swap_b32_e32 v131, v132
	v_mov_b32_e32 v136, v11
	s_waitcnt lgkmcnt(0)
	v_add_f32_e32 v131, v131, v132
	v_mov_b32_e32 v132, v131
	s_nop 1
	v_permlane32_swap_b32_e32 v131, v132
	s_waitcnt lgkmcnt(0)
	v_add_f32_e32 v131, v131, v132
	v_fmamk_f32 v133, v131, 0xbc800000, v17
	v_fmac_f32_e32 v135, 0xbc800000, v131
	v_fmamk_f32 v132, v131, 0xbc800000, v16
	v_fmac_f32_e32 v134, 0xbc800000, v131
	v_mul_f32_e32 v135, v135, v135
	v_mul_f32_e32 v133, v133, v133
	v_fmac_f32_e32 v135, v134, v134
	v_fmac_f32_e32 v133, v132, v132
	v_add_f32_e32 v132, v135, v133
	v_fmamk_f32 v134, v131, 0xbc800000, v13
	v_mov_b32_e32 v135, v10
	v_fmac_f32_e32 v136, 0xbc800000, v131
	v_fmamk_f32 v133, v131, 0xbc800000, v12
	v_fmac_f32_e32 v135, 0xbc800000, v131
	v_mul_f32_e32 v136, v136, v136
	v_mul_f32_e32 v134, v134, v134
	v_fmac_f32_e32 v136, v135, v135
	v_fmac_f32_e32 v134, v133, v133
	v_add_f32_e32 v133, v136, v134
	v_mov_b32_e32 v136, v7
	v_fmamk_f32 v134, v131, 0xbc800000, v9
	v_mov_b32_e32 v135, v6
	v_fmac_f32_e32 v136, 0xbc800000, v131
	v_add_f32_e32 v132, v132, v133
	v_fmamk_f32 v133, v131, 0xbc800000, v8
	v_fmac_f32_e32 v135, 0xbc800000, v131
	v_mul_f32_e32 v136, v136, v136
	v_mul_f32_e32 v134, v134, v134
	v_fmac_f32_e32 v136, v135, v135
	v_fmac_f32_e32 v134, v133, v133
	v_add_f32_e32 v133, v136, v134
	v_mov_b32_e32 v136, v3
	v_fmamk_f32 v134, v131, 0xbc800000, v5
	v_mov_b32_e32 v135, v2
	v_fmac_f32_e32 v136, 0xbc800000, v131
	v_add_f32_e32 v132, v133, v132
	v_fmamk_f32 v133, v131, 0xbc800000, v4
	v_fmac_f32_e32 v135, 0xbc800000, v131
	v_mul_f32_e32 v136, v136, v136
	v_mul_f32_e32 v134, v134, v134
	v_fmac_f32_e32 v136, v135, v135
	v_fmac_f32_e32 v134, v133, v133
	v_add_f32_e32 v133, v136, v134
	v_add_f32_e32 v132, v133, v132
	v_mov_b32_e32 v133, v132
	s_nop 1
	v_permlane16_swap_b32_e32 v132, v133
	s_waitcnt lgkmcnt(0)
	v_add_f32_e32 v132, v132, v133
	v_mov_b32_e32 v133, v132
	s_nop 1
	v_permlane32_swap_b32_e32 v132, v133
	s_and_saveexec_b64 s[0:1], s[6:7]
	s_cbranch_execz .LBB0_1467
	s_lshl_b32 s8, s33, 11
	s_add_i32 s8, s17, s8
	v_mul_f32_e32 v134, 0x3c800000, v131
	s_waitcnt lgkmcnt(0)
	v_add_f32_e32 v135, v132, v133
	v_lshl_add_u32 v131, v170, 5, s8
	ds_write_b64 v131, v[134:135] offset:5632

.LBB0_1491:
	s_or_b64 exec, exec, s[22:23]
	s_lshl_b32 s0, s40, 5
	s_lshl_b32 s1, s18, 8
	s_or_b32 s0, s1, s0
	v_lshrrev_b32_e32 v130, 2, v148
	v_and_or_b32 v162, v130, 12, s0
	v_add_u32_e32 v150, s19, v152
	s_lshl_b32 s0, s16, 5
	v_ashrrev_i32_e32 v151, 31, v150
	s_and_b32 s0, s0, 0xfffffc00
	v_ashrrev_i32_e32 v163, 31, v162
	v_lshlrev_b64 v[130:131], 11, v[150:151]
	v_add_u32_e32 v132, s0, v162
	v_lshl_add_u64 v[130:131], s[94:95], 0, v[130:131]
	v_lshlrev_b64 v[168:169], 1, v[162:163]
	s_waitcnt lgkmcnt(0)
	v_ashrrev_i32_e32 v133, 31, v132
	s_waitcnt lgkmcnt(0)
	s_barrier
	v_lshl_add_u64 v[130:131], v[130:131], 0, v[168:169]
	v_lshl_add_u64 v[148:149], v[132:133], 2, s[34:35]
	s_mov_b32 s19, 0x10c000
	global_load_dwordx2 v[154:155], v[130:131], off
	global_load_dwordx2 v[156:157], v[130:131], off offset:32
	global_load_dwordx2 v[158:159], v[130:131], off offset:256
	global_load_dwordx2 v[160:161], v[130:131], off offset:288
	v_add_co_u32_e32 v130, vcc, s19, v148
	s_mov_b64 s[0:1], 0x10c000
	s_nop 0
	v_addc_co_u32_e32 v131, vcc, 0, v149, vcc
	global_load_dwordx4 v[138:141], v[130:131], off
	v_lshl_add_u64 v[130:131], v[148:149], 0, s[0:1]
	global_load_dwordx4 v[142:145], v[130:131], off offset:64
	global_load_dwordx4 v[134:137], v[130:131], off offset:512
	s_nop 0
	global_load_dwordx4 v[130:133], v[130:131], off offset:576
	v_lshl_add_u32 v183, v152, 3, 0
	ds_read_b64 v[164:165], v183 offset:8192
	v_add_u32_e32 v152, 16, v150
	v_ashrrev_i32_e32 v153, 31, v152
	v_lshlrev_b64 v[166:167], 11, v[152:153]
	v_lshl_add_u64 v[166:167], s[94:95], 0, v[166:167]
	s_waitcnt lgkmcnt(0)
	v_pk_mul_f32 v[128:129], v[128:129], v[164:165] op_sel:[0,1]
	v_pk_mul_f32 v[126:127], v[126:127], v[164:165] op_sel:[0,1]
	v_pk_mul_f32 v[122:123], v[122:123], v[164:165] op_sel:[0,1]
	v_pk_mul_f32 v[124:125], v[124:125], v[164:165] op_sel:[0,1]
	v_pk_mul_f32 v[172:173], v[118:119], v[164:165] op_sel:[0,1]
	v_pk_mul_f32 v[174:175], v[120:121], v[164:165] op_sel:[0,1]
	v_pk_mul_f32 v[114:115], v[114:115], v[164:165] op_sel:[0,1]
	v_pk_mul_f32 v[116:117], v[116:117], v[164:165] op_sel:[0,1]
	v_lshl_add_u64 v[166:167], v[166:167], 0, v[168:169]
	s_waitcnt vmcnt(0)
	v_lshlrev_b32_e32 v118, 16, v154
	v_and_b32_e32 v119, 0xffff0000, v154
	v_lshlrev_b32_e32 v120, 16, v155
	v_and_b32_e32 v121, 0xffff0000, v155
	v_lshlrev_b32_e32 v154, 16, v156
	v_and_b32_e32 v155, 0xffff0000, v156
	v_lshlrev_b32_e32 v156, 16, v157
	v_and_b32_e32 v157, 0xffff0000, v157
	v_lshlrev_b32_e32 v164, 16, v158
	v_and_b32_e32 v165, 0xffff0000, v158
	v_lshlrev_b32_e32 v158, 16, v159
	v_and_b32_e32 v159, 0xffff0000, v159
	v_lshlrev_b32_e32 v176, 16, v160
	v_and_b32_e32 v177, 0xffff0000, v160
	v_lshlrev_b32_e32 v160, 16, v161
	v_and_b32_e32 v161, 0xffff0000, v161
	v_pk_fma_f32 v[118:119], v[138:139], v[126:127], v[118:119]
	v_pk_fma_f32 v[120:121], v[140:141], v[128:129], v[120:121]
	v_pk_fma_f32 v[124:125], v[144:145], v[124:125], v[156:157]
	v_pk_fma_f32 v[122:123], v[142:143], v[122:123], v[154:155]
	v_pk_fma_f32 v[128:129], v[136:137], v[174:175], v[158:159]
	v_pk_fma_f32 v[126:127], v[134:135], v[172:173], v[164:165]
	v_pk_fma_f32 v[116:117], v[132:133], v[116:117], v[160:161]
	v_pk_fma_f32 v[114:115], v[130:131], v[114:115], v[176:177]
	v_add_u32_e32 v154, 32, v150
	global_load_dwordx2 v[156:157], v[166:167], off
	global_load_dwordx2 v[158:159], v[166:167], off offset:32
	global_load_dwordx2 v[160:161], v[166:167], off offset:256
	global_load_dwordx2 v[164:165], v[166:167], off offset:288
	ds_read_b64 v[166:167], v183 offset:8320
	v_ashrrev_i32_e32 v155, 31, v154
	v_lshlrev_b64 v[172:173], 11, v[154:155]
	v_lshl_add_u64 v[172:173], s[94:95], 0, v[172:173]
	v_lshl_add_u64 v[172:173], v[172:173], 0, v[168:169]
	s_waitcnt lgkmcnt(0)
	v_pk_mul_f32 v[110:111], v[110:111], v[166:167] op_sel:[0,1]
	v_pk_mul_f32 v[112:113], v[112:113], v[166:167] op_sel:[0,1]
	v_pk_mul_f32 v[106:107], v[106:107], v[166:167] op_sel:[0,1]
	v_pk_mul_f32 v[108:109], v[108:109], v[166:167] op_sel:[0,1]
	v_pk_mul_f32 v[102:103], v[102:103], v[166:167] op_sel:[0,1]
	v_pk_mul_f32 v[104:105], v[104:105], v[166:167] op_sel:[0,1]
	v_pk_mul_f32 v[98:99], v[98:99], v[166:167] op_sel:[0,1]
	v_pk_mul_f32 v[100:101], v[100:101], v[166:167] op_sel:[0,1]
	v_add_f32_e32 v193, v126, v127
	v_add_f32_e32 v197, v128, v129
	v_mov_b32_e32 v192, v114
	v_mov_b32_e32 v196, v115
	v_mov_b32_e32 v198, v117
	s_waitcnt vmcnt(3)
	v_lshlrev_b32_e32 v166, 16, v156
	v_and_b32_e32 v167, 0xffff0000, v156
	v_lshlrev_b32_e32 v156, 16, v157
	v_and_b32_e32 v157, 0xffff0000, v157
	s_waitcnt vmcnt(2)
	v_lshlrev_b32_e32 v174, 16, v158
	v_and_b32_e32 v175, 0xffff0000, v158
	v_lshlrev_b32_e32 v158, 16, v159
	v_and_b32_e32 v159, 0xffff0000, v159
	s_waitcnt vmcnt(1)
	v_lshlrev_b32_e32 v176, 16, v160
	v_and_b32_e32 v177, 0xffff0000, v160
	v_lshlrev_b32_e32 v160, 16, v161
	v_and_b32_e32 v161, 0xffff0000, v161
	s_waitcnt vmcnt(0)
	v_lshlrev_b32_e32 v178, 16, v164
	v_and_b32_e32 v179, 0xffff0000, v164
	v_lshlrev_b32_e32 v164, 16, v165
	v_and_b32_e32 v165, 0xffff0000, v165
	v_pk_fma_f32 v[112:113], v[140:141], v[112:113], v[156:157]
	v_pk_fma_f32 v[110:111], v[138:139], v[110:111], v[166:167]
	v_pk_fma_f32 v[108:109], v[144:145], v[108:109], v[158:159]
	v_pk_fma_f32 v[106:107], v[142:143], v[106:107], v[174:175]
	v_pk_fma_f32 v[104:105], v[136:137], v[104:105], v[160:161]
	v_pk_fma_f32 v[102:103], v[134:135], v[102:103], v[176:177]
	v_pk_fma_f32 v[100:101], v[132:133], v[100:101], v[164:165]
	v_pk_fma_f32 v[98:99], v[130:131], v[98:99], v[178:179]
	v_add_u32_e32 v156, 48, v150
	global_load_dwordx2 v[158:159], v[172:173], off
	global_load_dwordx2 v[160:161], v[172:173], off offset:32
	global_load_dwordx2 v[164:165], v[172:173], off offset:256
	global_load_dwordx2 v[166:167], v[172:173], off offset:288
	ds_read_b64 v[172:173], v183 offset:8448
	v_ashrrev_i32_e32 v157, 31, v156
	v_lshlrev_b64 v[174:175], 11, v[156:157]
	v_lshl_add_u64 v[174:175], s[94:95], 0, v[174:175]
	v_lshl_add_u64 v[174:175], v[174:175], 0, v[168:169]
	s_waitcnt lgkmcnt(0)
	v_pk_mul_f32 v[94:95], v[94:95], v[172:173] op_sel:[0,1]
	v_pk_mul_f32 v[96:97], v[96:97], v[172:173] op_sel:[0,1]
	v_pk_mul_f32 v[90:91], v[90:91], v[172:173] op_sel:[0,1]
	v_pk_mul_f32 v[92:93], v[92:93], v[172:173] op_sel:[0,1]
	v_pk_mul_f32 v[86:87], v[86:87], v[172:173] op_sel:[0,1]
	v_pk_mul_f32 v[88:89], v[88:89], v[172:173] op_sel:[0,1]
	v_pk_mul_f32 v[82:83], v[82:83], v[172:173] op_sel:[0,1]
	v_pk_mul_f32 v[84:85], v[84:85], v[172:173] op_sel:[0,1]
	s_waitcnt vmcnt(3)
	v_lshlrev_b32_e32 v172, 16, v158
	v_and_b32_e32 v173, 0xffff0000, v158
	v_lshlrev_b32_e32 v158, 16, v159
	v_and_b32_e32 v159, 0xffff0000, v159
	s_waitcnt vmcnt(2)
	v_lshlrev_b32_e32 v176, 16, v160
	v_and_b32_e32 v177, 0xffff0000, v160
	v_lshlrev_b32_e32 v160, 16, v161
	v_and_b32_e32 v161, 0xffff0000, v161
	s_waitcnt vmcnt(1)
	v_lshlrev_b32_e32 v178, 16, v164
	v_and_b32_e32 v179, 0xffff0000, v164
	v_lshlrev_b32_e32 v164, 16, v165
	v_and_b32_e32 v165, 0xffff0000, v165
	s_waitcnt vmcnt(0)
	v_lshlrev_b32_e32 v180, 16, v166
	v_and_b32_e32 v181, 0xffff0000, v166
	v_lshlrev_b32_e32 v166, 16, v167
	v_and_b32_e32 v167, 0xffff0000, v167
	v_pk_fma_f32 v[96:97], v[140:141], v[96:97], v[158:159]
	v_pk_fma_f32 v[94:95], v[138:139], v[94:95], v[172:173]
	v_pk_fma_f32 v[92:93], v[144:145], v[92:93], v[160:161]
	v_pk_fma_f32 v[90:91], v[142:143], v[90:91], v[176:177]
	v_pk_fma_f32 v[88:89], v[136:137], v[88:89], v[164:165]
	v_pk_fma_f32 v[86:87], v[134:135], v[86:87], v[178:179]
	v_pk_fma_f32 v[84:85], v[132:133], v[84:85], v[166:167]
	v_pk_fma_f32 v[82:83], v[130:131], v[82:83], v[180:181]
	v_add_u32_e32 v158, 0x80, v150
	global_load_dwordx2 v[160:161], v[174:175], off
	global_load_dwordx2 v[164:165], v[174:175], off offset:32
	global_load_dwordx2 v[166:167], v[174:175], off offset:256
	global_load_dwordx2 v[172:173], v[174:175], off offset:288
	ds_read_b64 v[174:175], v183 offset:8576
	v_ashrrev_i32_e32 v159, 31, v158
	v_lshlrev_b64 v[176:177], 11, v[158:159]
	v_lshl_add_u64 v[176:177], s[94:95], 0, v[176:177]
	v_lshl_add_u64 v[176:177], v[176:177], 0, v[168:169]
	s_waitcnt lgkmcnt(0)
	v_pk_mul_f32 v[78:79], v[78:79], v[174:175] op_sel:[0,1]
	v_pk_mul_f32 v[80:81], v[80:81], v[174:175] op_sel:[0,1]
	v_pk_mul_f32 v[74:75], v[74:75], v[174:175] op_sel:[0,1]
	v_pk_mul_f32 v[76:77], v[76:77], v[174:175] op_sel:[0,1]
	v_pk_mul_f32 v[70:71], v[70:71], v[174:175] op_sel:[0,1]
	v_pk_mul_f32 v[72:73], v[72:73], v[174:175] op_sel:[0,1]
	v_pk_mul_f32 v[66:67], v[66:67], v[174:175] op_sel:[0,1]
	v_pk_mul_f32 v[68:69], v[68:69], v[174:175] op_sel:[0,1]
	s_waitcnt vmcnt(3)
	v_lshlrev_b32_e32 v174, 16, v160
	v_and_b32_e32 v175, 0xffff0000, v160
	v_lshlrev_b32_e32 v160, 16, v161
	v_and_b32_e32 v161, 0xffff0000, v161
	s_waitcnt vmcnt(2)
	v_lshlrev_b32_e32 v178, 16, v164
	v_and_b32_e32 v179, 0xffff0000, v164
	v_lshlrev_b32_e32 v164, 16, v165
	v_and_b32_e32 v165, 0xffff0000, v165
	s_waitcnt vmcnt(1)
	v_lshlrev_b32_e32 v180, 16, v166
	v_and_b32_e32 v181, 0xffff0000, v166
	v_lshlrev_b32_e32 v166, 16, v167
	v_and_b32_e32 v167, 0xffff0000, v167
	s_waitcnt vmcnt(0)
	v_lshlrev_b32_e32 v186, 16, v172
	v_and_b32_e32 v187, 0xffff0000, v172
	v_lshlrev_b32_e32 v172, 16, v173
	v_and_b32_e32 v173, 0xffff0000, v173
	v_pk_fma_f32 v[80:81], v[140:141], v[80:81], v[160:161]
	v_pk_fma_f32 v[78:79], v[138:139], v[78:79], v[174:175]
	v_pk_fma_f32 v[76:77], v[144:145], v[76:77], v[164:165]
	v_pk_fma_f32 v[74:75], v[142:143], v[74:75], v[178:179]
	v_pk_fma_f32 v[72:73], v[136:137], v[72:73], v[166:167]
	v_pk_fma_f32 v[70:71], v[134:135], v[70:71], v[180:181]
	v_pk_fma_f32 v[68:69], v[132:133], v[68:69], v[172:173]
	v_pk_fma_f32 v[66:67], v[130:131], v[66:67], v[186:187]
	v_add_u32_e32 v160, 0x90, v150
	global_load_dwordx2 v[164:165], v[176:177], off
	global_load_dwordx2 v[166:167], v[176:177], off offset:32
	global_load_dwordx2 v[172:173], v[176:177], off offset:256
	global_load_dwordx2 v[174:175], v[176:177], off offset:288
	ds_read_b64 v[176:177], v183 offset:9216
	v_ashrrev_i32_e32 v161, 31, v160
	v_lshlrev_b64 v[178:179], 11, v[160:161]
	v_lshl_add_u64 v[178:179], s[94:95], 0, v[178:179]
	v_lshl_add_u64 v[178:179], v[178:179], 0, v[168:169]
	s_waitcnt lgkmcnt(0)
	v_pk_mul_f32 v[62:63], v[62:63], v[176:177] op_sel:[0,1]
	v_pk_mul_f32 v[64:65], v[64:65], v[176:177] op_sel:[0,1]
	v_pk_mul_f32 v[58:59], v[58:59], v[176:177] op_sel:[0,1]
	v_pk_mul_f32 v[60:61], v[60:61], v[176:177] op_sel:[0,1]
	v_pk_mul_f32 v[54:55], v[54:55], v[176:177] op_sel:[0,1]
	v_pk_mul_f32 v[56:57], v[56:57], v[176:177] op_sel:[0,1]
	v_pk_mul_f32 v[50:51], v[50:51], v[176:177] op_sel:[0,1]
	v_pk_mul_f32 v[52:53], v[52:53], v[176:177] op_sel:[0,1]
	s_waitcnt vmcnt(3)
	v_lshlrev_b32_e32 v176, 16, v164
	v_and_b32_e32 v177, 0xffff0000, v164
	v_lshlrev_b32_e32 v164, 16, v165
	v_and_b32_e32 v165, 0xffff0000, v165
	s_waitcnt vmcnt(2)
	v_lshlrev_b32_e32 v180, 16, v166
	v_and_b32_e32 v181, 0xffff0000, v166
	v_lshlrev_b32_e32 v166, 16, v167
	v_and_b32_e32 v167, 0xffff0000, v167
	s_waitcnt vmcnt(1)
	v_lshlrev_b32_e32 v186, 16, v172
	v_and_b32_e32 v187, 0xffff0000, v172
	v_lshlrev_b32_e32 v172, 16, v173
	v_and_b32_e32 v173, 0xffff0000, v173
	s_waitcnt vmcnt(0)
	v_lshlrev_b32_e32 v188, 16, v174
	v_and_b32_e32 v189, 0xffff0000, v174
	v_lshlrev_b32_e32 v174, 16, v175
	v_and_b32_e32 v175, 0xffff0000, v175
	v_pk_fma_f32 v[64:65], v[140:141], v[64:65], v[164:165]
	v_pk_fma_f32 v[62:63], v[138:139], v[62:63], v[176:177]
	v_pk_fma_f32 v[60:61], v[144:145], v[60:61], v[166:167]
	v_pk_fma_f32 v[58:59], v[142:143], v[58:59], v[180:181]
	v_pk_fma_f32 v[56:57], v[136:137], v[56:57], v[172:173]
	v_pk_fma_f32 v[54:55], v[134:135], v[54:55], v[186:187]
	v_pk_fma_f32 v[52:53], v[132:133], v[52:53], v[174:175]
	v_pk_fma_f32 v[50:51], v[130:131], v[50:51], v[188:189]
	v_add_u32_e32 v164, 0xa0, v150
	global_load_dwordx2 v[166:167], v[178:179], off
	global_load_dwordx2 v[172:173], v[178:179], off offset:32
	global_load_dwordx2 v[174:175], v[178:179], off offset:256
	global_load_dwordx2 v[176:177], v[178:179], off offset:288
	ds_read_b64 v[178:179], v183 offset:9344
	v_ashrrev_i32_e32 v165, 31, v164
	v_lshlrev_b64 v[180:181], 11, v[164:165]
	v_lshl_add_u64 v[180:181], s[94:95], 0, v[180:181]
	v_lshl_add_u64 v[180:181], v[180:181], 0, v[168:169]
	s_waitcnt lgkmcnt(0)
	v_pk_mul_f32 v[46:47], v[46:47], v[178:179] op_sel:[0,1]
	v_pk_mul_f32 v[48:49], v[48:49], v[178:179] op_sel:[0,1]
	v_pk_mul_f32 v[42:43], v[42:43], v[178:179] op_sel:[0,1]
	v_pk_mul_f32 v[44:45], v[44:45], v[178:179] op_sel:[0,1]
	v_pk_mul_f32 v[38:39], v[38:39], v[178:179] op_sel:[0,1]
	v_pk_mul_f32 v[40:41], v[40:41], v[178:179] op_sel:[0,1]
	v_pk_mul_f32 v[34:35], v[34:35], v[178:179] op_sel:[0,1]
	v_pk_mul_f32 v[36:37], v[36:37], v[178:179] op_sel:[0,1]
	s_waitcnt vmcnt(3)
	v_lshlrev_b32_e32 v178, 16, v166
	v_and_b32_e32 v179, 0xffff0000, v166
	v_lshlrev_b32_e32 v166, 16, v167
	v_and_b32_e32 v167, 0xffff0000, v167
	s_waitcnt vmcnt(2)
	v_lshlrev_b32_e32 v186, 16, v172
	v_and_b32_e32 v187, 0xffff0000, v172
	v_lshlrev_b32_e32 v172, 16, v173
	v_and_b32_e32 v173, 0xffff0000, v173
	s_waitcnt vmcnt(1)
	v_lshlrev_b32_e32 v188, 16, v174
	v_and_b32_e32 v189, 0xffff0000, v174
	v_lshlrev_b32_e32 v174, 16, v175
	v_and_b32_e32 v175, 0xffff0000, v175
	s_waitcnt vmcnt(0)
	v_lshlrev_b32_e32 v190, 16, v176
	v_and_b32_e32 v191, 0xffff0000, v176
	v_lshlrev_b32_e32 v176, 16, v177
	v_and_b32_e32 v177, 0xffff0000, v177
	v_pk_fma_f32 v[48:49], v[140:141], v[48:49], v[166:167]
	v_pk_fma_f32 v[46:47], v[138:139], v[46:47], v[178:179]
	v_pk_fma_f32 v[44:45], v[144:145], v[44:45], v[172:173]
	v_pk_fma_f32 v[42:43], v[142:143], v[42:43], v[186:187]
	v_pk_fma_f32 v[40:41], v[136:137], v[40:41], v[174:175]
	v_pk_fma_f32 v[38:39], v[134:135], v[38:39], v[188:189]
	v_pk_fma_f32 v[36:37], v[132:133], v[36:37], v[176:177]
	v_pk_fma_f32 v[34:35], v[130:131], v[34:35], v[190:191]
	v_add_u32_e32 v166, 0xb0, v150
	global_load_dwordx2 v[172:173], v[180:181], off
	global_load_dwordx2 v[174:175], v[180:181], off offset:32
	global_load_dwordx2 v[176:177], v[180:181], off offset:256
	global_load_dwordx2 v[178:179], v[180:181], off offset:288
	ds_read_b64 v[194:195], v183 offset:9472
	v_ashrrev_i32_e32 v167, 31, v166
	v_lshlrev_b64 v[180:181], 11, v[166:167]
	v_lshl_add_u64 v[180:181], s[94:95], 0, v[180:181]
	v_lshl_add_u64 v[168:169], v[180:181], 0, v[168:169]
	v_mov_b32_e32 v180, v119
	v_mov_b32_e32 v181, v120
	v_mov_b32_e32 v186, v118
	v_mov_b32_e32 v187, v121
	v_mov_b32_e32 v188, v123
	v_mov_b32_e32 v189, v124
	v_mov_b32_e32 v190, v122
	v_mov_b32_e32 v191, v125
	s_waitcnt lgkmcnt(0)
	v_pk_mul_f32 v[30:31], v[30:31], v[194:195] op_sel:[0,1]
	v_pk_mul_f32 v[32:33], v[32:33], v[194:195] op_sel:[0,1]
	v_pk_mul_f32 v[26:27], v[26:27], v[194:195] op_sel:[0,1]
	v_pk_mul_f32 v[28:29], v[28:29], v[194:195] op_sel:[0,1]
	v_pk_mul_f32 v[22:23], v[22:23], v[194:195] op_sel:[0,1]
	v_pk_mul_f32 v[24:25], v[24:25], v[194:195] op_sel:[0,1]
	v_pk_mul_f32 v[18:19], v[18:19], v[194:195] op_sel:[0,1]
	v_pk_mul_f32 v[20:21], v[20:21], v[194:195] op_sel:[0,1]
	s_waitcnt vmcnt(3)
	v_lshlrev_b32_e32 v194, 16, v172
	v_and_b32_e32 v195, 0xffff0000, v172
	v_lshlrev_b32_e32 v172, 16, v173
	v_and_b32_e32 v173, 0xffff0000, v173
	s_waitcnt vmcnt(1)
	v_lshlrev_b32_e32 v204, 16, v176
	v_and_b32_e32 v205, 0xffff0000, v176
	v_lshlrev_b32_e32 v176, 16, v177
	v_and_b32_e32 v177, 0xffff0000, v177
	v_pk_fma_f32 v[32:33], v[140:141], v[32:33], v[172:173]
	v_pk_fma_f32 v[24:25], v[136:137], v[24:25], v[176:177]
	v_pk_add_f32 v[172:173], v[180:181], v[186:187]
	v_pk_add_f32 v[176:177], v[188:189], v[190:191]
	v_add_f32_e32 v186, v172, v173
	v_pk_add_f32 v[172:173], v[176:177], v[176:177] op_sel_hi:[0,1]
	v_lshlrev_b32_e32 v200, 16, v174
	v_and_b32_e32 v201, 0xffff0000, v174
	v_lshlrev_b32_e32 v174, 16, v175
	v_and_b32_e32 v175, 0xffff0000, v175
	s_waitcnt vmcnt(0)
	v_lshlrev_b32_e32 v206, 16, v178
	v_and_b32_e32 v207, 0xffff0000, v178
	v_lshlrev_b32_e32 v178, 16, v179
	v_and_b32_e32 v179, 0xffff0000, v179
	v_add_f32_e32 v199, 0, v186
	v_mov_b32_e32 v172, v116
	v_pk_fma_f32 v[30:31], v[138:139], v[30:31], v[194:195]
	v_pk_fma_f32 v[28:29], v[144:145], v[28:29], v[174:175]
	v_pk_fma_f32 v[26:27], v[142:143], v[26:27], v[200:201]
	v_pk_fma_f32 v[22:23], v[134:135], v[22:23], v[204:205]
	v_pk_fma_f32 v[20:21], v[132:133], v[20:21], v[178:179]
	v_pk_fma_f32 v[18:19], v[130:131], v[18:19], v[206:207]
	v_pk_add_f32 v[178:179], v[192:193], v[196:197]
	v_pk_add_f32 v[172:173], v[172:173], v[198:199]
	global_load_dwordx2 v[174:175], v[168:169], off
	global_load_dwordx2 v[180:181], v[168:169], off offset:32
	global_load_dwordx2 v[176:177], v[168:169], off offset:256
	v_pk_add_f32 v[172:173], v[178:179], v[172:173]
	global_load_dwordx2 v[178:179], v[168:169], off offset:288
	v_add_f32_e32 v168, v172, v173
	v_mov_b32_e32 v169, v168
	s_nop 1
	v_permlane16_swap_b32_e32 v168, v169
	s_waitcnt lgkmcnt(0)
	v_add_f32_e32 v168, v168, v169
	v_mov_b32_e32 v169, v168
	s_nop 1
	v_permlane32_swap_b32_e32 v168, v169
	s_waitcnt lgkmcnt(0)
	v_add_f32_e32 v168, v168, v169
	v_fmamk_f32 v172, v168, 0xbc800000, v121
	v_fmamk_f32 v186, v168, 0xbc800000, v119
	v_fmamk_f32 v188, v168, 0xbc800000, v125
	v_fmamk_f32 v190, v168, 0xbc800000, v123
	v_fmamk_f32 v169, v168, 0xbc800000, v120
	v_fmamk_f32 v173, v168, 0xbc800000, v118
	v_fmamk_f32 v187, v168, 0xbc800000, v124
	v_fmamk_f32 v189, v168, 0xbc800000, v122
	v_fmamk_f32 v192, v168, 0xbc800000, v129
	v_fmamk_f32 v194, v168, 0xbc800000, v127
	v_mul_f32_e32 v186, v186, v186
	v_mul_f32_e32 v172, v172, v172
	v_mul_f32_e32 v190, v190, v190
	v_mul_f32_e32 v188, v188, v188
	v_fmamk_f32 v191, v168, 0xbc800000, v128
	v_fmamk_f32 v193, v168, 0xbc800000, v126
	v_fmamk_f32 v196, v168, 0xbc800000, v117
	v_fmamk_f32 v198, v168, 0xbc800000, v115
	v_mul_f32_e32 v194, v194, v194
	v_mul_f32_e32 v192, v192, v192
	v_fmac_f32_e32 v186, v173, v173
	v_fmac_f32_e32 v172, v169, v169
	v_fmac_f32_e32 v190, v189, v189
	v_fmac_f32_e32 v188, v187, v187
	v_fmamk_f32 v195, v168, 0xbc800000, v116
	v_fmamk_f32 v197, v168, 0xbc800000, v114
	v_mul_f32_e32 v198, v198, v198
	v_mul_f32_e32 v196, v196, v196
	v_fmac_f32_e32 v194, v193, v193
	v_fmac_f32_e32 v192, v191, v191
	v_add_f32_e32 v169, v186, v172
	v_add_f32_e32 v172, v190, v188
	v_fmac_f32_e32 v198, v197, v197
	v_fmac_f32_e32 v196, v195, v195
	v_add_f32_e32 v173, v194, v192
	v_add_f32_e32 v169, v169, v172
	v_add_f32_e32 v186, v198, v196
	v_add_f32_e32 v169, v173, v169
	v_add_f32_e32 v169, v186, v169
	v_mov_b32_e32 v172, v169
	s_nop 1
	v_permlane16_swap_b32_e32 v169, v172
	ds_read_b64 v[186:187], v183 offset:9600
	s_waitcnt lgkmcnt(1)
	v_add_f32_e32 v169, v169, v172
	ds_bpermute_b32 v172, v202, v169
	s_waitcnt lgkmcnt(1)
	v_pk_mul_f32 v[14:15], v[14:15], v[186:187] op_sel:[0,1]
	v_pk_mul_f32 v[16:17], v[16:17], v[186:187] op_sel:[0,1]
	v_pk_mul_f32 v[10:11], v[10:11], v[186:187] op_sel:[0,1]
	v_pk_mul_f32 v[12:13], v[12:13], v[186:187] op_sel:[0,1]
	v_pk_mul_f32 v[6:7], v[6:7], v[186:187] op_sel:[0,1]
	v_pk_mul_f32 v[8:9], v[8:9], v[186:187] op_sel:[0,1]
	v_pk_mul_f32 v[2:3], v[2:3], v[186:187] op_sel:[0,1]
	v_pk_mul_f32 v[4:5], v[4:5], v[186:187] op_sel:[0,1]
	s_waitcnt vmcnt(3)
	v_lshlrev_b32_e32 v186, 16, v174
	v_and_b32_e32 v187, 0xffff0000, v174
	v_lshlrev_b32_e32 v174, 16, v175
	v_and_b32_e32 v175, 0xffff0000, v175
	s_waitcnt vmcnt(2)
	v_lshlrev_b32_e32 v188, 16, v180
	v_and_b32_e32 v189, 0xffff0000, v180
	v_lshlrev_b32_e32 v180, 16, v181
	v_and_b32_e32 v181, 0xffff0000, v181
	s_waitcnt vmcnt(1)
	v_lshlrev_b32_e32 v190, 16, v176
	v_and_b32_e32 v191, 0xffff0000, v176
	v_lshlrev_b32_e32 v176, 16, v177
	v_and_b32_e32 v177, 0xffff0000, v177
	s_waitcnt vmcnt(0)
	v_lshlrev_b32_e32 v192, 16, v178
	v_and_b32_e32 v193, 0xffff0000, v178
	v_lshlrev_b32_e32 v178, 16, v179
	v_and_b32_e32 v179, 0xffff0000, v179
	v_pk_fma_f32 v[16:17], v[140:141], v[16:17], v[174:175]
	v_pk_fma_f32 v[14:15], v[138:139], v[14:15], v[186:187]
	v_pk_fma_f32 v[12:13], v[144:145], v[12:13], v[180:181]
	v_pk_fma_f32 v[10:11], v[142:143], v[10:11], v[188:189]
	v_pk_fma_f32 v[8:9], v[136:137], v[8:9], v[176:177]
	v_pk_fma_f32 v[6:7], v[134:135], v[6:7], v[190:191]
	v_pk_fma_f32 v[4:5], v[132:133], v[4:5], v[178:179]
	v_pk_fma_f32 v[2:3], v[130:131], v[2:3], v[192:193]
	s_nop 0
	s_and_saveexec_b64 s[0:1], s[6:7]
	s_cbranch_execz .LBB0_1493
	s_lshl_b32 s19, s33, 11
	s_add_i32 s19, s17, s19
	v_mul_f32_e32 v130, 0x3c800000, v168
	s_waitcnt lgkmcnt(0)
	v_add_f32_e32 v131, v169, v172
	v_lshl_add_u32 v132, v170, 5, s19
	ds_write_b64 v132, v[130:131]
.LBB0_1493:
	s_or_b64 exec, exec, s[0:1]
	v_mov_b32_e32 v130, v111
	v_mov_b32_e32 v131, v112
	v_mov_b32_e32 v132, v110
	v_mov_b32_e32 v133, v113
	v_pk_add_f32 v[130:131], v[130:131], v[132:133]
	v_mov_b32_e32 v132, v107
	v_mov_b32_e32 v133, v108
	v_mov_b32_e32 v134, v106
	v_mov_b32_e32 v135, v109
	v_pk_add_f32 v[132:133], v[132:133], v[134:135]
	v_add_f32_e32 v130, v130, v131
	v_pk_add_f32 v[132:133], v[132:133], v[132:133] op_sel_hi:[0,1]
	v_add_f32_e32 v131, 0, v130
	v_add_f32_e32 v135, v102, v103
	v_add_f32_e32 v137, v104, v105
	v_mov_b32_e32 v134, v98
	v_mov_b32_e32 v136, v99
	v_mov_b32_e32 v132, v100
	v_mov_b32_e32 v130, v101
	v_pk_add_f32 v[134:135], v[134:135], v[136:137]
	v_pk_add_f32 v[130:131], v[132:133], v[130:131]
	s_nop 0
	v_pk_add_f32 v[130:131], v[134:135], v[130:131]
	s_nop 0
	v_add_f32_e32 v130, v130, v131
	v_mov_b32_e32 v131, v130
	s_nop 1
	v_permlane16_swap_b32_e32 v130, v131
	s_waitcnt lgkmcnt(0)
	v_add_f32_e32 v130, v130, v131
	v_mov_b32_e32 v131, v130
	s_nop 1
	v_permlane32_swap_b32_e32 v130, v131
	s_waitcnt lgkmcnt(0)
	v_add_f32_e32 v130, v130, v131
	v_fmamk_f32 v132, v130, 0xbc800000, v113
	v_fmamk_f32 v134, v130, 0xbc800000, v111
	v_fmamk_f32 v131, v130, 0xbc800000, v112
	v_fmamk_f32 v133, v130, 0xbc800000, v110
	v_mul_f32_e32 v134, v134, v134
	v_mul_f32_e32 v132, v132, v132
	v_fmac_f32_e32 v134, v133, v133
	v_fmac_f32_e32 v132, v131, v131
	v_fmamk_f32 v133, v130, 0xbc800000, v109
	v_fmamk_f32 v135, v130, 0xbc800000, v107
	v_add_f32_e32 v131, v134, v132
	v_fmamk_f32 v132, v130, 0xbc800000, v108
	v_fmamk_f32 v134, v130, 0xbc800000, v106
	v_mul_f32_e32 v135, v135, v135
	v_mul_f32_e32 v133, v133, v133
	v_fmac_f32_e32 v135, v134, v134
	v_fmac_f32_e32 v133, v132, v132
	v_add_f32_e32 v132, v135, v133
	v_fmamk_f32 v133, v130, 0xbc800000, v105
	v_fmamk_f32 v135, v130, 0xbc800000, v103
	v_add_f32_e32 v131, v131, v132
	v_fmamk_f32 v132, v130, 0xbc800000, v104
	v_fmamk_f32 v134, v130, 0xbc800000, v102
	v_mul_f32_e32 v135, v135, v135
	v_mul_f32_e32 v133, v133, v133
	v_fmac_f32_e32 v135, v134, v134
	v_fmac_f32_e32 v133, v132, v132
	v_add_f32_e32 v132, v135, v133
	v_fmamk_f32 v133, v130, 0xbc800000, v101
	v_fmamk_f32 v135, v130, 0xbc800000, v99
	v_add_f32_e32 v131, v132, v131
	v_fmamk_f32 v132, v130, 0xbc800000, v100
	v_fmamk_f32 v134, v130, 0xbc800000, v98
	v_mul_f32_e32 v135, v135, v135
	v_mul_f32_e32 v133, v133, v133
	v_fmac_f32_e32 v135, v134, v134
	v_fmac_f32_e32 v133, v132, v132
	v_add_f32_e32 v132, v135, v133
	v_add_f32_e32 v131, v132, v131
	v_mov_b32_e32 v132, v131
	s_nop 1
	v_permlane16_swap_b32_e32 v131, v132
	s_waitcnt lgkmcnt(0)
	v_add_f32_e32 v131, v131, v132
	v_mov_b32_e32 v132, v131
	s_nop 1
	v_permlane32_swap_b32_e32 v131, v132
	s_and_saveexec_b64 s[0:1], s[6:7]
	s_cbranch_execz .LBB0_1495
	s_lshl_b32 s19, s33, 11
	s_add_i32 s19, s17, s19
	v_mul_f32_e32 v130, 0x3c800000, v130
	s_waitcnt lgkmcnt(0)
	v_add_f32_e32 v131, v131, v132
	v_lshl_add_u32 v132, v170, 5, s19
	ds_write_b64 v132, v[130:131] offset:512
.LBB0_1495:
	s_or_b64 exec, exec, s[0:1]
	v_mov_b32_e32 v130, v95
	v_mov_b32_e32 v131, v96
	s_waitcnt lgkmcnt(0)
	v_mov_b32_e32 v132, v94
	v_mov_b32_e32 v133, v97
	v_pk_add_f32 v[130:131], v[130:131], v[132:133]
	v_mov_b32_e32 v132, v91
	v_mov_b32_e32 v133, v92
	v_mov_b32_e32 v134, v90
	v_mov_b32_e32 v135, v93
	v_pk_add_f32 v[132:133], v[132:133], v[134:135]
	v_add_f32_e32 v130, v130, v131
	v_pk_add_f32 v[132:133], v[132:133], v[132:133] op_sel_hi:[0,1]
	v_add_f32_e32 v131, 0, v130
	v_add_f32_e32 v135, v86, v87
	v_add_f32_e32 v137, v88, v89
	v_mov_b32_e32 v134, v82
	v_mov_b32_e32 v136, v83
	v_mov_b32_e32 v132, v84
	v_mov_b32_e32 v130, v85
	v_pk_add_f32 v[134:135], v[134:135], v[136:137]
	v_pk_add_f32 v[130:131], v[132:133], v[130:131]
	s_nop 0
	v_pk_add_f32 v[130:131], v[134:135], v[130:131]
	s_nop 0
	v_add_f32_e32 v130, v130, v131
	v_mov_b32_e32 v131, v130
	s_nop 1
	v_permlane16_swap_b32_e32 v130, v131
	s_waitcnt lgkmcnt(0)
	v_add_f32_e32 v130, v130, v131
	v_mov_b32_e32 v131, v130
	s_nop 1
	v_permlane32_swap_b32_e32 v130, v131
	s_waitcnt lgkmcnt(0)
	v_add_f32_e32 v130, v130, v131
	v_fmamk_f32 v132, v130, 0xbc800000, v97
	v_fmamk_f32 v134, v130, 0xbc800000, v95
	v_fmamk_f32 v131, v130, 0xbc800000, v96
	v_fmamk_f32 v133, v130, 0xbc800000, v94
	v_mul_f32_e32 v134, v134, v134
	v_mul_f32_e32 v132, v132, v132
	v_fmac_f32_e32 v134, v133, v133
	v_fmac_f32_e32 v132, v131, v131
	v_fmamk_f32 v133, v130, 0xbc800000, v93
	v_fmamk_f32 v135, v130, 0xbc800000, v91
	v_add_f32_e32 v131, v134, v132
	v_fmamk_f32 v132, v130, 0xbc800000, v92
	v_fmamk_f32 v134, v130, 0xbc800000, v90
	v_mul_f32_e32 v135, v135, v135
	v_mul_f32_e32 v133, v133, v133
	v_fmac_f32_e32 v135, v134, v134
	v_fmac_f32_e32 v133, v132, v132
	v_add_f32_e32 v132, v135, v133
	v_fmamk_f32 v133, v130, 0xbc800000, v89
	v_fmamk_f32 v135, v130, 0xbc800000, v87
	v_add_f32_e32 v131, v131, v132
	v_fmamk_f32 v132, v130, 0xbc800000, v88
	v_fmamk_f32 v134, v130, 0xbc800000, v86
	v_mul_f32_e32 v135, v135, v135
	v_mul_f32_e32 v133, v133, v133
	v_fmac_f32_e32 v135, v134, v134
	v_fmac_f32_e32 v133, v132, v132
	v_add_f32_e32 v132, v135, v133
	v_fmamk_f32 v133, v130, 0xbc800000, v85
	v_fmamk_f32 v135, v130, 0xbc800000, v83
	v_add_f32_e32 v131, v132, v131
	v_fmamk_f32 v132, v130, 0xbc800000, v84
	v_fmamk_f32 v134, v130, 0xbc800000, v82
	v_mul_f32_e32 v135, v135, v135
	v_mul_f32_e32 v133, v133, v133
	v_fmac_f32_e32 v135, v134, v134
	v_fmac_f32_e32 v133, v132, v132
	v_add_f32_e32 v132, v135, v133
	v_add_f32_e32 v131, v132, v131
	v_mov_b32_e32 v132, v131
	s_nop 1
	v_permlane16_swap_b32_e32 v131, v132
	s_waitcnt lgkmcnt(0)
	v_add_f32_e32 v131, v131, v132
	v_mov_b32_e32 v132, v131
	s_nop 1
	v_permlane32_swap_b32_e32 v131, v132
	s_and_saveexec_b64 s[0:1], s[6:7]
	s_cbranch_execz .LBB0_1497
	s_lshl_b32 s19, s33, 11
	s_add_i32 s19, s17, s19
	v_mul_f32_e32 v130, 0x3c800000, v130
	s_waitcnt lgkmcnt(0)
	v_add_f32_e32 v131, v131, v132
	v_lshl_add_u32 v132, v170, 5, s19
	ds_write_b64 v132, v[130:131] offset:1024
.LBB0_1497:
	s_or_b64 exec, exec, s[0:1]
	v_mov_b32_e32 v130, v79
	v_mov_b32_e32 v131, v80
	s_waitcnt lgkmcnt(0)
	v_mov_b32_e32 v132, v78
	v_mov_b32_e32 v133, v81
	v_pk_add_f32 v[130:131], v[130:131], v[132:133]
	v_mov_b32_e32 v132, v75
	v_mov_b32_e32 v133, v76
	v_mov_b32_e32 v134, v74
	v_mov_b32_e32 v135, v77
	v_pk_add_f32 v[132:133], v[132:133], v[134:135]
	v_add_f32_e32 v130, v130, v131
	v_pk_add_f32 v[132:133], v[132:133], v[132:133] op_sel_hi:[0,1]
	v_add_f32_e32 v131, 0, v130
	v_add_f32_e32 v135, v70, v71
	v_add_f32_e32 v137, v72, v73
	v_mov_b32_e32 v134, v66
	v_mov_b32_e32 v136, v67
	v_mov_b32_e32 v132, v68
	v_mov_b32_e32 v130, v69
	v_pk_add_f32 v[134:135], v[134:135], v[136:137]
	v_pk_add_f32 v[130:131], v[132:133], v[130:131]
	s_nop 0
	v_pk_add_f32 v[130:131], v[134:135], v[130:131]
	s_nop 0
	v_add_f32_e32 v130, v130, v131
	v_mov_b32_e32 v131, v130
	s_nop 1
	v_permlane16_swap_b32_e32 v130, v131
	s_waitcnt lgkmcnt(0)
	v_add_f32_e32 v130, v130, v131
	v_mov_b32_e32 v131, v130
	s_nop 1
	v_permlane32_swap_b32_e32 v130, v131
	s_waitcnt lgkmcnt(0)
	v_add_f32_e32 v130, v130, v131
	v_fmamk_f32 v132, v130, 0xbc800000, v81
	v_fmamk_f32 v134, v130, 0xbc800000, v79
	v_fmamk_f32 v131, v130, 0xbc800000, v80
	v_fmamk_f32 v133, v130, 0xbc800000, v78
	v_mul_f32_e32 v134, v134, v134
	v_mul_f32_e32 v132, v132, v132
	v_fmac_f32_e32 v134, v133, v133
	v_fmac_f32_e32 v132, v131, v131
	v_fmamk_f32 v133, v130, 0xbc800000, v77
	v_fmamk_f32 v135, v130, 0xbc800000, v75
	v_add_f32_e32 v131, v134, v132
	v_fmamk_f32 v132, v130, 0xbc800000, v76
	v_fmamk_f32 v134, v130, 0xbc800000, v74
	v_mul_f32_e32 v135, v135, v135
	v_mul_f32_e32 v133, v133, v133
	v_fmac_f32_e32 v135, v134, v134
	v_fmac_f32_e32 v133, v132, v132
	v_add_f32_e32 v132, v135, v133
	v_fmamk_f32 v133, v130, 0xbc800000, v73
	v_fmamk_f32 v135, v130, 0xbc800000, v71
	v_add_f32_e32 v131, v131, v132
	v_fmamk_f32 v132, v130, 0xbc800000, v72
	v_fmamk_f32 v134, v130, 0xbc800000, v70
	v_mul_f32_e32 v135, v135, v135
	v_mul_f32_e32 v133, v133, v133
	v_fmac_f32_e32 v135, v134, v134
	v_fmac_f32_e32 v133, v132, v132
	v_add_f32_e32 v132, v135, v133
	v_fmamk_f32 v133, v130, 0xbc800000, v69
	v_fmamk_f32 v135, v130, 0xbc800000, v67
	v_add_f32_e32 v131, v132, v131
	v_fmamk_f32 v132, v130, 0xbc800000, v68
	v_fmamk_f32 v134, v130, 0xbc800000, v66
	v_mul_f32_e32 v135, v135, v135
	v_mul_f32_e32 v133, v133, v133
	v_fmac_f32_e32 v135, v134, v134
	v_fmac_f32_e32 v133, v132, v132
	v_add_f32_e32 v132, v135, v133
	v_add_f32_e32 v131, v132, v131
	v_mov_b32_e32 v132, v131
	s_nop 1
	v_permlane16_swap_b32_e32 v131, v132
	s_waitcnt lgkmcnt(0)
	v_add_f32_e32 v131, v131, v132
	v_mov_b32_e32 v132, v131
	s_nop 1
	v_permlane32_swap_b32_e32 v131, v132
	s_and_saveexec_b64 s[0:1], s[6:7]
	s_cbranch_execz .LBB0_1499
	s_lshl_b32 s19, s33, 11
	s_add_i32 s19, s17, s19
	v_mul_f32_e32 v130, 0x3c800000, v130
	s_waitcnt lgkmcnt(0)
	v_add_f32_e32 v131, v131, v132
	v_lshl_add_u32 v132, v170, 5, s19
	ds_write_b64 v132, v[130:131] offset:1536
.LBB0_1499:
	s_or_b64 exec, exec, s[0:1]
	v_mov_b32_e32 v130, v63
	v_mov_b32_e32 v131, v64
	s_waitcnt lgkmcnt(0)
	v_mov_b32_e32 v132, v62
	v_mov_b32_e32 v133, v65
	v_pk_add_f32 v[130:131], v[130:131], v[132:133]
	v_mov_b32_e32 v132, v59
	v_mov_b32_e32 v133, v60
	v_mov_b32_e32 v134, v58
	v_mov_b32_e32 v135, v61
	v_pk_add_f32 v[132:133], v[132:133], v[134:135]
	v_add_f32_e32 v130, v130, v131
	v_pk_add_f32 v[132:133], v[132:133], v[132:133] op_sel_hi:[0,1]
	v_add_f32_e32 v131, 0, v130
	v_add_f32_e32 v135, v54, v55
	v_add_f32_e32 v137, v56, v57
	v_mov_b32_e32 v134, v50
	v_mov_b32_e32 v136, v51
	v_mov_b32_e32 v132, v52
	v_mov_b32_e32 v130, v53
	v_pk_add_f32 v[134:135], v[134:135], v[136:137]
	v_pk_add_f32 v[130:131], v[132:133], v[130:131]
	s_nop 0
	v_pk_add_f32 v[130:131], v[134:135], v[130:131]
	s_nop 0
	v_add_f32_e32 v130, v130, v131
	v_mov_b32_e32 v131, v130
	s_nop 1
	v_permlane16_swap_b32_e32 v130, v131
	s_waitcnt lgkmcnt(0)
	v_add_f32_e32 v130, v130, v131
	v_mov_b32_e32 v131, v130
	s_nop 1
	v_permlane32_swap_b32_e32 v130, v131
	s_waitcnt lgkmcnt(0)
	v_add_f32_e32 v130, v130, v131
	v_fmamk_f32 v132, v130, 0xbc800000, v65
	v_fmamk_f32 v134, v130, 0xbc800000, v63
	v_fmamk_f32 v131, v130, 0xbc800000, v64
	v_fmamk_f32 v133, v130, 0xbc800000, v62
	v_mul_f32_e32 v134, v134, v134
	v_mul_f32_e32 v132, v132, v132
	v_fmac_f32_e32 v134, v133, v133
	v_fmac_f32_e32 v132, v131, v131
	v_fmamk_f32 v133, v130, 0xbc800000, v61
	v_fmamk_f32 v135, v130, 0xbc800000, v59
	v_add_f32_e32 v131, v134, v132
	v_fmamk_f32 v132, v130, 0xbc800000, v60
	v_fmamk_f32 v134, v130, 0xbc800000, v58
	v_mul_f32_e32 v135, v135, v135
	v_mul_f32_e32 v133, v133, v133
	v_fmac_f32_e32 v135, v134, v134
	v_fmac_f32_e32 v133, v132, v132
	v_add_f32_e32 v132, v135, v133
	v_fmamk_f32 v133, v130, 0xbc800000, v57
	v_fmamk_f32 v135, v130, 0xbc800000, v55
	v_add_f32_e32 v131, v131, v132
	v_fmamk_f32 v132, v130, 0xbc800000, v56
	v_fmamk_f32 v134, v130, 0xbc800000, v54
	v_mul_f32_e32 v135, v135, v135
	v_mul_f32_e32 v133, v133, v133
	v_fmac_f32_e32 v135, v134, v134
	v_fmac_f32_e32 v133, v132, v132
	v_add_f32_e32 v132, v135, v133
	v_fmamk_f32 v133, v130, 0xbc800000, v53
	v_fmamk_f32 v135, v130, 0xbc800000, v51
	v_add_f32_e32 v131, v132, v131
	v_fmamk_f32 v132, v130, 0xbc800000, v52
	v_fmamk_f32 v134, v130, 0xbc800000, v50
	v_mul_f32_e32 v135, v135, v135
	v_mul_f32_e32 v133, v133, v133
	v_fmac_f32_e32 v135, v134, v134
	v_fmac_f32_e32 v133, v132, v132
	v_add_f32_e32 v132, v135, v133
	v_add_f32_e32 v131, v132, v131
	v_mov_b32_e32 v132, v131
	s_nop 1
	v_permlane16_swap_b32_e32 v131, v132
	s_waitcnt lgkmcnt(0)
	v_add_f32_e32 v131, v131, v132
	v_mov_b32_e32 v132, v131
	s_nop 1
	v_permlane32_swap_b32_e32 v131, v132
	s_and_saveexec_b64 s[0:1], s[6:7]
	s_cbranch_execz .LBB0_1501
	s_lshl_b32 s19, s33, 11
	s_add_i32 s19, s17, s19
	v_mul_f32_e32 v130, 0x3c800000, v130
	s_waitcnt lgkmcnt(0)
	v_add_f32_e32 v131, v131, v132
	v_lshl_add_u32 v132, v170, 5, s19
	ds_write_b64 v132, v[130:131] offset:4096
.LBB0_1501:
	s_or_b64 exec, exec, s[0:1]
	v_mov_b32_e32 v130, v47
	v_mov_b32_e32 v131, v48
	s_waitcnt lgkmcnt(0)
	v_mov_b32_e32 v132, v46
	v_mov_b32_e32 v133, v49
	v_pk_add_f32 v[130:131], v[130:131], v[132:133]
	v_mov_b32_e32 v132, v43
	v_mov_b32_e32 v133, v44
	v_mov_b32_e32 v134, v42
	v_mov_b32_e32 v135, v45
	v_pk_add_f32 v[132:133], v[132:133], v[134:135]
	v_add_f32_e32 v130, v130, v131
	v_pk_add_f32 v[132:133], v[132:133], v[132:133] op_sel_hi:[0,1]
	v_add_f32_e32 v131, 0, v130
	v_add_f32_e32 v135, v38, v39
	v_add_f32_e32 v137, v40, v41
	v_mov_b32_e32 v134, v34
	v_mov_b32_e32 v136, v35
	v_mov_b32_e32 v132, v36
	v_mov_b32_e32 v130, v37
	v_pk_add_f32 v[134:135], v[134:135], v[136:137]
	v_pk_add_f32 v[130:131], v[132:133], v[130:131]
	s_nop 0
	v_pk_add_f32 v[130:131], v[134:135], v[130:131]
	s_nop 0
	v_add_f32_e32 v130, v130, v131
	v_mov_b32_e32 v131, v130
	s_nop 1
	v_permlane16_swap_b32_e32 v130, v131
	s_waitcnt lgkmcnt(0)
	v_add_f32_e32 v130, v130, v131
	v_mov_b32_e32 v131, v130
	s_nop 1
	v_permlane32_swap_b32_e32 v130, v131
	s_waitcnt lgkmcnt(0)
	v_add_f32_e32 v130, v130, v131
	v_fmamk_f32 v132, v130, 0xbc800000, v49
	v_fmamk_f32 v134, v130, 0xbc800000, v47
	v_fmamk_f32 v131, v130, 0xbc800000, v48
	v_fmamk_f32 v133, v130, 0xbc800000, v46
	v_mul_f32_e32 v134, v134, v134
	v_mul_f32_e32 v132, v132, v132
	v_fmac_f32_e32 v134, v133, v133
	v_fmac_f32_e32 v132, v131, v131
	v_fmamk_f32 v133, v130, 0xbc800000, v45
	v_fmamk_f32 v135, v130, 0xbc800000, v43
	v_add_f32_e32 v131, v134, v132
	v_fmamk_f32 v132, v130, 0xbc800000, v44
	v_fmamk_f32 v134, v130, 0xbc800000, v42
	v_mul_f32_e32 v135, v135, v135
	v_mul_f32_e32 v133, v133, v133
	v_fmac_f32_e32 v135, v134, v134
	v_fmac_f32_e32 v133, v132, v132
	v_add_f32_e32 v132, v135, v133
	v_fmamk_f32 v133, v130, 0xbc800000, v41
	v_fmamk_f32 v135, v130, 0xbc800000, v39
	v_add_f32_e32 v131, v131, v132
	v_fmamk_f32 v132, v130, 0xbc800000, v40
	v_fmamk_f32 v134, v130, 0xbc800000, v38
	v_mul_f32_e32 v135, v135, v135
	v_mul_f32_e32 v133, v133, v133
	v_fmac_f32_e32 v135, v134, v134
	v_fmac_f32_e32 v133, v132, v132
	v_add_f32_e32 v132, v135, v133
	v_fmamk_f32 v133, v130, 0xbc800000, v37
	v_fmamk_f32 v135, v130, 0xbc800000, v35
	v_add_f32_e32 v131, v132, v131
	v_fmamk_f32 v132, v130, 0xbc800000, v36
	v_fmamk_f32 v134, v130, 0xbc800000, v34
	v_mul_f32_e32 v135, v135, v135
	v_mul_f32_e32 v133, v133, v133
	v_fmac_f32_e32 v135, v134, v134
	v_fmac_f32_e32 v133, v132, v132
	v_add_f32_e32 v132, v135, v133
	v_add_f32_e32 v131, v132, v131
	v_mov_b32_e32 v132, v131
	s_nop 1
	v_permlane16_swap_b32_e32 v131, v132
	s_waitcnt lgkmcnt(0)
	v_add_f32_e32 v131, v131, v132
	v_mov_b32_e32 v132, v131
	s_nop 1
	v_permlane32_swap_b32_e32 v131, v132
	s_and_saveexec_b64 s[0:1], s[6:7]
	s_cbranch_execz .LBB0_1503
	s_lshl_b32 s19, s33, 11
	s_add_i32 s19, s17, s19
	v_mul_f32_e32 v130, 0x3c800000, v130
	s_waitcnt lgkmcnt(0)
	v_add_f32_e32 v131, v131, v132
	v_lshl_add_u32 v132, v170, 5, s19
	ds_write_b64 v132, v[130:131] offset:4608
.LBB0_1503:
	s_or_b64 exec, exec, s[0:1]
	v_mov_b32_e32 v130, v31
	v_mov_b32_e32 v131, v32
	s_waitcnt lgkmcnt(0)
	v_mov_b32_e32 v132, v30
	v_mov_b32_e32 v133, v33
	v_pk_add_f32 v[130:131], v[130:131], v[132:133]
	v_mov_b32_e32 v132, v27
	v_mov_b32_e32 v133, v28
	v_mov_b32_e32 v134, v26
	v_mov_b32_e32 v135, v29
	v_pk_add_f32 v[132:133], v[132:133], v[134:135]
	v_add_f32_e32 v130, v130, v131
	v_pk_add_f32 v[132:133], v[132:133], v[132:133] op_sel_hi:[0,1]
	v_add_f32_e32 v131, 0, v130
	v_add_f32_e32 v135, v22, v23
	v_add_f32_e32 v137, v24, v25
	v_mov_b32_e32 v134, v18
	v_mov_b32_e32 v136, v19
	v_mov_b32_e32 v132, v20
	v_mov_b32_e32 v130, v21
	v_pk_add_f32 v[134:135], v[134:135], v[136:137]
	v_pk_add_f32 v[130:131], v[132:133], v[130:131]
	s_nop 0
	v_pk_add_f32 v[130:131], v[134:135], v[130:131]
	s_nop 0
	v_add_f32_e32 v130, v130, v131
	v_mov_b32_e32 v131, v130
	s_nop 1
	v_permlane16_swap_b32_e32 v130, v131
	s_waitcnt lgkmcnt(0)
	v_add_f32_e32 v130, v130, v131
	v_mov_b32_e32 v131, v130
	s_nop 1
	v_permlane32_swap_b32_e32 v130, v131
	s_waitcnt lgkmcnt(0)
	v_add_f32_e32 v130, v130, v131
	v_fmamk_f32 v132, v130, 0xbc800000, v33
	v_fmamk_f32 v134, v130, 0xbc800000, v31
	v_fmamk_f32 v131, v130, 0xbc800000, v32
	v_fmamk_f32 v133, v130, 0xbc800000, v30
	v_mul_f32_e32 v134, v134, v134
	v_mul_f32_e32 v132, v132, v132
	v_fmac_f32_e32 v134, v133, v133
	v_fmac_f32_e32 v132, v131, v131
	v_fmamk_f32 v133, v130, 0xbc800000, v29
	v_fmamk_f32 v135, v130, 0xbc800000, v27
	v_add_f32_e32 v131, v134, v132
	v_fmamk_f32 v132, v130, 0xbc800000, v28
	v_fmamk_f32 v134, v130, 0xbc800000, v26
	v_mul_f32_e32 v135, v135, v135
	v_mul_f32_e32 v133, v133, v133
	v_fmac_f32_e32 v135, v134, v134
	v_fmac_f32_e32 v133, v132, v132
	v_add_f32_e32 v132, v135, v133
	v_fmamk_f32 v133, v130, 0xbc800000, v25
	v_fmamk_f32 v135, v130, 0xbc800000, v23
	v_add_f32_e32 v131, v131, v132
	v_fmamk_f32 v132, v130, 0xbc800000, v24
	v_fmamk_f32 v134, v130, 0xbc800000, v22
	v_mul_f32_e32 v135, v135, v135
	v_mul_f32_e32 v133, v133, v133
	v_fmac_f32_e32 v135, v134, v134
	v_fmac_f32_e32 v133, v132, v132
	v_add_f32_e32 v132, v135, v133
	v_fmamk_f32 v133, v130, 0xbc800000, v21
	v_fmamk_f32 v135, v130, 0xbc800000, v19
	v_add_f32_e32 v131, v132, v131
	v_fmamk_f32 v132, v130, 0xbc800000, v20
	v_fmamk_f32 v134, v130, 0xbc800000, v18
	v_mul_f32_e32 v135, v135, v135
	v_mul_f32_e32 v133, v133, v133
	v_fmac_f32_e32 v135, v134, v134
	v_fmac_f32_e32 v133, v132, v132
	v_add_f32_e32 v132, v135, v133
	v_add_f32_e32 v131, v132, v131
	v_mov_b32_e32 v132, v131
	s_nop 1
	v_permlane16_swap_b32_e32 v131, v132
	s_waitcnt lgkmcnt(0)
	v_add_f32_e32 v131, v131, v132
	v_mov_b32_e32 v132, v131
	s_nop 1
	v_permlane32_swap_b32_e32 v131, v132
	s_and_saveexec_b64 s[0:1], s[6:7]
	s_cbranch_execz .LBB0_1505
	s_lshl_b32 s19, s33, 11
	s_add_i32 s19, s17, s19
	v_mul_f32_e32 v130, 0x3c800000, v130
	s_waitcnt lgkmcnt(0)
	v_add_f32_e32 v131, v131, v132
	v_lshl_add_u32 v132, v170, 5, s19
	ds_write_b64 v132, v[130:131] offset:5120
.LBB0_1505:
	s_or_b64 exec, exec, s[0:1]
	v_mov_b32_e32 v130, v15
	v_mov_b32_e32 v131, v16
	s_waitcnt lgkmcnt(0)
	v_mov_b32_e32 v132, v14
	v_mov_b32_e32 v133, v17
	v_pk_add_f32 v[130:131], v[130:131], v[132:133]
	v_mov_b32_e32 v132, v11
	v_mov_b32_e32 v133, v12
	v_mov_b32_e32 v134, v10
	v_mov_b32_e32 v135, v13
	v_pk_add_f32 v[132:133], v[132:133], v[134:135]
	v_add_f32_e32 v130, v130, v131
	v_pk_add_f32 v[132:133], v[132:133], v[132:133] op_sel_hi:[0,1]
	v_add_f32_e32 v131, 0, v130
	v_add_f32_e32 v135, v6, v7
	v_add_f32_e32 v137, v8, v9
	v_mov_b32_e32 v134, v2
	v_mov_b32_e32 v136, v3
	v_mov_b32_e32 v132, v4
	v_mov_b32_e32 v130, v5
	v_pk_add_f32 v[134:135], v[134:135], v[136:137]
	v_pk_add_f32 v[130:131], v[132:133], v[130:131]
	s_nop 0
	v_pk_add_f32 v[130:131], v[134:135], v[130:131]
	s_nop 0
	v_add_f32_e32 v130, v130, v131
	v_mov_b32_e32 v131, v130
	s_nop 1
	v_permlane16_swap_b32_e32 v130, v131
	s_waitcnt lgkmcnt(0)
	v_add_f32_e32 v130, v130, v131
	v_mov_b32_e32 v131, v130
	s_nop 1
	v_permlane32_swap_b32_e32 v130, v131
	s_waitcnt lgkmcnt(0)
	v_add_f32_e32 v130, v130, v131
	v_fmamk_f32 v132, v130, 0xbc800000, v17
	v_fmamk_f32 v134, v130, 0xbc800000, v15
	v_fmamk_f32 v131, v130, 0xbc800000, v16
	v_fmamk_f32 v133, v130, 0xbc800000, v14
	v_mul_f32_e32 v134, v134, v134
	v_mul_f32_e32 v132, v132, v132
	v_fmac_f32_e32 v134, v133, v133
	v_fmac_f32_e32 v132, v131, v131
	v_fmamk_f32 v133, v130, 0xbc800000, v13
	v_fmamk_f32 v135, v130, 0xbc800000, v11
	v_add_f32_e32 v131, v134, v132
	v_fmamk_f32 v132, v130, 0xbc800000, v12
	v_fmamk_f32 v134, v130, 0xbc800000, v10
	v_mul_f32_e32 v135, v135, v135
	v_mul_f32_e32 v133, v133, v133
	v_fmac_f32_e32 v135, v134, v134
	v_fmac_f32_e32 v133, v132, v132
	v_add_f32_e32 v132, v135, v133
	v_fmamk_f32 v133, v130, 0xbc800000, v9
	v_fmamk_f32 v135, v130, 0xbc800000, v7
	v_add_f32_e32 v131, v131, v132
	v_fmamk_f32 v132, v130, 0xbc800000, v8
	v_fmamk_f32 v134, v130, 0xbc800000, v6
	v_mul_f32_e32 v135, v135, v135
	v_mul_f32_e32 v133, v133, v133
	v_fmac_f32_e32 v135, v134, v134
	v_fmac_f32_e32 v133, v132, v132
	v_add_f32_e32 v132, v135, v133
	v_fmamk_f32 v133, v130, 0xbc800000, v5
	v_fmamk_f32 v135, v130, 0xbc800000, v3
	v_add_f32_e32 v131, v132, v131
	v_fmamk_f32 v132, v130, 0xbc800000, v4
	v_fmamk_f32 v134, v130, 0xbc800000, v2
	v_mul_f32_e32 v135, v135, v135
	v_mul_f32_e32 v133, v133, v133
	v_fmac_f32_e32 v135, v134, v134
	v_fmac_f32_e32 v133, v132, v132
	v_add_f32_e32 v132, v135, v133
	v_add_f32_e32 v131, v132, v131
	v_mov_b32_e32 v132, v131
	s_nop 1
	v_permlane16_swap_b32_e32 v131, v132
	s_waitcnt lgkmcnt(0)
	v_add_f32_e32 v131, v131, v132
	v_mov_b32_e32 v132, v131
	s_nop 1
	v_permlane32_swap_b32_e32 v131, v132
	s_and_saveexec_b64 s[0:1], s[6:7]
	s_cbranch_execz .LBB0_1507
	s_lshl_b32 s6, s33, 11
	s_add_i32 s17, s17, s6
	v_mul_f32_e32 v130, 0x3c800000, v130
	s_waitcnt lgkmcnt(0)
	v_add_f32_e32 v131, v131, v132
	v_lshl_add_u32 v132, v170, 5, s17
	ds_write_b64 v132, v[130:131] offset:5632

.LBB0_1678:
	s_lshl_b32 s16, s24, 8
	v_add_u32_e32 v249, s16, v149
	v_lshlrev_b32_e32 v249, 11, v249
	s_lshl_b32 s17, s8, 8
	s_lshl_b32 s18, s25, 5
	s_or_b32 s17, s17, s18
	v_lshrrev_b32_e32 v230, 2, v0
	v_and_or_b32 v230, v230, 12, s17
	v_lshl_add_u32 v248, v230, 1, v249
	s_lshl_b32 s19, s24, 5
	s_and_b32 s19, s19, 0xfffffc00
	s_lshl_b32 s19, s19, 2
	s_add_i32 s19, s19, 0x112000
	v_lshl_add_u32 v250, v230, 2, s19
	global_load_dwordx4 v[232:235], v250, s[34:35]
	global_load_dwordx4 v[236:239], v250, s[34:35] offset:64
	global_load_dwordx4 v[240:243], v250, s[34:35] offset:512
	global_load_dwordx4 v[244:247], v250, s[34:35] offset:576
	global_load_dwordx2 v[164:165], v248, s[56:57]
	global_load_dwordx2 v[166:167], v248, s[56:57] offset:32
	global_load_dwordx2 v[168:169], v248, s[56:57] offset:256
	global_load_dwordx2 v[170:171], v248, s[56:57] offset:288
	v_add_u32_e32 v249, 0x8000, v248
	global_load_dwordx2 v[172:173], v249, s[56:57]
	global_load_dwordx2 v[174:175], v249, s[56:57] offset:32
	global_load_dwordx2 v[176:177], v249, s[56:57] offset:256
	global_load_dwordx2 v[178:179], v249, s[56:57] offset:288
	v_add_u32_e32 v249, 0x10000, v248
	global_load_dwordx2 v[180:181], v249, s[56:57]
	global_load_dwordx2 v[182:183], v249, s[56:57] offset:32
	global_load_dwordx2 v[184:185], v249, s[56:57] offset:256
	global_load_dwordx2 v[186:187], v249, s[56:57] offset:288
	v_add_u32_e32 v249, 0x18000, v248
	global_load_dwordx2 v[188:189], v249, s[56:57]
	global_load_dwordx2 v[190:191], v249, s[56:57] offset:32
	global_load_dwordx2 v[192:193], v249, s[56:57] offset:256
	global_load_dwordx2 v[194:195], v249, s[56:57] offset:288
	v_add_u32_e32 v249, 0x40000, v248
	global_load_dwordx2 v[196:197], v249, s[56:57]
	global_load_dwordx2 v[198:199], v249, s[56:57] offset:32
	global_load_dwordx2 v[200:201], v249, s[56:57] offset:256
	global_load_dwordx2 v[204:205], v249, s[56:57] offset:288
	v_add_u32_e32 v249, 0x48000, v248
	global_load_dwordx2 v[206:207], v249, s[56:57]
	global_load_dwordx2 v[208:209], v249, s[56:57] offset:32
	global_load_dwordx2 v[210:211], v249, s[56:57] offset:256
	global_load_dwordx2 v[212:213], v249, s[56:57] offset:288
	v_add_u32_e32 v249, 0x50000, v248
	global_load_dwordx2 v[214:215], v249, s[56:57]
	global_load_dwordx2 v[216:217], v249, s[56:57] offset:32
	global_load_dwordx2 v[218:219], v249, s[56:57] offset:256
	global_load_dwordx2 v[220:221], v249, s[56:57] offset:288
	v_add_u32_e32 v249, 0x58000, v248
	global_load_dwordx2 v[222:223], v249, s[56:57]
	global_load_dwordx2 v[224:225], v249, s[56:57] offset:32
	global_load_dwordx2 v[226:227], v249, s[56:57] offset:256
	global_load_dwordx2 v[228:229], v249, s[56:57] offset:288
	v_mov_b32_e32 v130, v127
	v_mov_b32_e32 v131, v128
	v_mov_b32_e32 v132, v126
	v_mov_b32_e32 v133, v129
	v_pk_add_f32 v[130:131], v[130:131], v[132:133]
	v_mov_b32_e32 v132, v123
	v_mov_b32_e32 v133, v124
	v_mov_b32_e32 v134, v122
	v_mov_b32_e32 v135, v125
	v_pk_add_f32 v[132:133], v[132:133], v[134:135]
	v_add_f32_e32 v130, v130, v131
	v_pk_add_f32 v[132:133], v[132:133], v[132:133] op_sel_hi:[0,1]
	v_add_f32_e32 v131, 0, v130
	v_add_f32_e32 v135, v118, v119
	v_add_f32_e32 v137, v120, v121
	v_mov_b32_e32 v134, v110
	v_mov_b32_e32 v136, v111
	v_mov_b32_e32 v132, v112
	v_mov_b32_e32 v130, v113
	v_pk_add_f32 v[134:135], v[134:135], v[136:137]
	v_pk_add_f32 v[130:131], v[132:133], v[130:131]
	v_mov_b32_e32 v133, v126
	v_pk_add_f32 v[130:131], v[134:135], v[130:131]
	v_mov_b32_e32 v134, v127
	v_add_f32_e32 v130, v130, v131
	v_mov_b32_e32 v131, v130
	s_nop 1
	v_permlane16_swap_b32_e32 v130, v131
	v_mov_b32_e32 v135, v123
	s_lshl_b32 s0, s25, 3
	s_add_i32 s2, s0, 0
	s_barrier
	s_waitcnt lgkmcnt(0)
	v_add_f32_e32 v130, v130, v131
	v_mov_b32_e32 v131, v130
	s_nop 1
	v_permlane32_swap_b32_e32 v130, v131
	s_waitcnt lgkmcnt(0)
	v_add_f32_e32 v131, v130, v131
	v_fmamk_f32 v132, v131, 0xbc800000, v129
	v_fmac_f32_e32 v134, 0xbc800000, v131
	v_fmamk_f32 v130, v131, 0xbc800000, v128
	v_fmac_f32_e32 v133, 0xbc800000, v131
	v_mul_f32_e32 v134, v134, v134
	v_mul_f32_e32 v132, v132, v132
	v_fmac_f32_e32 v134, v133, v133
	v_fmac_f32_e32 v132, v130, v130
	v_add_f32_e32 v130, v134, v132
	v_fmamk_f32 v133, v131, 0xbc800000, v125
	v_mov_b32_e32 v134, v122
	v_fmac_f32_e32 v135, 0xbc800000, v131
	v_fmamk_f32 v132, v131, 0xbc800000, v124
	v_fmac_f32_e32 v134, 0xbc800000, v131
	v_mul_f32_e32 v135, v135, v135
	v_mul_f32_e32 v133, v133, v133
	v_fmac_f32_e32 v135, v134, v134
	v_fmac_f32_e32 v133, v132, v132
	v_add_f32_e32 v132, v135, v133
	v_mov_b32_e32 v135, v119
	v_fmamk_f32 v133, v131, 0xbc800000, v121
	v_mov_b32_e32 v134, v118
	v_fmac_f32_e32 v135, 0xbc800000, v131
	v_add_f32_e32 v130, v130, v132
	v_fmamk_f32 v132, v131, 0xbc800000, v120
	v_fmac_f32_e32 v134, 0xbc800000, v131
	v_mul_f32_e32 v135, v135, v135
	v_mul_f32_e32 v133, v133, v133
	v_fmac_f32_e32 v135, v134, v134
	v_fmac_f32_e32 v133, v132, v132
	v_add_f32_e32 v132, v135, v133
	v_mov_b32_e32 v135, v111
	v_fmamk_f32 v133, v131, 0xbc800000, v113
	v_mov_b32_e32 v134, v110
	v_fmac_f32_e32 v135, 0xbc800000, v131
	v_add_f32_e32 v130, v132, v130
	v_fmamk_f32 v132, v131, 0xbc800000, v112
	v_fmac_f32_e32 v134, 0xbc800000, v131
	v_mul_f32_e32 v135, v135, v135
	v_mul_f32_e32 v133, v133, v133
	v_fmac_f32_e32 v135, v134, v134
	v_fmac_f32_e32 v133, v132, v132
	v_add_f32_e32 v132, v135, v133
	v_add_f32_e32 v132, v132, v130
	v_mov_b32_e32 v133, v132
	s_nop 1
	v_permlane16_swap_b32_e32 v132, v133
	v_and_b32_e32 v130, 63, v0
	v_cmp_gt_u32_e32 vcc, 16, v130
	s_waitcnt lgkmcnt(0)
	v_add_f32_e32 v132, v132, v133
	v_mov_b32_e32 v133, v132
	s_nop 1
	v_permlane32_swap_b32_e32 v132, v133
	s_and_saveexec_b64 s[0:1], vcc
	s_cbranch_execz .LBB0_1680
	s_lshl_b32 s3, s27, 11
	s_add_i32 s3, s2, s3
	v_mul_f32_e32 v134, 0x3c800000, v131
	s_waitcnt lgkmcnt(0)
	v_add_f32_e32 v135, v132, v133
	v_lshl_add_u32 v131, v146, 5, s3
	ds_write_b64 v131, v[134:135]
.LBB0_1680:
	s_or_b64 exec, exec, s[0:1]
	v_mov_b32_e32 v132, v115
	s_waitcnt lgkmcnt(0)
	v_mov_b32_e32 v133, v116
	v_mov_b32_e32 v134, v114
	v_mov_b32_e32 v135, v117
	v_pk_add_f32 v[132:133], v[132:133], v[134:135]
	v_mov_b32_e32 v134, v107
	v_mov_b32_e32 v135, v108
	v_mov_b32_e32 v136, v106
	v_mov_b32_e32 v137, v109
	v_pk_add_f32 v[134:135], v[134:135], v[136:137]
	v_add_f32_e32 v131, v132, v133
	v_pk_add_f32 v[134:135], v[134:135], v[134:135] op_sel_hi:[0,1]
	v_add_f32_e32 v133, 0, v131
	v_add_f32_e32 v137, v102, v103
	v_add_f32_e32 v139, v104, v105
	v_mov_b32_e32 v136, v98
	v_mov_b32_e32 v138, v99
	v_mov_b32_e32 v134, v100
	v_mov_b32_e32 v132, v101
	v_pk_add_f32 v[136:137], v[136:137], v[138:139]
	v_pk_add_f32 v[132:133], v[134:135], v[132:133]
	v_mov_b32_e32 v135, v115
	v_pk_add_f32 v[132:133], v[136:137], v[132:133]
	v_mov_b32_e32 v134, v114
	v_add_f32_e32 v131, v132, v133
	v_mov_b32_e32 v132, v131
	s_nop 1
	v_permlane16_swap_b32_e32 v131, v132
	v_mov_b32_e32 v136, v107
	s_waitcnt lgkmcnt(0)
	v_add_f32_e32 v131, v131, v132
	v_mov_b32_e32 v132, v131
	s_nop 1
	v_permlane32_swap_b32_e32 v131, v132
	s_waitcnt lgkmcnt(0)
	v_add_f32_e32 v131, v131, v132
	v_fmamk_f32 v133, v131, 0xbc800000, v117
	v_fmac_f32_e32 v135, 0xbc800000, v131
	v_fmamk_f32 v132, v131, 0xbc800000, v116
	v_fmac_f32_e32 v134, 0xbc800000, v131
	v_mul_f32_e32 v135, v135, v135
	v_mul_f32_e32 v133, v133, v133
	v_fmac_f32_e32 v135, v134, v134
	v_fmac_f32_e32 v133, v132, v132
	v_add_f32_e32 v132, v135, v133
	v_fmamk_f32 v134, v131, 0xbc800000, v109
	v_mov_b32_e32 v135, v106
	v_fmac_f32_e32 v136, 0xbc800000, v131
	v_fmamk_f32 v133, v131, 0xbc800000, v108
	v_fmac_f32_e32 v135, 0xbc800000, v131
	v_mul_f32_e32 v136, v136, v136
	v_mul_f32_e32 v134, v134, v134
	v_fmac_f32_e32 v136, v135, v135
	v_fmac_f32_e32 v134, v133, v133
	v_add_f32_e32 v133, v136, v134
	v_mov_b32_e32 v136, v103
	v_fmamk_f32 v134, v131, 0xbc800000, v105
	v_mov_b32_e32 v135, v102
	v_fmac_f32_e32 v136, 0xbc800000, v131
	v_add_f32_e32 v132, v132, v133
	v_fmamk_f32 v133, v131, 0xbc800000, v104
	v_fmac_f32_e32 v135, 0xbc800000, v131
	v_mul_f32_e32 v136, v136, v136
	v_mul_f32_e32 v134, v134, v134
	v_fmac_f32_e32 v136, v135, v135
	v_fmac_f32_e32 v134, v133, v133
	v_add_f32_e32 v133, v136, v134
	v_mov_b32_e32 v136, v99
	v_fmamk_f32 v134, v131, 0xbc800000, v101
	v_mov_b32_e32 v135, v98
	v_fmac_f32_e32 v136, 0xbc800000, v131
	v_add_f32_e32 v132, v133, v132
	v_fmamk_f32 v133, v131, 0xbc800000, v100
	v_fmac_f32_e32 v135, 0xbc800000, v131
	v_mul_f32_e32 v136, v136, v136
	v_mul_f32_e32 v134, v134, v134
	v_fmac_f32_e32 v136, v135, v135
	v_fmac_f32_e32 v134, v133, v133
	v_add_f32_e32 v133, v136, v134
	v_add_f32_e32 v132, v133, v132
	v_mov_b32_e32 v133, v132
	s_nop 1
	v_permlane16_swap_b32_e32 v132, v133
	s_waitcnt lgkmcnt(0)
	v_add_f32_e32 v132, v132, v133
	v_mov_b32_e32 v133, v132
	s_nop 1
	v_permlane32_swap_b32_e32 v132, v133
	s_and_saveexec_b64 s[0:1], vcc
	s_cbranch_execz .LBB0_1682
	s_lshl_b32 s3, s27, 11
	s_add_i32 s3, s2, s3
	v_mul_f32_e32 v134, 0x3c800000, v131
	s_waitcnt lgkmcnt(0)
	v_add_f32_e32 v135, v132, v133
	v_lshl_add_u32 v131, v146, 5, s3
	ds_write_b64 v131, v[134:135] offset:512
.LBB0_1682:
	s_or_b64 exec, exec, s[0:1]
	v_mov_b32_e32 v132, v95
	s_waitcnt lgkmcnt(0)
	v_mov_b32_e32 v133, v96
	v_mov_b32_e32 v134, v94
	v_mov_b32_e32 v135, v97
	v_pk_add_f32 v[132:133], v[132:133], v[134:135]
	v_mov_b32_e32 v134, v91
	v_mov_b32_e32 v135, v92
	v_mov_b32_e32 v136, v90
	v_mov_b32_e32 v137, v93
	v_pk_add_f32 v[134:135], v[134:135], v[136:137]
	v_add_f32_e32 v131, v132, v133
	v_pk_add_f32 v[134:135], v[134:135], v[134:135] op_sel_hi:[0,1]
	v_add_f32_e32 v133, 0, v131
	v_add_f32_e32 v137, v86, v87
	v_add_f32_e32 v139, v88, v89
	v_mov_b32_e32 v136, v82
	v_mov_b32_e32 v138, v83
	v_mov_b32_e32 v134, v84
	v_mov_b32_e32 v132, v85
	v_pk_add_f32 v[136:137], v[136:137], v[138:139]
	v_pk_add_f32 v[132:133], v[134:135], v[132:133]
	v_mov_b32_e32 v135, v95
	v_pk_add_f32 v[132:133], v[136:137], v[132:133]
	v_mov_b32_e32 v134, v94
	v_add_f32_e32 v131, v132, v133
	v_mov_b32_e32 v132, v131
	s_nop 1
	v_permlane16_swap_b32_e32 v131, v132
	v_mov_b32_e32 v136, v91
	s_waitcnt lgkmcnt(0)
	v_add_f32_e32 v131, v131, v132
	v_mov_b32_e32 v132, v131
	s_nop 1
	v_permlane32_swap_b32_e32 v131, v132
	s_waitcnt lgkmcnt(0)
	v_add_f32_e32 v131, v131, v132
	v_fmamk_f32 v133, v131, 0xbc800000, v97
	v_fmac_f32_e32 v135, 0xbc800000, v131
	v_fmamk_f32 v132, v131, 0xbc800000, v96
	v_fmac_f32_e32 v134, 0xbc800000, v131
	v_mul_f32_e32 v135, v135, v135
	v_mul_f32_e32 v133, v133, v133
	v_fmac_f32_e32 v135, v134, v134
	v_fmac_f32_e32 v133, v132, v132
	v_add_f32_e32 v132, v135, v133
	v_fmamk_f32 v134, v131, 0xbc800000, v93
	v_mov_b32_e32 v135, v90
	v_fmac_f32_e32 v136, 0xbc800000, v131
	v_fmamk_f32 v133, v131, 0xbc800000, v92
	v_fmac_f32_e32 v135, 0xbc800000, v131
	v_mul_f32_e32 v136, v136, v136
	v_mul_f32_e32 v134, v134, v134
	v_fmac_f32_e32 v136, v135, v135
	v_fmac_f32_e32 v134, v133, v133
	v_add_f32_e32 v133, v136, v134
	v_mov_b32_e32 v136, v87
	v_fmamk_f32 v134, v131, 0xbc800000, v89
	v_mov_b32_e32 v135, v86
	v_fmac_f32_e32 v136, 0xbc800000, v131
	v_add_f32_e32 v132, v132, v133
	v_fmamk_f32 v133, v131, 0xbc800000, v88
	v_fmac_f32_e32 v135, 0xbc800000, v131
	v_mul_f32_e32 v136, v136, v136
	v_mul_f32_e32 v134, v134, v134
	v_fmac_f32_e32 v136, v135, v135
	v_fmac_f32_e32 v134, v133, v133
	v_add_f32_e32 v133, v136, v134
	v_mov_b32_e32 v136, v83
	v_fmamk_f32 v134, v131, 0xbc800000, v85
	v_mov_b32_e32 v135, v82
	v_fmac_f32_e32 v136, 0xbc800000, v131
	v_add_f32_e32 v132, v133, v132
	v_fmamk_f32 v133, v131, 0xbc800000, v84
	v_fmac_f32_e32 v135, 0xbc800000, v131
	v_mul_f32_e32 v136, v136, v136
	v_mul_f32_e32 v134, v134, v134
	v_fmac_f32_e32 v136, v135, v135
	v_fmac_f32_e32 v134, v133, v133
	v_add_f32_e32 v133, v136, v134
	v_add_f32_e32 v132, v133, v132
	v_mov_b32_e32 v133, v132
	s_nop 1
	v_permlane16_swap_b32_e32 v132, v133
	s_waitcnt lgkmcnt(0)
	v_add_f32_e32 v132, v132, v133
	v_mov_b32_e32 v133, v132
	s_nop 1
	v_permlane32_swap_b32_e32 v132, v133
	s_and_saveexec_b64 s[0:1], vcc
	s_cbranch_execz .LBB0_1684
	s_lshl_b32 s3, s27, 11
	s_add_i32 s3, s2, s3
	v_mul_f32_e32 v134, 0x3c800000, v131
	s_waitcnt lgkmcnt(0)
	v_add_f32_e32 v135, v132, v133
	v_lshl_add_u32 v131, v146, 5, s3
	ds_write_b64 v131, v[134:135] offset:1024
.LBB0_1684:
	s_or_b64 exec, exec, s[0:1]
	v_mov_b32_e32 v132, v79
	s_waitcnt lgkmcnt(0)
	v_mov_b32_e32 v133, v80
	v_mov_b32_e32 v134, v78
	v_mov_b32_e32 v135, v81
	v_pk_add_f32 v[132:133], v[132:133], v[134:135]
	v_mov_b32_e32 v134, v75
	v_mov_b32_e32 v135, v76
	v_mov_b32_e32 v136, v74
	v_mov_b32_e32 v137, v77
	v_pk_add_f32 v[134:135], v[134:135], v[136:137]
	v_add_f32_e32 v131, v132, v133
	v_pk_add_f32 v[134:135], v[134:135], v[134:135] op_sel_hi:[0,1]
	v_add_f32_e32 v133, 0, v131
	v_add_f32_e32 v137, v70, v71
	v_add_f32_e32 v139, v72, v73
	v_mov_b32_e32 v136, v66
	v_mov_b32_e32 v138, v67
	v_mov_b32_e32 v134, v68
	v_mov_b32_e32 v132, v69
	v_pk_add_f32 v[136:137], v[136:137], v[138:139]
	v_pk_add_f32 v[132:133], v[134:135], v[132:133]
	v_mov_b32_e32 v135, v79
	v_pk_add_f32 v[132:133], v[136:137], v[132:133]
	v_mov_b32_e32 v134, v78
	v_add_f32_e32 v131, v132, v133
	v_mov_b32_e32 v132, v131
	s_nop 1
	v_permlane16_swap_b32_e32 v131, v132
	v_mov_b32_e32 v136, v75
	s_waitcnt lgkmcnt(0)
	v_add_f32_e32 v131, v131, v132
	v_mov_b32_e32 v132, v131
	s_nop 1
	v_permlane32_swap_b32_e32 v131, v132
	s_waitcnt lgkmcnt(0)
	v_add_f32_e32 v131, v131, v132
	v_fmamk_f32 v133, v131, 0xbc800000, v81
	v_fmac_f32_e32 v135, 0xbc800000, v131
	v_fmamk_f32 v132, v131, 0xbc800000, v80
	v_fmac_f32_e32 v134, 0xbc800000, v131
	v_mul_f32_e32 v135, v135, v135
	v_mul_f32_e32 v133, v133, v133
	v_fmac_f32_e32 v135, v134, v134
	v_fmac_f32_e32 v133, v132, v132
	v_add_f32_e32 v132, v135, v133
	v_fmamk_f32 v134, v131, 0xbc800000, v77
	v_mov_b32_e32 v135, v74
	v_fmac_f32_e32 v136, 0xbc800000, v131
	v_fmamk_f32 v133, v131, 0xbc800000, v76
	v_fmac_f32_e32 v135, 0xbc800000, v131
	v_mul_f32_e32 v136, v136, v136
	v_mul_f32_e32 v134, v134, v134
	v_fmac_f32_e32 v136, v135, v135
	v_fmac_f32_e32 v134, v133, v133
	v_add_f32_e32 v133, v136, v134
	v_mov_b32_e32 v136, v71
	v_fmamk_f32 v134, v131, 0xbc800000, v73
	v_mov_b32_e32 v135, v70
	v_fmac_f32_e32 v136, 0xbc800000, v131
	v_add_f32_e32 v132, v132, v133
	v_fmamk_f32 v133, v131, 0xbc800000, v72
	v_fmac_f32_e32 v135, 0xbc800000, v131
	v_mul_f32_e32 v136, v136, v136
	v_mul_f32_e32 v134, v134, v134
	v_fmac_f32_e32 v136, v135, v135
	v_fmac_f32_e32 v134, v133, v133
	v_add_f32_e32 v133, v136, v134
	v_mov_b32_e32 v136, v67
	v_fmamk_f32 v134, v131, 0xbc800000, v69
	v_mov_b32_e32 v135, v66
	v_fmac_f32_e32 v136, 0xbc800000, v131
	v_add_f32_e32 v132, v133, v132
	v_fmamk_f32 v133, v131, 0xbc800000, v68
	v_fmac_f32_e32 v135, 0xbc800000, v131
	v_mul_f32_e32 v136, v136, v136
	v_mul_f32_e32 v134, v134, v134
	v_fmac_f32_e32 v136, v135, v135
	v_fmac_f32_e32 v134, v133, v133
	v_add_f32_e32 v133, v136, v134
	v_add_f32_e32 v132, v133, v132
	v_mov_b32_e32 v133, v132
	s_nop 1
	v_permlane16_swap_b32_e32 v132, v133
	s_waitcnt lgkmcnt(0)
	v_add_f32_e32 v132, v132, v133
	v_mov_b32_e32 v133, v132
	s_nop 1
	v_permlane32_swap_b32_e32 v132, v133
	s_and_saveexec_b64 s[0:1], vcc
	s_cbranch_execz .LBB0_1686
	s_lshl_b32 s3, s27, 11
	s_add_i32 s3, s2, s3
	v_mul_f32_e32 v134, 0x3c800000, v131
	s_waitcnt lgkmcnt(0)
	v_add_f32_e32 v135, v132, v133
	v_lshl_add_u32 v131, v146, 5, s3
	ds_write_b64 v131, v[134:135] offset:1536
.LBB0_1686:
	s_or_b64 exec, exec, s[0:1]
	v_mov_b32_e32 v132, v63
	s_waitcnt lgkmcnt(0)
	v_mov_b32_e32 v133, v64
	v_mov_b32_e32 v134, v62
	v_mov_b32_e32 v135, v65
	v_pk_add_f32 v[132:133], v[132:133], v[134:135]
	v_mov_b32_e32 v134, v59
	v_mov_b32_e32 v135, v60
	v_mov_b32_e32 v136, v58
	v_mov_b32_e32 v137, v61
	v_pk_add_f32 v[134:135], v[134:135], v[136:137]
	v_add_f32_e32 v131, v132, v133
	v_pk_add_f32 v[134:135], v[134:135], v[134:135] op_sel_hi:[0,1]
	v_add_f32_e32 v133, 0, v131
	v_add_f32_e32 v137, v54, v55
	v_add_f32_e32 v139, v56, v57
	v_mov_b32_e32 v136, v50
	v_mov_b32_e32 v138, v51
	v_mov_b32_e32 v134, v52
	v_mov_b32_e32 v132, v53
	v_pk_add_f32 v[136:137], v[136:137], v[138:139]
	v_pk_add_f32 v[132:133], v[134:135], v[132:133]
	v_mov_b32_e32 v135, v63
	v_pk_add_f32 v[132:133], v[136:137], v[132:133]
	v_mov_b32_e32 v134, v62
	v_add_f32_e32 v131, v132, v133
	v_mov_b32_e32 v132, v131
	s_nop 1
	v_permlane16_swap_b32_e32 v131, v132
	v_mov_b32_e32 v136, v59
	s_waitcnt lgkmcnt(0)
	v_add_f32_e32 v131, v131, v132
	v_mov_b32_e32 v132, v131
	s_nop 1
	v_permlane32_swap_b32_e32 v131, v132
	s_waitcnt lgkmcnt(0)
	v_add_f32_e32 v131, v131, v132
	v_fmamk_f32 v133, v131, 0xbc800000, v65
	v_fmac_f32_e32 v135, 0xbc800000, v131
	v_fmamk_f32 v132, v131, 0xbc800000, v64
	v_fmac_f32_e32 v134, 0xbc800000, v131
	v_mul_f32_e32 v135, v135, v135
	v_mul_f32_e32 v133, v133, v133
	v_fmac_f32_e32 v135, v134, v134
	v_fmac_f32_e32 v133, v132, v132
	v_add_f32_e32 v132, v135, v133
	v_fmamk_f32 v134, v131, 0xbc800000, v61
	v_mov_b32_e32 v135, v58
	v_fmac_f32_e32 v136, 0xbc800000, v131
	v_fmamk_f32 v133, v131, 0xbc800000, v60
	v_fmac_f32_e32 v135, 0xbc800000, v131
	v_mul_f32_e32 v136, v136, v136
	v_mul_f32_e32 v134, v134, v134
	v_fmac_f32_e32 v136, v135, v135
	v_fmac_f32_e32 v134, v133, v133
	v_add_f32_e32 v133, v136, v134
	v_mov_b32_e32 v136, v55
	v_fmamk_f32 v134, v131, 0xbc800000, v57
	v_mov_b32_e32 v135, v54
	v_fmac_f32_e32 v136, 0xbc800000, v131
	v_add_f32_e32 v132, v132, v133
	v_fmamk_f32 v133, v131, 0xbc800000, v56
	v_fmac_f32_e32 v135, 0xbc800000, v131
	v_mul_f32_e32 v136, v136, v136
	v_mul_f32_e32 v134, v134, v134
	v_fmac_f32_e32 v136, v135, v135
	v_fmac_f32_e32 v134, v133, v133
	v_add_f32_e32 v133, v136, v134
	v_mov_b32_e32 v136, v51
	v_fmamk_f32 v134, v131, 0xbc800000, v53
	v_mov_b32_e32 v135, v50
	v_fmac_f32_e32 v136, 0xbc800000, v131
	v_add_f32_e32 v132, v133, v132
	v_fmamk_f32 v133, v131, 0xbc800000, v52
	v_fmac_f32_e32 v135, 0xbc800000, v131
	v_mul_f32_e32 v136, v136, v136
	v_mul_f32_e32 v134, v134, v134
	v_fmac_f32_e32 v136, v135, v135
	v_fmac_f32_e32 v134, v133, v133
	v_add_f32_e32 v133, v136, v134
	v_add_f32_e32 v132, v133, v132
	v_mov_b32_e32 v133, v132
	s_nop 1
	v_permlane16_swap_b32_e32 v132, v133
	s_waitcnt lgkmcnt(0)
	v_add_f32_e32 v132, v132, v133
	v_mov_b32_e32 v133, v132
	s_nop 1
	v_permlane32_swap_b32_e32 v132, v133
	s_and_saveexec_b64 s[0:1], vcc
	s_cbranch_execz .LBB0_1688
	s_lshl_b32 s3, s27, 11
	s_add_i32 s3, s2, s3
	v_mul_f32_e32 v134, 0x3c800000, v131
	s_waitcnt lgkmcnt(0)
	v_add_f32_e32 v135, v132, v133
	v_lshl_add_u32 v131, v146, 5, s3
	ds_write_b64 v131, v[134:135] offset:4096
.LBB0_1688:
	s_or_b64 exec, exec, s[0:1]
	v_mov_b32_e32 v132, v47
	s_waitcnt lgkmcnt(0)
	v_mov_b32_e32 v133, v48
	v_mov_b32_e32 v134, v46
	v_mov_b32_e32 v135, v49
	v_pk_add_f32 v[132:133], v[132:133], v[134:135]
	v_mov_b32_e32 v134, v43
	v_mov_b32_e32 v135, v44
	v_mov_b32_e32 v136, v42
	v_mov_b32_e32 v137, v45
	v_pk_add_f32 v[134:135], v[134:135], v[136:137]
	v_add_f32_e32 v131, v132, v133
	v_pk_add_f32 v[134:135], v[134:135], v[134:135] op_sel_hi:[0,1]
	v_add_f32_e32 v133, 0, v131
	v_add_f32_e32 v137, v38, v39
	v_add_f32_e32 v139, v40, v41
	v_mov_b32_e32 v136, v34
	v_mov_b32_e32 v138, v35
	v_mov_b32_e32 v134, v36
	v_mov_b32_e32 v132, v37
	v_pk_add_f32 v[136:137], v[136:137], v[138:139]
	v_pk_add_f32 v[132:133], v[134:135], v[132:133]
	v_mov_b32_e32 v135, v47
	v_pk_add_f32 v[132:133], v[136:137], v[132:133]
	v_mov_b32_e32 v134, v46
	v_add_f32_e32 v131, v132, v133
	v_mov_b32_e32 v132, v131
	s_nop 1
	v_permlane16_swap_b32_e32 v131, v132
	v_mov_b32_e32 v136, v43
	s_waitcnt lgkmcnt(0)
	v_add_f32_e32 v131, v131, v132
	v_mov_b32_e32 v132, v131
	s_nop 1
	v_permlane32_swap_b32_e32 v131, v132
	s_waitcnt lgkmcnt(0)
	v_add_f32_e32 v131, v131, v132
	v_fmamk_f32 v133, v131, 0xbc800000, v49
	v_fmac_f32_e32 v135, 0xbc800000, v131
	v_fmamk_f32 v132, v131, 0xbc800000, v48
	v_fmac_f32_e32 v134, 0xbc800000, v131
	v_mul_f32_e32 v135, v135, v135
	v_mul_f32_e32 v133, v133, v133
	v_fmac_f32_e32 v135, v134, v134
	v_fmac_f32_e32 v133, v132, v132
	v_add_f32_e32 v132, v135, v133
	v_fmamk_f32 v134, v131, 0xbc800000, v45
	v_mov_b32_e32 v135, v42
	v_fmac_f32_e32 v136, 0xbc800000, v131
	v_fmamk_f32 v133, v131, 0xbc800000, v44
	v_fmac_f32_e32 v135, 0xbc800000, v131
	v_mul_f32_e32 v136, v136, v136
	v_mul_f32_e32 v134, v134, v134
	v_fmac_f32_e32 v136, v135, v135
	v_fmac_f32_e32 v134, v133, v133
	v_add_f32_e32 v133, v136, v134
	v_mov_b32_e32 v136, v39
	v_fmamk_f32 v134, v131, 0xbc800000, v41
	v_mov_b32_e32 v135, v38
	v_fmac_f32_e32 v136, 0xbc800000, v131
	v_add_f32_e32 v132, v132, v133
	v_fmamk_f32 v133, v131, 0xbc800000, v40
	v_fmac_f32_e32 v135, 0xbc800000, v131
	v_mul_f32_e32 v136, v136, v136
	v_mul_f32_e32 v134, v134, v134
	v_fmac_f32_e32 v136, v135, v135
	v_fmac_f32_e32 v134, v133, v133
	v_add_f32_e32 v133, v136, v134
	v_mov_b32_e32 v136, v35
	v_fmamk_f32 v134, v131, 0xbc800000, v37
	v_mov_b32_e32 v135, v34
	v_fmac_f32_e32 v136, 0xbc800000, v131
	v_add_f32_e32 v132, v133, v132
	v_fmamk_f32 v133, v131, 0xbc800000, v36
	v_fmac_f32_e32 v135, 0xbc800000, v131
	v_mul_f32_e32 v136, v136, v136
	v_mul_f32_e32 v134, v134, v134
	v_fmac_f32_e32 v136, v135, v135
	v_fmac_f32_e32 v134, v133, v133
	v_add_f32_e32 v133, v136, v134
	v_add_f32_e32 v132, v133, v132
	v_mov_b32_e32 v133, v132
	s_nop 1
	v_permlane16_swap_b32_e32 v132, v133
	s_waitcnt lgkmcnt(0)
	v_add_f32_e32 v132, v132, v133
	v_mov_b32_e32 v133, v132
	s_nop 1
	v_permlane32_swap_b32_e32 v132, v133
	s_and_saveexec_b64 s[0:1], vcc
	s_cbranch_execz .LBB0_1690
	s_lshl_b32 s3, s27, 11
	s_add_i32 s3, s2, s3
	v_mul_f32_e32 v134, 0x3c800000, v131
	s_waitcnt lgkmcnt(0)
	v_add_f32_e32 v135, v132, v133
	v_lshl_add_u32 v131, v146, 5, s3
	ds_write_b64 v131, v[134:135] offset:4608
.LBB0_1690:
	s_or_b64 exec, exec, s[0:1]
	v_mov_b32_e32 v132, v31
	s_waitcnt lgkmcnt(0)
	v_mov_b32_e32 v133, v32
	v_mov_b32_e32 v134, v30
	v_mov_b32_e32 v135, v33
	v_pk_add_f32 v[132:133], v[132:133], v[134:135]
	v_mov_b32_e32 v134, v27
	v_mov_b32_e32 v135, v28
	v_mov_b32_e32 v136, v26
	v_mov_b32_e32 v137, v29
	v_pk_add_f32 v[134:135], v[134:135], v[136:137]
	v_add_f32_e32 v131, v132, v133
	v_pk_add_f32 v[134:135], v[134:135], v[134:135] op_sel_hi:[0,1]
	v_add_f32_e32 v133, 0, v131
	v_add_f32_e32 v137, v22, v23
	v_add_f32_e32 v139, v24, v25
	v_mov_b32_e32 v136, v18
	v_mov_b32_e32 v138, v19
	v_mov_b32_e32 v134, v20
	v_mov_b32_e32 v132, v21
	v_pk_add_f32 v[136:137], v[136:137], v[138:139]
	v_pk_add_f32 v[132:133], v[134:135], v[132:133]
	v_mov_b32_e32 v135, v31
	v_pk_add_f32 v[132:133], v[136:137], v[132:133]
	v_mov_b32_e32 v134, v30
	v_add_f32_e32 v131, v132, v133
	v_mov_b32_e32 v132, v131
	s_nop 1
	v_permlane16_swap_b32_e32 v131, v132
	v_mov_b32_e32 v136, v27
	s_waitcnt lgkmcnt(0)
	v_add_f32_e32 v131, v131, v132
	v_mov_b32_e32 v132, v131
	s_nop 1
	v_permlane32_swap_b32_e32 v131, v132
	s_waitcnt lgkmcnt(0)
	v_add_f32_e32 v131, v131, v132
	v_fmamk_f32 v133, v131, 0xbc800000, v33
	v_fmac_f32_e32 v135, 0xbc800000, v131
	v_fmamk_f32 v132, v131, 0xbc800000, v32
	v_fmac_f32_e32 v134, 0xbc800000, v131
	v_mul_f32_e32 v135, v135, v135
	v_mul_f32_e32 v133, v133, v133
	v_fmac_f32_e32 v135, v134, v134
	v_fmac_f32_e32 v133, v132, v132
	v_add_f32_e32 v132, v135, v133
	v_fmamk_f32 v134, v131, 0xbc800000, v29
	v_mov_b32_e32 v135, v26
	v_fmac_f32_e32 v136, 0xbc800000, v131
	v_fmamk_f32 v133, v131, 0xbc800000, v28
	v_fmac_f32_e32 v135, 0xbc800000, v131
	v_mul_f32_e32 v136, v136, v136
	v_mul_f32_e32 v134, v134, v134
	v_fmac_f32_e32 v136, v135, v135
	v_fmac_f32_e32 v134, v133, v133
	v_add_f32_e32 v133, v136, v134
	v_mov_b32_e32 v136, v23
	v_fmamk_f32 v134, v131, 0xbc800000, v25
	v_mov_b32_e32 v135, v22
	v_fmac_f32_e32 v136, 0xbc800000, v131
	v_add_f32_e32 v132, v132, v133
	v_fmamk_f32 v133, v131, 0xbc800000, v24
	v_fmac_f32_e32 v135, 0xbc800000, v131
	v_mul_f32_e32 v136, v136, v136
	v_mul_f32_e32 v134, v134, v134
	v_fmac_f32_e32 v136, v135, v135
	v_fmac_f32_e32 v134, v133, v133
	v_add_f32_e32 v133, v136, v134
	v_mov_b32_e32 v136, v19
	v_fmamk_f32 v134, v131, 0xbc800000, v21
	v_mov_b32_e32 v135, v18
	v_fmac_f32_e32 v136, 0xbc800000, v131
	v_add_f32_e32 v132, v133, v132
	v_fmamk_f32 v133, v131, 0xbc800000, v20
	v_fmac_f32_e32 v135, 0xbc800000, v131
	v_mul_f32_e32 v136, v136, v136
	v_mul_f32_e32 v134, v134, v134
	v_fmac_f32_e32 v136, v135, v135
	v_fmac_f32_e32 v134, v133, v133
	v_add_f32_e32 v133, v136, v134
	v_add_f32_e32 v132, v133, v132
	v_mov_b32_e32 v133, v132
	s_nop 1
	v_permlane16_swap_b32_e32 v132, v133
	s_waitcnt lgkmcnt(0)
	v_add_f32_e32 v132, v132, v133
	v_mov_b32_e32 v133, v132
	s_nop 1
	v_permlane32_swap_b32_e32 v132, v133
	s_and_saveexec_b64 s[0:1], vcc
	s_cbranch_execz .LBB0_1692
	s_lshl_b32 s3, s27, 11
	s_add_i32 s3, s2, s3
	v_mul_f32_e32 v134, 0x3c800000, v131
	s_waitcnt lgkmcnt(0)
	v_add_f32_e32 v135, v132, v133
	v_lshl_add_u32 v131, v146, 5, s3
	ds_write_b64 v131, v[134:135] offset:5120
.LBB0_1692:
	s_or_b64 exec, exec, s[0:1]
	v_mov_b32_e32 v132, v15
	s_waitcnt lgkmcnt(0)
	v_mov_b32_e32 v133, v16
	v_mov_b32_e32 v134, v14
	v_mov_b32_e32 v135, v17
	v_pk_add_f32 v[132:133], v[132:133], v[134:135]
	v_mov_b32_e32 v134, v11
	v_mov_b32_e32 v135, v12
	v_mov_b32_e32 v136, v10
	v_mov_b32_e32 v137, v13
	v_pk_add_f32 v[134:135], v[134:135], v[136:137]
	v_add_f32_e32 v131, v132, v133
	v_pk_add_f32 v[134:135], v[134:135], v[134:135] op_sel_hi:[0,1]
	v_add_f32_e32 v133, 0, v131
	v_add_f32_e32 v137, v6, v7
	v_add_f32_e32 v139, v8, v9
	v_mov_b32_e32 v136, v2
	v_mov_b32_e32 v138, v3
	v_mov_b32_e32 v134, v4
	v_mov_b32_e32 v132, v5
	v_pk_add_f32 v[136:137], v[136:137], v[138:139]
	v_pk_add_f32 v[132:133], v[134:135], v[132:133]
	v_mov_b32_e32 v135, v15
	v_pk_add_f32 v[132:133], v[136:137], v[132:133]
	v_mov_b32_e32 v134, v14
	v_add_f32_e32 v131, v132, v133
	v_mov_b32_e32 v132, v131
	s_nop 1
	v_permlane16_swap_b32_e32 v131, v132
	v_mov_b32_e32 v136, v11
	s_waitcnt lgkmcnt(0)
	v_add_f32_e32 v131, v131, v132
	v_mov_b32_e32 v132, v131
	s_nop 1
	v_permlane32_swap_b32_e32 v131, v132
	s_waitcnt lgkmcnt(0)
	v_add_f32_e32 v131, v131, v132
	v_fmamk_f32 v133, v131, 0xbc800000, v17
	v_fmac_f32_e32 v135, 0xbc800000, v131
	v_fmamk_f32 v132, v131, 0xbc800000, v16
	v_fmac_f32_e32 v134, 0xbc800000, v131
	v_mul_f32_e32 v135, v135, v135
	v_mul_f32_e32 v133, v133, v133
	v_fmac_f32_e32 v135, v134, v134
	v_fmac_f32_e32 v133, v132, v132
	v_add_f32_e32 v132, v135, v133
	v_fmamk_f32 v134, v131, 0xbc800000, v13
	v_mov_b32_e32 v135, v10
	v_fmac_f32_e32 v136, 0xbc800000, v131
	v_fmamk_f32 v133, v131, 0xbc800000, v12
	v_fmac_f32_e32 v135, 0xbc800000, v131
	v_mul_f32_e32 v136, v136, v136
	v_mul_f32_e32 v134, v134, v134
	v_fmac_f32_e32 v136, v135, v135
	v_fmac_f32_e32 v134, v133, v133
	v_add_f32_e32 v133, v136, v134
	v_mov_b32_e32 v136, v7
	v_fmamk_f32 v134, v131, 0xbc800000, v9
	v_mov_b32_e32 v135, v6
	v_fmac_f32_e32 v136, 0xbc800000, v131
	v_add_f32_e32 v132, v132, v133
	v_fmamk_f32 v133, v131, 0xbc800000, v8
	v_fmac_f32_e32 v135, 0xbc800000, v131
	v_mul_f32_e32 v136, v136, v136
	v_mul_f32_e32 v134, v134, v134
	v_fmac_f32_e32 v136, v135, v135
	v_fmac_f32_e32 v134, v133, v133
	v_add_f32_e32 v133, v136, v134
	v_mov_b32_e32 v136, v3
	v_fmamk_f32 v134, v131, 0xbc800000, v5
	v_mov_b32_e32 v135, v2
	v_fmac_f32_e32 v136, 0xbc800000, v131
	v_add_f32_e32 v132, v133, v132
	v_fmamk_f32 v133, v131, 0xbc800000, v4
	v_fmac_f32_e32 v135, 0xbc800000, v131
	v_mul_f32_e32 v136, v136, v136
	v_mul_f32_e32 v134, v134, v134
	v_fmac_f32_e32 v136, v135, v135
	v_fmac_f32_e32 v134, v133, v133
	v_add_f32_e32 v133, v136, v134
	v_add_f32_e32 v132, v133, v132
	v_mov_b32_e32 v1, v132
	s_nop 1
	v_permlane16_swap_b32_e32 v132, v1
	s_waitcnt lgkmcnt(0)
	v_add_f32_e32 v1, v132, v1
	v_mov_b32_e32 v132, v1
	s_nop 1
	v_permlane32_swap_b32_e32 v1, v132
	s_and_saveexec_b64 s[0:1], vcc
	s_cbranch_execz .LBB0_1694
	s_lshl_b32 s3, s27, 11
	s_add_i32 s2, s2, s3
	v_mul_f32_e32 v134, 0x3c800000, v131
	s_waitcnt lgkmcnt(0)
	v_add_f32_e32 v135, v1, v132
	v_lshl_add_u32 v1, v146, 5, s2
	ds_write_b64 v1, v[134:135] offset:5632
